# attention hot loops: drop trivially-satisfied lgkmcnt waits, merge V-frag waits, drop m0 save/restore + s_nop in LDS-DMA issue
# speedup vs baseline: 1.0107x; 1.0107x over previous
; #define WAIT_BAR(N) asm volatile("s_waitcnt vmcnt(" #N ") lgkmcnt(0)\n\ts_barrier":::"memory")
;   #define CMASK(P0,P1,t) do{}while(0)
;   #define CMASK(P0,P1,t) do{}while(0)
; template<int THRL,bool FIXED> __device__ __forceinline__ void attn_unit(int qb,const bf16*Qp,const unsigned char*__restrict__ K8h,const bf16*__restrict__ Vh,bf16*Op,int PO,char*shm){
;   int tid_=threadIdx.x; asm volatile("":"+v"(tid_)); const int tid=tid_,lane=tid&63,r32=lane&31,hi=lane>>5; const int wid=__builtin_amdgcn_readfirstlane(tid>>6);
;   const int q0=qb*QB;
;   const bf16*Qw=Qp+(long)(q0+wid*QBLK)*PQ;
;   const unsigned lds0=(unsigned)(uintptr_t)shm;
;   float*wsf=(float*)(shm+LDS_WS)+wid*64;
;   const unsigned char*ksrc=K8h+(long)lane*128+(wid&3)*16;
;   const bf16*vsrc=Vh+(long)(16*(wid&3)+(lane>>2))*PQ+(wid>>2)*32+(lane&3)*8;
;   const unsigned kdst=lds0+LDS_K+(wid&3)*1024, vdst=lds0+LDS_V+wid*1024;
;     ...
;   const int vb0=(int)(lds0+LDS_V)+((lane>>4)&1)*32+(lane&3)*8+(4*hi+((lane&15)>>2))*64;
;   u32x4 klo[2],khi_[2];
;   const lds_cptr shm3=(lds_cptr)shm; const lds_cptr kp0=shm3+LDS_K+hi*2048+r32*16; const lds_cptr vp0=shm3+LDS_V+((lane>>4)&1)*32+(lane&3)*8+(4*hi+((lane&15)>>2))*64;
;   constexpr int NT=SEQ/KVBLK;
;   DMA_K(0,0);DMA_V(0,VSL(0));DMA_K(1,SLOTB);DMA_V(1,VSL(1));
;   v8i_t q8;
;   { bf16x8 qv[4];
;     #pragma unroll
;     for(int c=0;c<4;++c)qv[c]=*reinterpret_cast<const bf16x8*>(&Qw[(long)r32*PQ+32*hi+8*c]);
;     #pragma unroll
;     for(int c=0;c<4;++c){ float f[8];
;       #pragma unroll
;       for(int e=0;e<8;++e)f[e]=__builtin_bit_cast(float,((unsigned)(unsigned short)qv[c][e])<<16)*16.0f;
;       int w0=__builtin_amdgcn_cvt_pk_fp8_f32(f[0],f[1],0,false); w0=__builtin_amdgcn_cvt_pk_fp8_f32(f[2],f[3],w0,true);
;       int w1=__builtin_amdgcn_cvt_pk_fp8_f32(f[4],f[5],0,false); w1=__builtin_amdgcn_cvt_pk_fp8_f32(f[6],f[7],w1,true);
;       q8[2*c]=w0; q8[2*c+1]=w1; } }
;   float mhat=0.f,l_reg=0.f;f32x16 o[2];o[0]=f32x16{};o[1]=f32x16{};f32x16 negm=f32x16{};asm volatile("":"+v"(negm));
;     ...
;   bool resc=false;
;     ...
;   f32x16 pA0,pA1,pB0,pB1;
;   int sl_prev=0,sl_cur=0,sl_next=SLOTB;
;     ...
;   DMA_K(2,2*SLOTB);
;   WAIT_BAR(3);
;   { const u32x4 a0=*(lds_q16)(kp0),a1=*(lds_q16)(kp0+1024),b0=*(lds_q16)(kp0+512),b1=*(lds_q16)(kp0+1536); pA0=mf8(a0,a1,q8,negm); pA1=mf8(b0,b1,q8,negm); }asm volatile("s_nop 15\n\ts_nop 7":"+v"(pA0),"+v"(pA1));CMASK(pA0,pA1,0);
.LBB0_542:
	s_lshr_b32 s4, s2, 2
	s_and_b32 s22, s4, 64
	v_readlane_b32 s4, v253, 8
	s_add_i32 s4, s3, s4
	s_ashr_i32 s8, s4, 9
	s_ashr_i32 s9, s8, 31
	s_mul_i32 s10, s8, 0x4800000
	v_readlane_b32 s12, v254, 42
	s_mul_hi_i32 s5, s8, 0x4800000
	v_readlane_b32 s13, v254, 43
	s_add_u32 s12, s12, s10
	s_addc_u32 s5, s13, s5
	s_and_b32 s35, s4, 0x1c0
	s_lshl_b32 s10, s35, 1
	s_add_u32 s13, s12, s10
	s_addc_u32 s23, s5, 0
	s_lshl_b64 s[10:11], s[8:9], 21
	s_add_u32 s28, s30, s10
	s_addc_u32 s29, s31, s11
	s_lshr_b32 s4, s4, 2
	s_and_b32 s4, s4, 64
	s_add_u32 s28, s28, s4
	s_addc_u32 s29, s29, 0
	s_lshl_b32 s4, s4, 1
	v_mov_b32_e32 v40, v238
	s_add_u32 s50, s12, s4
	s_addc_u32 s51, s5, 0
	v_readfirstlane_b32 s34, v40
	s_ashr_i32 s33, s34, 6
	s_lshl_b32 s4, s3, 8
	s_and_b32 s4, s4, 0x3f00
	s_lshl_b32 s5, s33, 5
	s_add_i32 s4, s5, s4
	s_ashr_i32 s5, s4, 31
	s_mul_i32 s12, s4, 0x1200
	v_and_b32_e32 v156, 63, v40
	s_mul_hi_i32 s44, s4, 0x1200
	s_add_u32 s12, s13, s12
	s_addc_u32 s13, s23, s44
	v_lshlrev_b32_e32 v160, 7, v156
	s_and_b32 s23, s33, 3
	v_lshl_add_u64 v[0:1], s[28:29], 0, v[160:161]
	s_lshl_b32 s96, s23, 4
	v_lshl_add_u64 v[154:155], v[0:1], 0, s[96:97]
	v_bfe_u32 v0, v40, 2, 4
	v_or_b32_e32 v0, s96, v0
	v_mul_u32_u24_e32 v0, 0x900, v0
	s_ashr_i32 s28, s34, 3
	v_lshlrev_b32_e32 v0, 1, v0
	v_mov_b32_e32 v1, v161
	s_andn2_b32 s28, s28, 31
	v_lshlrev_b32_e32 v157, 3, v40
	v_lshl_add_u64 v[0:1], s[50:51], 0, v[0:1]
	s_ashr_i32 s29, s28, 31
	v_and_b32_e32 v162, 24, v157
	v_lshl_add_u64 v[0:1], s[28:29], 1, v[0:1]
	v_lshlrev_b32_e32 v2, 1, v162
	v_mov_b32_e32 v3, v161
	v_lshl_add_u64 v[96:97], v[0:1], 0, v[2:3]
	s_mov_b64 s[28:29], 0x500
	v_lshl_add_u64 v[152:153], v[96:97], 0, s[28:29]
	s_lshl_b32 s29, s23, 10
	s_cmp_lg_u32 0, -1
	s_cselect_b32 s23, 0, 0
	s_lshl_b32 s28, s33, 10
	s_add_i32 s29, s29, s23
	s_add_i32 s23, s23, s28
	s_mov_b32 s50, m0
	s_mov_b32 m0, s29
	s_nop 0
	global_load_lds_dwordx4 v[154:155], off
	s_mov_b32 m0, s50
	s_add_i32 s44, s23, 0x6000
	s_mov_b32 s50, m0
	s_mov_b32 m0, s44
	s_nop 0
	global_load_lds_dwordx4 v[152:153], off
	s_mov_b32 m0, s50
	s_mov_b64 s[50:51], 0x2000
	v_lshl_add_u64 v[0:1], v[154:155], 0, s[50:51]
	s_add_i32 s50, s29, 0x2000
	s_mov_b32 s51, m0
	s_mov_b32 m0, s50
	s_nop 0
	global_load_lds_dwordx4 v[0:1], off
	s_mov_b32 m0, s51
	s_mov_b64 s[50:51], 0x48500
	v_and_b32_e32 v158, 31, v40
	v_lshl_add_u64 v[0:1], v[96:97], 0, s[50:51]
	s_add_i32 s50, s23, 0x8000
	s_mov_b32 s51, m0
	s_mov_b32 m0, s50
	s_nop 0
	global_load_lds_dwordx4 v[0:1], off
	s_mov_b32 m0, s51
	v_mul_u32_u24_e32 v0, 0x900, v158
	v_and_or_b32 v0, v40, 32, v0
	v_lshlrev_b32_e32 v12, 1, v0
	global_load_dwordx4 v[0:3], v12, s[12:13]
	global_load_dwordx4 v[4:7], v12, s[12:13] offset:16
	global_load_dwordx4 v[8:11], v12, s[12:13] offset:32
	global_load_dwordx4 v[22:25], v12, s[12:13] offset:48
	v_bfe_u32 v159, v40, 5, 1
	v_lshlrev_b32_e32 v12, 11, v159
	v_lshlrev_b32_e32 v13, 4, v158
	v_add3_u32 v165, 0, v12, v13
	v_mov_b32_e32 v128, v161
	v_mov_b32_e32 v129, v161
	v_mov_b32_e32 v130, v161
	v_mov_b32_e32 v131, v161
	v_mov_b32_e32 v132, v161
	v_mov_b32_e32 v133, v161
	v_mov_b32_e32 v134, v161
	v_mov_b32_e32 v135, v161
	s_mov_b64 s[12:13], 0x4000
	v_lshlrev_b32_e32 v41, 1, v40
	v_lshlrev_b32_e32 v40, 4, v40
	v_and_b32_e32 v40, 0xc0, v40
	v_and_b32_e32 v163, 32, v41
	v_lshl_or_b32 v164, v159, 8, v40
	s_mov_b64 s[56:57], 0x90500
	s_add_i32 s23, s23, 0xa000
	v_add_u32_e32 v80, 0, v163
	v_add3_u32 v166, v80, v162, v164
	v_mov_b32_e32 v118, 0
	s_movk_i32 s50, 0x2000
	s_waitcnt vmcnt(3)
	v_lshlrev_b32_e32 v12, 16, v0
	v_and_b32_e32 v0, 0xffff0000, v0
	v_mul_f32_e32 v12, 0x41800000, v12
	v_mul_f32_e32 v0, 0x41800000, v0
	v_cvt_pk_fp8_f32 v128, v12, v0
	v_lshlrev_b32_e32 v14, 16, v2
	v_and_b32_e32 v2, 0xffff0000, v2
	v_lshlrev_b32_e32 v13, 16, v1
	v_and_b32_e32 v1, 0xffff0000, v1
	v_mul_f32_e32 v14, 0x41800000, v14
	v_mul_f32_e32 v2, 0x41800000, v2
	s_waitcnt vmcnt(2)
	v_lshlrev_b32_e32 v16, 16, v4
	v_and_b32_e32 v4, 0xffff0000, v4
	v_lshlrev_b32_e32 v18, 16, v6
	v_and_b32_e32 v6, 0xffff0000, v6
	v_mul_f32_e32 v13, 0x41800000, v13
	v_mul_f32_e32 v1, 0x41800000, v1
	v_cvt_pk_fp8_f32 v129, v14, v2
	v_mul_f32_e32 v16, 0x41800000, v16
	v_mul_f32_e32 v4, 0x41800000, v4
	v_mul_f32_e32 v2, 0x41800000, v18
	v_cvt_pk_fp8_f32 v128, v13, v1 op_sel:[0,0,1]
	v_mul_f32_e32 v1, 0x41800000, v6
	v_lshlrev_b32_e32 v15, 16, v3
	v_and_b32_e32 v3, 0xffff0000, v3
	v_cvt_pk_fp8_f32 v130, v16, v4
	v_cvt_pk_fp8_f32 v131, v2, v1
	v_mul_f32_e32 v15, 0x41800000, v15
	v_mul_f32_e32 v3, 0x41800000, v3
	v_lshlrev_b32_e32 v17, 16, v5
	v_and_b32_e32 v5, 0xffff0000, v5
	v_cvt_pk_fp8_f32 v129, v15, v3 op_sel:[0,0,1]
	v_lshlrev_b32_e32 v3, 16, v7
	v_and_b32_e32 v1, 0xffff0000, v7
	v_mul_f32_e32 v17, 0x41800000, v17
	v_mul_f32_e32 v0, 0x41800000, v5
	v_mul_f32_e32 v3, 0x41800000, v3
	v_mul_f32_e32 v1, 0x41800000, v1
	v_cvt_pk_fp8_f32 v130, v17, v0 op_sel:[0,0,1]
	v_cvt_pk_fp8_f32 v131, v3, v1 op_sel:[0,0,1]
	s_waitcnt vmcnt(1)
	v_lshlrev_b32_e32 v0, 16, v8
	v_and_b32_e32 v1, 0xffff0000, v8
	v_mul_f32_e32 v0, 0x41800000, v0
	v_mul_f32_e32 v1, 0x41800000, v1
	v_cvt_pk_fp8_f32 v132, v0, v1
	v_lshlrev_b32_e32 v4, 16, v10
	v_and_b32_e32 v5, 0xffff0000, v10
	v_lshlrev_b32_e32 v2, 16, v9
	v_and_b32_e32 v3, 0xffff0000, v9
	v_mul_f32_e32 v4, 0x41800000, v4
	v_mul_f32_e32 v5, 0x41800000, v5
	v_mul_f32_e32 v2, 0x41800000, v2
	v_mul_f32_e32 v3, 0x41800000, v3
	v_cvt_pk_fp8_f32 v133, v4, v5
	v_cvt_pk_fp8_f32 v132, v2, v3 op_sel:[0,0,1]
	s_waitcnt vmcnt(0)
	v_lshlrev_b32_e32 v2, 16, v23
	v_lshlrev_b32_e32 v6, 16, v11
	v_and_b32_e32 v0, 0xffff0000, v11
	v_mul_f32_e32 v26, 0x41800000, v2
	v_and_b32_e32 v2, 0xffff0000, v23
	v_mul_f32_e32 v6, 0x41800000, v6
	v_mul_f32_e32 v0, 0x41800000, v0
	v_mul_f32_e32 v27, 0x41800000, v2
	v_lshlrev_b32_e32 v2, 16, v24
	v_cvt_pk_fp8_f32 v133, v6, v0 op_sel:[0,0,1]
	v_lshlrev_b32_e32 v0, 16, v22
	v_and_b32_e32 v1, 0xffff0000, v22
	v_mul_f32_e32 v28, 0x41800000, v2
	v_and_b32_e32 v2, 0xffff0000, v24
	v_mul_f32_e32 v0, 0x41800000, v0
	v_mul_f32_e32 v1, 0x41800000, v1
	v_mul_f32_e32 v24, 0x41800000, v2
	v_lshlrev_b32_e32 v2, 16, v25
	v_mul_f32_e32 v29, 0x41800000, v2
	v_cvt_pk_fp8_f32 v134, v0, v1
	v_mov_b32_e32 v0, v161
	v_mov_b32_e32 v1, v161
	v_mov_b32_e32 v2, v161
	v_mov_b32_e32 v3, v161
	v_mov_b32_e32 v4, v161
	v_mov_b32_e32 v5, v161
	v_mov_b32_e32 v6, v161
	v_mov_b32_e32 v7, v161
	v_mov_b32_e32 v8, v161
	v_mov_b32_e32 v9, v161
	v_mov_b32_e32 v10, v161
	v_mov_b32_e32 v11, v161
	v_mov_b32_e32 v12, v161
	v_mov_b32_e32 v13, v161
	v_mov_b32_e32 v14, v161
	v_mov_b32_e32 v15, v161
	v_cvt_pk_fp8_f32 v135, v28, v24
	v_lshl_add_u64 v[16:17], v[154:155], 0, s[12:13]
	s_add_i32 s12, s29, 0x4000
	s_mov_b32 s13, m0
	s_mov_b32 m0, s12
	s_nop 0
	global_load_lds_dwordx4 v[16:17], off
	s_mov_b32 m0, s13
	s_waitcnt vmcnt(3) lgkmcnt(0)
	s_barrier
; #define WAIT_BAR(N) asm volatile("s_waitcnt vmcnt(" #N ") lgkmcnt(0)\n\ts_barrier":::"memory")
;   #define DMA_K(t,slot) glds16(ksrc+(long)(t)*KVBLK*PQ,(unsigned)__builtin_amdgcn_readfirstlane(kdst+(slot)))
;   #define DMA_V(t,slot) glds16(vsrc+(long)(t)*KVBLK*PQ,(unsigned)__builtin_amdgcn_readfirstlane(vdst+(slot)))
;   #define CMASK(P0,P1,t) do{}while(0)
;   #define START(P0,P1) do{ const float rm=rowmax(P0,P1); resc=false; \
;     { const float dl=rm; mhat=fadd_s(mhat,dl); \
;       _Pragma("unroll") for(int r=0;r<16;++r){P0[r]=fsub_s(P0[r],dl);P1[r]=fsub_s(P1[r],dl);} \
;       _Pragma("unroll") for(int r=0;r<16;++r)negm[r]=-mhat; asm volatile("":"+v"(negm)); } \
;     _Pragma("unroll") for(int r=0;r<16;++r)P0[r]=__builtin_amdgcn_exp2f(P0[r]); }while(0)
;   #define ROT() do{sl_prev=sl_cur;sl_cur=sl_next;sl_next=(sl_next==(NSLOT-1)*SLOTB)?0:sl_next+SLOTB;}while(0)
;   #define CMASK(P0,P1,t) do{}while(0)
;   #define CMASK(P0,P1,t) do{}while(0)
; #define WAIT_BAR(N) asm volatile("s_waitcnt vmcnt(" #N ") lgkmcnt(0)\n\ts_barrier":::"memory")
;   #define DMA_K(t,slot) glds16(ksrc+(long)(t)*KVBLK*PQ,(unsigned)__builtin_amdgcn_readfirstlane(kdst+(slot)))
;   #define DMA_V(t,slot) do{ glds16(vsrc+(long)(t)*KVBLK*PQ,(unsigned)__builtin_amdgcn_readfirstlane(vdst+(slot))); glds16(vsrc+(long)(t)*KVBLK*PQ+64,(unsigned)__builtin_amdgcn_readfirstlane(vdst+(slot)+8192)); }while(0)
;   #define CMASK(P0,P1,t) do{}while(0)
;   #define ROT() do{sl_prev=sl_cur;sl_cur=sl_next;sl_next=(sl_next==(NSLOT-1)*SLOTB)?0:sl_next+SLOTB;}while(0)
;   #define CMASK(P0,P1,t) do{}while(0)
;   #define CMASK(P0,P1,t) do{}while(0)
; template<int THRL,bool FIXED> __device__ __forceinline__ void attn_unit(int qb,const bf16*Qp,const unsigned char*__restrict__ K8h,const bf16*__restrict__ Vh,bf16*Op,int PO,char*shm){
;     ...
;   { const u32x4 a0=*(lds_q16)(kp0),a1=*(lds_q16)(kp0+1024),b0=*(lds_q16)(kp0+512),b1=*(lds_q16)(kp0+1536); pA0=mf8(a0,a1,q8,negm); pA1=mf8(b0,b1,q8,negm); }asm volatile("s_nop 15\n\ts_nop 7":"+v"(pA0),"+v"(pA1));CMASK(pA0,pA1,0);
;   START(pA0,pA1);
;   _Pragma("unroll") for(int r=0;r<16;++r)pA1[r]=__builtin_amdgcn_exp2f(pA1[r]);
;   WAIT_BAR(0);
;   DMA_K(3,0);DMA_V(2,VSL(2));
;   ROT();
;   klo[0]=*(lds_q16)(kp0+sl_cur); khi_[0]=*(lds_q16)(kp0+sl_cur+1024); klo[1]=*(lds_q16)(kp0+sl_cur+512); khi_[1]=*(lds_q16)(kp0+sl_cur+1536);
;   WAIT_BAR(2);
	v_and_b32_e32 v24, 0xffff0000, v25
	ds_read_b128 v[16:19], v165
	ds_read_b128 v[20:23], v165 offset:1024
	v_mul_f32_e32 v24, 0x41800000, v24
	ds_read_b128 v[32:35], v165 offset:512
	ds_read_b128 v[36:39], v165 offset:1536
	v_cvt_pk_fp8_f32 v134, v26, v27 op_sel:[0,0,1]
	v_cvt_pk_fp8_f32 v135, v29, v24 op_sel:[0,0,1]
	s_mov_b32 s12, -1
	s_movk_i32 s13, 0x4000
	s_waitcnt lgkmcnt(2)
	v_mfma_scale_f32_32x32x64_f8f6f4 v[16:31], v[16:23], v[128:135], v[0:15], v242, v241 op_sel_hi:[0,0,0]
	s_waitcnt lgkmcnt(0)
	v_mfma_scale_f32_32x32x64_f8f6f4 v[0:15], v[32:39], v[128:135], v[0:15], v242, v241 op_sel_hi:[0,0,0]
	s_nop 15
	s_nop 7
	s_nop 0
	v_max3_f32 v32, v16, v17, v0
	v_max3_f32 v33, v18, v19, v1
	s_nop 0
	v_max3_f32 v32, v32, v2, v3
	v_max3_f32 v33, v33, v22, v23
	s_nop 0
	v_max3_f32 v32, v32, v20, v21
	v_max3_f32 v33, v33, v6, v7
	s_nop 0
	v_max3_f32 v32, v32, v4, v5
	v_max3_f32 v33, v33, v26, v27
	s_nop 0
	v_max3_f32 v32, v32, v24, v25
	v_max3_f32 v33, v33, v10, v11
	s_nop 0
	v_max3_f32 v32, v32, v8, v9
	v_max3_f32 v33, v33, v30, v31
	s_nop 0
	v_max3_f32 v32, v32, v28, v29
	v_max3_f32 v33, v33, v14, v15
	s_nop 0
	v_max3_f32 v32, v32, v12, v13
	s_nop 0
	v_max_f32_e32 v32, v32, v33
	s_nop 0
	v_mov_b32_e32 v33, v32
	s_nop 1
	v_permlane32_swap_b32_e32 v32, v33
	v_max_f32_e32 v32, v32, v33
	s_nop 0
	v_add_f32_e32 v33, v161, v32
	v_sub_f32_e32 v16, v16, v32
	v_sub_f32_e32 v0, v0, v32
	v_sub_f32_e32 v17, v17, v32
	v_sub_f32_e32 v1, v1, v32
	v_sub_f32_e32 v18, v18, v32
	v_sub_f32_e32 v2, v2, v32
	v_sub_f32_e32 v19, v19, v32
	v_sub_f32_e32 v3, v3, v32
	v_sub_f32_e32 v20, v20, v32
	v_sub_f32_e32 v4, v4, v32
	v_sub_f32_e32 v21, v21, v32
	v_sub_f32_e32 v5, v5, v32
	v_sub_f32_e32 v22, v22, v32
	v_sub_f32_e32 v6, v6, v32
	v_sub_f32_e32 v23, v23, v32
	v_sub_f32_e32 v7, v7, v32
	v_sub_f32_e32 v24, v24, v32
	v_sub_f32_e32 v8, v8, v32
	v_sub_f32_e32 v25, v25, v32
	v_sub_f32_e32 v9, v9, v32
	v_sub_f32_e32 v26, v26, v32
	v_sub_f32_e32 v10, v10, v32
	v_sub_f32_e32 v27, v27, v32
	v_sub_f32_e32 v11, v11, v32
	v_sub_f32_e32 v28, v28, v32
	v_sub_f32_e32 v12, v12, v32
	v_sub_f32_e32 v29, v29, v32
	v_sub_f32_e32 v13, v13, v32
	v_sub_f32_e32 v30, v30, v32
	v_sub_f32_e32 v14, v14, v32
	v_sub_f32_e32 v31, v31, v32
	v_sub_f32_e32 v15, v15, v32
	s_nop 0
	v_xor_b32_e32 v32, 0x80000000, v33
	v_mov_b32_e32 v33, v32
	v_mov_b32_e32 v34, v32
	v_mov_b32_e32 v35, v32
	v_mov_b32_e32 v36, v32
	v_mov_b32_e32 v37, v32
	v_mov_b32_e32 v38, v32
	v_mov_b32_e32 v39, v32
	v_mov_b32_e32 v40, v32
	v_mov_b32_e32 v41, v32
	v_mov_b32_e32 v42, v32
	v_mov_b32_e32 v43, v32
	v_mov_b32_e32 v44, v32
	v_mov_b32_e32 v45, v32
	v_mov_b32_e32 v46, v32
	v_mov_b32_e32 v47, v32
	s_waitcnt vmcnt(0) lgkmcnt(0)
	s_barrier
	v_exp_f32_e32 v48, v0
	v_exp_f32_e32 v49, v1
	v_lshl_add_u64 v[0:1], v[154:155], 0, s[60:61]
	s_mov_b32 s51, m0
	s_mov_b32 m0, s29
	s_nop 0
	global_load_lds_dwordx4 v[0:1], off
	s_mov_b32 m0, s51
	v_lshl_add_u64 v[0:1], v[96:97], 0, s[56:57]
	s_mov_b32 s51, m0
	s_mov_b32 m0, s23
	s_nop 0
	global_load_lds_dwordx4 v[0:1], off
	s_mov_b32 m0, s51
	v_readlane_b32 s23, v253, 28
	ds_read_b128 v[88:91], v165 offset:8192
	ds_read_b128 v[80:83], v165 offset:8704
	ds_read_b128 v[92:95], v165 offset:9216
	ds_read_b128 v[84:87], v165 offset:9728
	s_add_u32 s23, s23, s96
	v_readlane_b32 s51, v253, 29
	s_addc_u32 s51, s51, 0
	s_add_u32 s22, s23, s22
	v_exp_f32_e32 v64, v16
	v_exp_f32_e32 v65, v17
	v_exp_f32_e32 v66, v18
	v_exp_f32_e32 v67, v19
	v_exp_f32_e32 v68, v20
	v_exp_f32_e32 v69, v21
	v_exp_f32_e32 v70, v22
	v_exp_f32_e32 v71, v23
	v_exp_f32_e32 v72, v24
	v_exp_f32_e32 v73, v25
	v_exp_f32_e32 v74, v26
	v_exp_f32_e32 v75, v27
	v_exp_f32_e32 v76, v28
	v_exp_f32_e32 v77, v29
	v_exp_f32_e32 v78, v30
	v_exp_f32_e32 v79, v31
	v_exp_f32_e32 v50, v2
	v_exp_f32_e32 v51, v3
	v_exp_f32_e32 v52, v4
	v_exp_f32_e32 v53, v5
	v_exp_f32_e32 v54, v6
	v_exp_f32_e32 v55, v7
	v_exp_f32_e32 v56, v8
	v_exp_f32_e32 v57, v9
	v_exp_f32_e32 v58, v10
	v_exp_f32_e32 v59, v11
	v_exp_f32_e32 v60, v12
	v_exp_f32_e32 v61, v13
	v_exp_f32_e32 v62, v14
	v_exp_f32_e32 v63, v15
	s_addc_u32 s23, s51, 0
	s_waitcnt vmcnt(2) lgkmcnt(0)
	s_barrier
	s_add_u32 s10, s22, s10
	s_mov_b64 s[56:57], 0x120500
	s_addc_u32 s11, s23, s11
	v_lshl_add_u64 v[112:113], v[96:97], 0, s[56:57]
	v_lshl_add_u64 v[114:115], s[10:11], 0, v[160:161]
	s_mov_b64 s[10:11], 0
	v_mov_b32_e32 v0, 0
	v_mov_b32_e32 v1, v118
	v_mov_b32_e32 v2, v118
	v_mov_b32_e32 v3, v118
	v_mov_b32_e32 v4, v118
	v_mov_b32_e32 v5, v118
	v_mov_b32_e32 v6, v118
	v_mov_b32_e32 v7, v118
	v_mov_b32_e32 v8, v118
	v_mov_b32_e32 v9, v118
	v_mov_b32_e32 v10, v118
	v_mov_b32_e32 v11, v118
	v_mov_b32_e32 v12, v118
	v_mov_b32_e32 v13, v118
	v_mov_b32_e32 v14, v118
	v_mov_b32_e32 v15, v118
	v_mov_b32_e32 v16, 0
	v_mov_b32_e32 v17, v118
	v_mov_b32_e32 v18, v118
	v_mov_b32_e32 v19, v118
	v_mov_b32_e32 v20, v118
	v_mov_b32_e32 v21, v118
	v_mov_b32_e32 v22, v118
	v_mov_b32_e32 v23, v118
	v_mov_b32_e32 v24, v118
	v_mov_b32_e32 v25, v118
	v_mov_b32_e32 v26, v118
	v_mov_b32_e32 v27, v118
	v_mov_b32_e32 v28, v118
	v_mov_b32_e32 v29, v118
	v_mov_b32_e32 v30, v118
	v_mov_b32_e32 v31, v118
	s_mov_b64 s[56:57], 0x8000
	s_mov_b32 s101, m0
.LBB0_543:
	s_add_i32 s22, s10, 0x8000
	s_and_b32 s22, s22, 0x6000
	v_add_u32_e32 v116, s22, v166
	ds_read_b64_tr_b16 v[120:121], v116 offset:24576
	ds_read_b64_tr_b16 v[122:123], v116 offset:25088
	s_add_i32 s23, s10, 0x2000
	v_add_f32_e32 v96, v64, v65
	v_add_f32_e32 v96, v66, v96
	v_add_f32_e32 v96, v67, v96
	v_add_f32_e32 v96, v68, v96
	v_add_f32_e32 v117, v69, v96
	v_cvt_pk_bf16_f32 v148, v64, v65
	v_cvt_pk_bf16_f32 v149, v66, v67
	v_mfma_scale_f32_32x32x64_f8f6f4 v[96:111], v[88:95], v[128:135], v[32:47], v242, v241 op_sel_hi:[0,0,0]
	ds_read_b64_tr_b16 v[64:65], v116 offset:28672
	ds_read_b64_tr_b16 v[66:67], v116 offset:29184
	v_add_f32_e32 v88, v70, v117
	v_add_f32_e32 v88, v71, v88
	v_add_f32_e32 v88, v72, v88
	v_add_f32_e32 v117, v73, v88
	v_mfma_scale_f32_32x32x64_f8f6f4 v[80:95], v[80:87], v[128:135], v[32:47], v242, v241 op_sel_hi:[0,0,0]
	v_cvt_pk_bf16_f32 v150, v68, v69
	v_cvt_pk_bf16_f32 v151, v70, v71
	ds_read_b64_tr_b16 v[68:69], v116 offset:25600
	ds_read_b64_tr_b16 v[70:71], v116 offset:26112
	v_add_f32_e32 v117, v74, v117
	v_add_f32_e32 v117, v75, v117
	v_add_f32_e32 v117, v76, v117
	v_add_f32_e32 v117, v77, v117
	v_cvt_pk_bf16_f32 v144, v72, v73
	v_cvt_pk_bf16_f32 v145, v74, v75
	ds_read_b64_tr_b16 v[72:73], v116 offset:29696
	ds_read_b64_tr_b16 v[74:75], v116 offset:30208
	v_add_f32_e32 v117, v78, v117
	v_add_f32_e32 v117, v79, v117
	v_add_f32_e32 v117, v48, v117
	v_add_f32_e32 v117, v49, v117
	v_cvt_pk_bf16_f32 v146, v76, v77
	v_cvt_pk_bf16_f32 v147, v78, v79
	ds_read_b64_tr_b16 v[76:77], v116 offset:26624
	ds_read_b64_tr_b16 v[78:79], v116 offset:27136
	v_add_f32_e32 v117, v50, v117
	v_add_f32_e32 v117, v51, v117
	v_add_f32_e32 v117, v52, v117
	v_add_f32_e32 v117, v53, v117
	v_cvt_pk_bf16_f32 v140, v48, v49
	v_cvt_pk_bf16_f32 v141, v50, v51
	ds_read_b64_tr_b16 v[124:125], v116 offset:30720
	ds_read_b64_tr_b16 v[126:127], v116 offset:31232
	v_add_f32_e32 v48, v54, v117
	v_add_f32_e32 v48, v55, v48
	v_add_f32_e32 v48, v56, v48
	v_add_f32_e32 v48, v57, v48
	v_cvt_pk_bf16_f32 v142, v52, v53
	v_cvt_pk_bf16_f32 v143, v54, v55
	ds_read_b64_tr_b16 v[168:169], v116 offset:27648
	ds_read_b64_tr_b16 v[170:171], v116 offset:28160
	v_add_f32_e32 v48, v58, v48
	v_add_f32_e32 v48, v59, v48
	v_add_f32_e32 v48, v60, v48
	v_add_f32_e32 v48, v61, v48
	v_cvt_pk_bf16_f32 v136, v56, v57
	v_cvt_pk_bf16_f32 v137, v58, v59
	ds_read_b64_tr_b16 v[172:173], v116 offset:31744
	ds_read_b64_tr_b16 v[174:175], v116 offset:32256
	v_add_f32_e32 v48, v62, v48
	v_add_f32_e32 v48, v63, v48
	v_add_f32_e32 v119, 0, v48
	v_cvt_pk_bf16_f32 v138, v60, v61
	v_cvt_pk_bf16_f32 v139, v62, v63
	v_lshl_add_u64 v[116:117], v[114:115], 0, s[10:11]
	s_add_i32 s50, s50, s29
	s_mov_b32 m0, s50
	v_lshl_add_u64 v[48:49], v[116:117], 0, s[60:61]
	global_load_lds_dwordx4 v[48:49], off
	s_add_i32 s50, s10, 0x6000
	s_and_b32 s50, s50, 0x6000
	s_add_i32 s50, s50, s44
	s_mov_b32 m0, s50
	v_lshl_add_u64 v[48:49], v[112:113], 0, s[36:37]
	global_load_lds_dwordx4 v[48:49], off
	s_waitcnt lgkmcnt(8)
	v_mfma_f32_32x32x16_bf16 v[0:15], v[148:151], v[120:123], v[0:15]
	v_exp_f32_e32 v96, v96
	v_exp_f32_e32 v97, v97
	v_exp_f32_e32 v98, v98
	v_exp_f32_e32 v99, v99
	v_mfma_f32_32x32x16_bf16 v[16:31], v[148:151], v[64:67], v[16:31]
	v_exp_f32_e32 v100, v100
	v_exp_f32_e32 v101, v101
	v_exp_f32_e32 v102, v102
	v_exp_f32_e32 v103, v103
	v_add_u32_e32 v60, s13, v165
	ds_read_b128 v[48:51], v60
	v_mfma_f32_32x32x16_bf16 v[0:15], v[144:147], v[68:71], v[0:15]
	v_exp_f32_e32 v104, v104
	v_exp_f32_e32 v105, v105
	v_exp_f32_e32 v106, v106
	v_exp_f32_e32 v107, v107
	ds_read_b128 v[52:55], v60 offset:1024
	v_mfma_f32_32x32x16_bf16 v[16:31], v[144:147], v[72:75], v[16:31]
	v_exp_f32_e32 v108, v108
	v_exp_f32_e32 v109, v109
	v_exp_f32_e32 v110, v110
	v_exp_f32_e32 v111, v111
	ds_read_b128 v[56:59], v60 offset:512
	s_waitcnt lgkmcnt(3)
	v_mfma_f32_32x32x16_bf16 v[0:15], v[140:143], v[76:79], v[0:15]
	v_exp_f32_e32 v80, v80
	v_exp_f32_e32 v81, v81
	v_exp_f32_e32 v82, v82
	v_exp_f32_e32 v83, v83
	ds_read_b128 v[60:63], v60 offset:1536
	v_mfma_f32_32x32x16_bf16 v[16:31], v[140:143], v[124:127], v[16:31]
	v_exp_f32_e32 v84, v84
	v_exp_f32_e32 v85, v85
	v_exp_f32_e32 v86, v86
	v_exp_f32_e32 v87, v87
	v_mfma_f32_32x32x16_bf16 v[0:15], v[136:139], v[168:171], v[0:15]
	v_exp_f32_e32 v88, v88
	v_exp_f32_e32 v89, v89
	v_exp_f32_e32 v90, v90
	v_exp_f32_e32 v91, v91
	v_mfma_f32_32x32x16_bf16 v[16:31], v[136:139], v[172:175], v[16:31]
	v_exp_f32_e32 v92, v92
	v_exp_f32_e32 v93, v93
	v_exp_f32_e32 v94, v94
	v_exp_f32_e32 v95, v95
	s_waitcnt vmcnt(3) lgkmcnt(0)
	s_barrier
; #define WAIT_BAR(N) asm volatile("s_waitcnt vmcnt(" #N ") lgkmcnt(0)\n\ts_barrier":::"memory")
;   #define RESC() do{ if(resc){ asm volatile("s_waitcnt lgkmcnt(0)":::"memory"); \
;       _Pragma("unroll") for(int d_=0;d_<2;++d_) _Pragma("unroll") for(int r=0;r<16;++r)o[d_][r]*=wsf[crow(r,hi)]; } }while(0)
;   #define ROT() do{sl_prev=sl_cur;sl_cur=sl_next;sl_next=(sl_next==(NSLOT-1)*SLOTB)?0:sl_next+SLOTB;}while(0)
; #define WAIT_BAR(N) asm volatile("s_waitcnt vmcnt(" #N ") lgkmcnt(0)\n\ts_barrier":::"memory")
;   #define RESC() do{ if(resc){ asm volatile("s_waitcnt lgkmcnt(0)":::"memory"); \
;       _Pragma("unroll") for(int d_=0;d_<4;++d_) _Pragma("unroll") for(int r=0;r<16;++r)o[d_][r]*=wsf[crow(r,hi)]; } }while(0)
;   #define ROT() do{sl_prev=sl_cur;sl_cur=sl_next;sl_next=(sl_next==(NSLOT-1)*SLOTB)?0:sl_next+SLOTB;}while(0)
; #define WAIT_BAR(N) asm volatile("s_waitcnt vmcnt(" #N ") lgkmcnt(0)\n\ts_barrier":::"memory")
;   #define RESC() do{ if(resc){ asm volatile("s_waitcnt lgkmcnt(0)":::"memory"); \
;       _Pragma("unroll") for(int d_=0;d_<2;++d_) _Pragma("unroll") for(int r=0;r<16;++r)o[d_][r]*=wsf[crow(r,hi)]; } }while(0)
;   #define ROT() do{sl_prev=sl_cur;sl_cur=sl_next;sl_next=(sl_next==(NSLOT-1)*SLOTB)?0:sl_next+SLOTB;}while(0)
; template<int THRL,bool FIXED> __device__ __forceinline__ void attn_unit(int qb,const bf16*Qp,const unsigned char*__restrict__ K8h,const bf16*__restrict__ Vh,bf16*Op,int PO,char*shm){
;     ...
;   int t=1;
;     ...
;   for(;t+5<NT;t+=2){
;     STEP(pB0,pB1,pA0,pA1,t,true,true,true);     WAIT_BAR(3); RESC(); ROT();
;     STEP(pA0,pA1,pB0,pB1,t+1,true,true,true);   WAIT_BAR(3); RESC(); ROT();
;   }
	s_add_i32 s50, s13, 0x2000
	s_cmpk_lg_i32 s13, 0x4000
	s_cselect_b32 s50, s50, 0
	s_and_b32 s23, s23, 0x6000
	v_add_u32_e32 v160, s23, v166
	ds_read_b64_tr_b16 v[120:121], v160 offset:24576
	ds_read_b64_tr_b16 v[122:123], v160 offset:25088
	v_add_f32_e32 v64, v96, v97
	v_add_f32_e32 v64, v98, v64
	v_add_f32_e32 v64, v99, v64
	v_add_f32_e32 v64, v100, v64
	v_add_f32_e32 v124, v101, v64
	v_mfma_scale_f32_32x32x64_f8f6f4 v[64:79], v[48:55], v[128:135], v[32:47], v242, v241 op_sel_hi:[0,0,0]
	v_cvt_pk_bf16_f32 v148, v96, v97
	v_cvt_pk_bf16_f32 v149, v98, v99
	ds_read_b64_tr_b16 v[96:97], v160 offset:28672
	ds_read_b64_tr_b16 v[98:99], v160 offset:29184
	v_add_f32_e32 v48, v102, v124
	v_add_f32_e32 v48, v103, v48
	v_add_f32_e32 v48, v104, v48
	v_add_f32_e32 v124, v105, v48
	v_mfma_scale_f32_32x32x64_f8f6f4 v[48:63], v[56:63], v[128:135], v[32:47], v242, v241 op_sel_hi:[0,0,0]
	v_cvt_pk_bf16_f32 v150, v100, v101
	v_cvt_pk_bf16_f32 v151, v102, v103
	ds_read_b64_tr_b16 v[100:101], v160 offset:25600
	ds_read_b64_tr_b16 v[102:103], v160 offset:26112
	v_add_f32_e32 v124, v106, v124
	v_add_f32_e32 v124, v107, v124
	v_add_f32_e32 v124, v108, v124
	v_add_f32_e32 v124, v109, v124
	v_cvt_pk_bf16_f32 v144, v104, v105
	v_cvt_pk_bf16_f32 v145, v106, v107
	ds_read_b64_tr_b16 v[104:105], v160 offset:29696
	ds_read_b64_tr_b16 v[106:107], v160 offset:30208
	v_add_f32_e32 v124, v110, v124
	v_add_f32_e32 v124, v111, v124
	v_add_f32_e32 v124, v80, v124
	v_add_f32_e32 v124, v81, v124
	v_cvt_pk_bf16_f32 v146, v108, v109
	v_cvt_pk_bf16_f32 v147, v110, v111
	ds_read_b64_tr_b16 v[108:109], v160 offset:26624
	ds_read_b64_tr_b16 v[110:111], v160 offset:27136
	v_add_f32_e32 v124, v82, v124
	v_add_f32_e32 v124, v83, v124
	v_add_f32_e32 v124, v84, v124
	v_add_f32_e32 v136, v85, v124
	v_cvt_pk_bf16_f32 v140, v80, v81
	v_cvt_pk_bf16_f32 v141, v82, v83
	ds_read_b64_tr_b16 v[124:125], v160 offset:30720
	ds_read_b64_tr_b16 v[126:127], v160 offset:31232
	v_add_f32_e32 v80, v86, v136
	v_add_f32_e32 v80, v87, v80
	v_add_f32_e32 v80, v88, v80
	v_add_f32_e32 v80, v89, v80
	v_cvt_pk_bf16_f32 v142, v84, v85
	v_cvt_pk_bf16_f32 v143, v86, v87
	ds_read_b64_tr_b16 v[168:169], v160 offset:27648
	ds_read_b64_tr_b16 v[170:171], v160 offset:28160
	v_add_f32_e32 v80, v90, v80
	v_add_f32_e32 v80, v91, v80
	v_add_f32_e32 v80, v92, v80
	v_add_f32_e32 v80, v93, v80
	v_cvt_pk_bf16_f32 v136, v88, v89
	v_cvt_pk_bf16_f32 v137, v90, v91
	ds_read_b64_tr_b16 v[172:173], v160 offset:31744
	ds_read_b64_tr_b16 v[174:175], v160 offset:32256
	v_add_f32_e32 v80, v94, v80
	v_add_f32_e32 v80, v95, v80
	v_add_f32_e32 v160, 0, v80
	v_cvt_pk_bf16_f32 v138, v92, v93
	v_cvt_pk_bf16_f32 v139, v94, v95
	s_add_i32 s13, s13, s29
	s_mov_b32 m0, s13
	v_lshl_add_u64 v[80:81], v[116:117], 0, s[56:57]
	global_load_lds_dwordx4 v[80:81], off
	s_add_i32 s13, s22, s44
	s_mov_b32 m0, s13
	s_nop 0
	global_load_lds_dwordx4 v[112:113], off
	s_waitcnt lgkmcnt(8)
	v_mfma_f32_32x32x16_bf16 v[0:15], v[148:151], v[120:123], v[0:15]
	v_exp_f32_e32 v64, v64
	v_exp_f32_e32 v65, v65
	v_exp_f32_e32 v66, v66
	v_exp_f32_e32 v67, v67
	v_mfma_f32_32x32x16_bf16 v[16:31], v[148:151], v[96:99], v[16:31]
	v_exp_f32_e32 v68, v68
	v_exp_f32_e32 v69, v69
	v_exp_f32_e32 v70, v70
	v_exp_f32_e32 v71, v71
	v_add_u32_e32 v84, s50, v165
	ds_read_b128 v[88:91], v84
	v_mfma_f32_32x32x16_bf16 v[0:15], v[144:147], v[100:103], v[0:15]
	v_exp_f32_e32 v72, v72
	v_exp_f32_e32 v73, v73
	v_exp_f32_e32 v74, v74
	v_exp_f32_e32 v75, v75
	ds_read_b128 v[92:95], v84 offset:1024
	v_mfma_f32_32x32x16_bf16 v[16:31], v[144:147], v[104:107], v[16:31]
	v_exp_f32_e32 v76, v76
	v_exp_f32_e32 v77, v77
	v_exp_f32_e32 v78, v78
	v_exp_f32_e32 v79, v79
	ds_read_b128 v[80:83], v84 offset:512
	s_waitcnt lgkmcnt(3)
	v_mfma_f32_32x32x16_bf16 v[0:15], v[140:143], v[108:111], v[0:15]
	v_exp_f32_e32 v48, v48
	v_exp_f32_e32 v49, v49
	v_exp_f32_e32 v50, v50
	v_exp_f32_e32 v51, v51
	ds_read_b128 v[84:87], v84 offset:1536
	v_mfma_f32_32x32x16_bf16 v[16:31], v[140:143], v[124:127], v[16:31]
	v_exp_f32_e32 v52, v52
	v_exp_f32_e32 v53, v53
	v_exp_f32_e32 v54, v54
	v_exp_f32_e32 v55, v55
	v_mfma_f32_32x32x16_bf16 v[0:15], v[136:139], v[168:171], v[0:15]
	v_exp_f32_e32 v56, v56
	v_exp_f32_e32 v57, v57
	v_exp_f32_e32 v58, v58
	v_exp_f32_e32 v59, v59
	v_mfma_f32_32x32x16_bf16 v[16:31], v[136:139], v[172:175], v[16:31]
	v_exp_f32_e32 v60, v60
	v_exp_f32_e32 v61, v61
	v_exp_f32_e32 v62, v62
	v_exp_f32_e32 v63, v63
	s_add_i32 s13, s50, 0x2000
	s_cmpk_lg_i32 s50, 0x4000
	s_cselect_b32 s13, s13, 0
	s_add_i32 s12, s12, 2
	s_waitcnt vmcnt(3) lgkmcnt(0)
	s_barrier
	s_add_u32 s10, s10, 0x4000
	v_add_f32_e32 v96, v118, v119
	s_addc_u32 s11, s11, 0
	v_lshl_add_u64 v[112:113], v[112:113], 0, s[40:41]
	s_cmpk_gt_u32 s12, 0xf8
	v_add_f32_e32 v118, v96, v160
	s_cbranch_scc0 .LBB0_543
; #define WAIT_BAR(N) asm volatile("s_waitcnt vmcnt(" #N ") lgkmcnt(0)\n\ts_barrier":::"memory")
;   #define RESC() do{ if(resc){ asm volatile("s_waitcnt lgkmcnt(0)":::"memory"); \
;       _Pragma("unroll") for(int d_=0;d_<2;++d_) _Pragma("unroll") for(int r=0;r<16;++r)o[d_][r]*=wsf[crow(r,hi)]; } }while(0)
;   #define ROT() do{sl_prev=sl_cur;sl_cur=sl_next;sl_next=(sl_next==(NSLOT-1)*SLOTB)?0:sl_next+SLOTB;}while(0)
;   #define ENDW(tt) do{ if((tt)+3<NT){WAIT_BAR(3);} else if((tt)+2<NT){WAIT_BAR(2);} else {WAIT_BAR(0);} }while(0)
; #define WAIT_BAR(N) asm volatile("s_waitcnt vmcnt(" #N ") lgkmcnt(0)\n\ts_barrier":::"memory")
;   #define RESC() do{ if(resc){ asm volatile("s_waitcnt lgkmcnt(0)":::"memory"); \
;       _Pragma("unroll") for(int d_=0;d_<4;++d_) _Pragma("unroll") for(int r=0;r<16;++r)o[d_][r]*=wsf[crow(r,hi)]; } }while(0)
;   #define ROT() do{sl_prev=sl_cur;sl_cur=sl_next;sl_next=(sl_next==(NSLOT-1)*SLOTB)?0:sl_next+SLOTB;}while(0)
;   #define ENDW(tt) do{ if((tt)+3<NT){WAIT_BAR(5);} else if((tt)+2<NT){WAIT_BAR(4);} else {WAIT_BAR(0);} }while(0)
; #define WAIT_BAR(N) asm volatile("s_waitcnt vmcnt(" #N ") lgkmcnt(0)\n\ts_barrier":::"memory")
;   #define RESC() do{ if(resc){ asm volatile("s_waitcnt lgkmcnt(0)":::"memory"); \
;       _Pragma("unroll") for(int d_=0;d_<2;++d_) _Pragma("unroll") for(int r=0;r<16;++r)o[d_][r]*=wsf[crow(r,hi)]; } }while(0)
;   #define ROT() do{sl_prev=sl_cur;sl_cur=sl_next;sl_next=(sl_next==(NSLOT-1)*SLOTB)?0:sl_next+SLOTB;}while(0)
;   #define ENDW(tt) do{ if((tt)+3<NT){WAIT_BAR(3);} else if((tt)+2<NT){WAIT_BAR(2);} else {WAIT_BAR(0);} }while(0)
; template<int THRL,bool FIXED> __device__ __forceinline__ void attn_unit(int qb,const bf16*Qp,const unsigned char*__restrict__ K8h,const bf16*__restrict__ Vh,bf16*Op,int PO,char*shm){
;     ...
;   int t=1;
;     ...
;   for(;t+5<NT;t+=2){
;     STEP(pB0,pB1,pA0,pA1,t,true,true,true);     WAIT_BAR(3); RESC(); ROT();
;     STEP(pA0,pA1,pB0,pB1,t+1,true,true,true);   WAIT_BAR(3); RESC(); ROT();
;   }
;     ...
;   for(;t+1<NT;t+=2){
;     STEP(pB0,pB1,pA0,pA1,t,(t+3<NT),(t+2<NT),(t+1<NT));       ENDW(t);   RESC(); ROT();
	s_mov_b32 m0, s101
	s_and_b32 s10, s34, 0x3fffffc0
	s_lshl_b32 s10, s10, 2
	s_add_i32 s12, s10, 0
	ds_read_b64_tr_b16 v[112:113], v166 offset:40960
	ds_read_b64_tr_b16 v[114:115], v166 offset:41472
	v_add_f32_e32 v96, v64, v65
	v_add_f32_e32 v96, v66, v96
	v_add_f32_e32 v96, v67, v96
	v_add_f32_e32 v96, v68, v96
	v_add_f32_e32 v116, v69, v96
	v_cvt_pk_bf16_f32 v148, v64, v65
	v_cvt_pk_bf16_f32 v149, v66, v67
	s_waitcnt lgkmcnt(4)
	v_mfma_scale_f32_32x32x64_f8f6f4 v[96:111], v[88:95], v[128:135], v[32:47], v242, v241 op_sel_hi:[0,0,0]
	ds_read_b64_tr_b16 v[64:65], v166 offset:45056
	ds_read_b64_tr_b16 v[66:67], v166 offset:45568
	v_add_f32_e32 v88, v70, v116
	v_add_f32_e32 v88, v71, v88
	v_add_f32_e32 v88, v72, v88
	v_add_f32_e32 v116, v73, v88
	v_cvt_pk_bf16_f32 v150, v68, v69
	v_cvt_pk_bf16_f32 v151, v70, v71
	s_waitcnt lgkmcnt(4)
	v_mfma_scale_f32_32x32x64_f8f6f4 v[80:95], v[80:87], v[128:135], v[32:47], v242, v241 op_sel_hi:[0,0,0]
	ds_read_b64_tr_b16 v[68:69], v166 offset:41984
	ds_read_b64_tr_b16 v[70:71], v166 offset:42496
	v_add_f32_e32 v116, v74, v116
	v_add_f32_e32 v116, v75, v116
	v_add_f32_e32 v116, v76, v116
	v_add_f32_e32 v116, v77, v116
	v_cvt_pk_bf16_f32 v144, v72, v73
	v_cvt_pk_bf16_f32 v145, v74, v75
	ds_read_b64_tr_b16 v[72:73], v166 offset:46080
	ds_read_b64_tr_b16 v[74:75], v166 offset:46592
	v_add_f32_e32 v116, v78, v116
	v_add_f32_e32 v116, v79, v116
	v_add_f32_e32 v116, v48, v116
	v_add_f32_e32 v116, v49, v116
	v_cvt_pk_bf16_f32 v146, v76, v77
	v_cvt_pk_bf16_f32 v147, v78, v79
	ds_read_b64_tr_b16 v[76:77], v166 offset:43008
	ds_read_b64_tr_b16 v[78:79], v166 offset:43520
	v_add_f32_e32 v116, v50, v116
	v_add_f32_e32 v116, v51, v116
	v_add_f32_e32 v116, v52, v116
	v_add_f32_e32 v116, v53, v116
	v_cvt_pk_bf16_f32 v140, v48, v49
	v_cvt_pk_bf16_f32 v141, v50, v51
	ds_read_b64_tr_b16 v[120:121], v166 offset:47104
	ds_read_b64_tr_b16 v[122:123], v166 offset:47616
	v_add_f32_e32 v48, v54, v116
	v_add_f32_e32 v48, v55, v48
	v_add_f32_e32 v48, v56, v48
	v_add_f32_e32 v48, v57, v48
	v_cvt_pk_bf16_f32 v142, v52, v53
	v_cvt_pk_bf16_f32 v143, v54, v55
	ds_read_b64_tr_b16 v[124:125], v166 offset:44032
	ds_read_b64_tr_b16 v[126:127], v166 offset:44544
	v_add_f32_e32 v48, v58, v48
	v_add_f32_e32 v48, v59, v48
	v_add_f32_e32 v48, v60, v48
	v_add_f32_e32 v48, v61, v48
	v_cvt_pk_bf16_f32 v136, v56, v57
	v_cvt_pk_bf16_f32 v137, v58, v59
	ds_read_b64_tr_b16 v[168:169], v166 offset:48128
	ds_read_b64_tr_b16 v[170:171], v166 offset:48640
	v_add_f32_e32 v48, v62, v48
	v_add_f32_e32 v48, v63, v48
	v_add_f32_e32 v48, 0, v48
	v_cvt_pk_bf16_f32 v138, v60, v61
	v_cvt_pk_bf16_f32 v139, v62, v63
	s_mov_b64 s[22:23], 0x1fc000
	v_add_f32_e32 v160, v118, v48
	s_add_i32 s10, s50, s29
	v_lshl_add_u64 v[48:49], v[154:155], 0, s[22:23]
	s_mov_b32 s11, m0
	s_mov_b32 m0, s10
	s_nop 0
	global_load_lds_dwordx4 v[48:49], off
	s_mov_b32 m0, s11
	s_mov_b64 s[10:11], 0x4728000
	s_cmp_lg_u32 0, -1
	v_lshl_add_u64 v[48:49], v[152:153], 0, s[10:11]
	s_cselect_b32 s10, 0, 0
	s_add_i32 s11, s10, s28
	s_add_i32 s22, s11, 0x8000
	s_mov_b32 s23, m0
	s_mov_b32 m0, s22
	s_nop 0
	global_load_lds_dwordx4 v[48:49], off
	s_mov_b32 m0, s23
	s_waitcnt lgkmcnt(14)
	v_mfma_f32_32x32x16_bf16 v[0:15], v[148:151], v[112:115], v[0:15]
	v_exp_f32_e32 v96, v96
	v_exp_f32_e32 v97, v97
	v_exp_f32_e32 v98, v98
	v_exp_f32_e32 v99, v99
	s_waitcnt lgkmcnt(12)
	v_mfma_f32_32x32x16_bf16 v[16:31], v[148:151], v[64:67], v[16:31]
	v_exp_f32_e32 v100, v100
	v_exp_f32_e32 v101, v101
	v_exp_f32_e32 v102, v102
	v_exp_f32_e32 v103, v103
	v_add_u32_e32 v60, s13, v165
	ds_read_b128 v[48:51], v60
	s_waitcnt lgkmcnt(11)
	v_mfma_f32_32x32x16_bf16 v[0:15], v[144:147], v[68:71], v[0:15]
	v_exp_f32_e32 v104, v104
	v_exp_f32_e32 v105, v105
	v_exp_f32_e32 v106, v106
	v_exp_f32_e32 v107, v107
	ds_read_b128 v[52:55], v60 offset:1024
	s_waitcnt lgkmcnt(10)
	v_mfma_f32_32x32x16_bf16 v[16:31], v[144:147], v[72:75], v[16:31]
	v_exp_f32_e32 v108, v108
	v_exp_f32_e32 v109, v109
	v_exp_f32_e32 v110, v110
	v_exp_f32_e32 v111, v111
	ds_read_b128 v[56:59], v60 offset:512
	s_waitcnt lgkmcnt(9)
	v_mfma_f32_32x32x16_bf16 v[0:15], v[140:143], v[76:79], v[0:15]
	v_exp_f32_e32 v80, v80
	v_exp_f32_e32 v81, v81
	v_exp_f32_e32 v82, v82
	v_exp_f32_e32 v83, v83
	ds_read_b128 v[60:63], v60 offset:1536
	s_waitcnt lgkmcnt(8)
	v_mfma_f32_32x32x16_bf16 v[16:31], v[140:143], v[120:123], v[16:31]
	v_exp_f32_e32 v84, v84
	v_exp_f32_e32 v85, v85
	v_exp_f32_e32 v86, v86
	v_exp_f32_e32 v87, v87
	s_waitcnt lgkmcnt(6)
	v_mfma_f32_32x32x16_bf16 v[0:15], v[136:139], v[124:127], v[0:15]
	v_exp_f32_e32 v88, v88
	v_exp_f32_e32 v89, v89
	v_exp_f32_e32 v90, v90
	v_exp_f32_e32 v91, v91
	s_waitcnt lgkmcnt(4)
	v_mfma_f32_32x32x16_bf16 v[16:31], v[136:139], v[168:171], v[16:31]
	v_exp_f32_e32 v92, v92
	v_exp_f32_e32 v93, v93
	v_exp_f32_e32 v94, v94
	v_exp_f32_e32 v95, v95
	s_waitcnt vmcnt(3) lgkmcnt(0)
	s_barrier
; #define WAIT_BAR(N) asm volatile("s_waitcnt vmcnt(" #N ") lgkmcnt(0)\n\ts_barrier":::"memory")
;   #define RESC() do{ if(resc){ asm volatile("s_waitcnt lgkmcnt(0)":::"memory"); \
;       _Pragma("unroll") for(int d_=0;d_<2;++d_) _Pragma("unroll") for(int r=0;r<16;++r)o[d_][r]*=wsf[crow(r,hi)]; } }while(0)
;   #define ROT() do{sl_prev=sl_cur;sl_cur=sl_next;sl_next=(sl_next==(NSLOT-1)*SLOTB)?0:sl_next+SLOTB;}while(0)
;   #define ENDW(tt) do{ if((tt)+3<NT){WAIT_BAR(3);} else if((tt)+2<NT){WAIT_BAR(2);} else {WAIT_BAR(0);} }while(0)
; #define WAIT_BAR(N) asm volatile("s_waitcnt vmcnt(" #N ") lgkmcnt(0)\n\ts_barrier":::"memory")
;   #define RESC() do{ if(resc){ asm volatile("s_waitcnt lgkmcnt(0)":::"memory"); \
;       _Pragma("unroll") for(int d_=0;d_<4;++d_) _Pragma("unroll") for(int r=0;r<16;++r)o[d_][r]*=wsf[crow(r,hi)]; } }while(0)
;   #define ROT() do{sl_prev=sl_cur;sl_cur=sl_next;sl_next=(sl_next==(NSLOT-1)*SLOTB)?0:sl_next+SLOTB;}while(0)
;   #define ENDW(tt) do{ if((tt)+3<NT){WAIT_BAR(5);} else if((tt)+2<NT){WAIT_BAR(4);} else {WAIT_BAR(0);} }while(0)
; #define WAIT_BAR(N) asm volatile("s_waitcnt vmcnt(" #N ") lgkmcnt(0)\n\ts_barrier":::"memory")
;   #define RESC() do{ if(resc){ asm volatile("s_waitcnt lgkmcnt(0)":::"memory"); \
;       _Pragma("unroll") for(int d_=0;d_<2;++d_) _Pragma("unroll") for(int r=0;r<16;++r)o[d_][r]*=wsf[crow(r,hi)]; } }while(0)
;   #define ROT() do{sl_prev=sl_cur;sl_cur=sl_next;sl_next=(sl_next==(NSLOT-1)*SLOTB)?0:sl_next+SLOTB;}while(0)
;   #define ENDW(tt) do{ if((tt)+3<NT){WAIT_BAR(3);} else if((tt)+2<NT){WAIT_BAR(2);} else {WAIT_BAR(0);} }while(0)
; template<int THRL,bool FIXED> __device__ __forceinline__ void attn_unit(int qb,const bf16*Qp,const unsigned char*__restrict__ K8h,const bf16*__restrict__ Vh,bf16*Op,int PO,char*shm){
;     ...
;   int t=1;
;     ...
;   for(;t+5<NT;t+=2){
;     STEP(pB0,pB1,pA0,pA1,t,true,true,true);     WAIT_BAR(3); RESC(); ROT();
;     STEP(pA0,pA1,pB0,pB1,t+1,true,true,true);   WAIT_BAR(3); RESC(); ROT();
;   }
;     ...
;   for(;t+1<NT;t+=2){
;     STEP(pB0,pB1,pA0,pA1,t,(t+3<NT),(t+2<NT),(t+1<NT));       ENDW(t);   RESC(); ROT();
;     STEP(pA0,pA1,pB0,pB1,t+1,(t+4<NT),(t+3<NT),(t+2<NT));     ENDW(t+1); RESC(); ROT();
	s_add_i32 s22, s13, 0x2000
	s_cmpk_lg_i32 s13, 0x4000
	s_cselect_b32 s22, s22, 0
	ds_read_b64_tr_b16 v[64:65], v166 offset:49152
	ds_read_b64_tr_b16 v[66:67], v166 offset:49664
	v_add_f32_e32 v68, v96, v97
	v_add_f32_e32 v68, v98, v68
	v_add_f32_e32 v68, v99, v68
	v_add_f32_e32 v68, v100, v68
	v_add_f32_e32 v72, v101, v68
	v_cvt_pk_bf16_f32 v148, v96, v97
	v_cvt_pk_bf16_f32 v149, v98, v99
	s_waitcnt lgkmcnt(4)
	v_mfma_scale_f32_32x32x64_f8f6f4 v[112:127], v[48:55], v[128:135], v[32:47], v242, v241 op_sel_hi:[0,0,0]
	ds_read_b64_tr_b16 v[68:69], v166 offset:53248
	ds_read_b64_tr_b16 v[70:71], v166 offset:53760
	v_add_f32_e32 v48, v102, v72
	v_add_f32_e32 v48, v103, v48
	v_add_f32_e32 v48, v104, v48
	v_add_f32_e32 v76, v105, v48
	s_waitcnt lgkmcnt(4)
	v_mfma_scale_f32_32x32x64_f8f6f4 v[48:63], v[56:63], v[128:135], v[32:47], v242, v241 op_sel_hi:[0,0,0]
	v_cvt_pk_bf16_f32 v150, v100, v101
	v_cvt_pk_bf16_f32 v151, v102, v103
	ds_read_b64_tr_b16 v[72:73], v166 offset:50176
	ds_read_b64_tr_b16 v[74:75], v166 offset:50688
	v_add_f32_e32 v76, v106, v76
	v_add_f32_e32 v76, v107, v76
	v_add_f32_e32 v76, v108, v76
	v_add_f32_e32 v96, v109, v76
	v_cvt_pk_bf16_f32 v144, v104, v105
	v_cvt_pk_bf16_f32 v145, v106, v107
	ds_read_b64_tr_b16 v[76:77], v166 offset:54272
	ds_read_b64_tr_b16 v[78:79], v166 offset:54784
	v_add_f32_e32 v96, v110, v96
	v_add_f32_e32 v96, v111, v96
	v_add_f32_e32 v96, v80, v96
	v_add_f32_e32 v100, v81, v96
	v_cvt_pk_bf16_f32 v146, v108, v109
	v_cvt_pk_bf16_f32 v147, v110, v111
	ds_read_b64_tr_b16 v[96:97], v166 offset:51200
	ds_read_b64_tr_b16 v[98:99], v166 offset:51712
	v_add_f32_e32 v100, v82, v100
	v_add_f32_e32 v100, v83, v100
	v_add_f32_e32 v100, v84, v100
	v_add_f32_e32 v100, v85, v100
	v_cvt_pk_bf16_f32 v140, v80, v81
	v_cvt_pk_bf16_f32 v141, v82, v83
	ds_read_b64_tr_b16 v[80:81], v166 offset:55296
	ds_read_b64_tr_b16 v[82:83], v166 offset:55808
	v_add_f32_e32 v100, v86, v100
	v_add_f32_e32 v100, v87, v100
	v_add_f32_e32 v100, v88, v100
	v_add_f32_e32 v100, v89, v100
	v_cvt_pk_bf16_f32 v142, v84, v85
	v_cvt_pk_bf16_f32 v143, v86, v87
	ds_read_b64_tr_b16 v[84:85], v166 offset:52224
	ds_read_b64_tr_b16 v[86:87], v166 offset:52736
	v_add_f32_e32 v100, v90, v100
	v_add_f32_e32 v100, v91, v100
	v_add_f32_e32 v100, v92, v100
	v_add_f32_e32 v100, v93, v100
	v_cvt_pk_bf16_f32 v136, v88, v89
	v_cvt_pk_bf16_f32 v137, v90, v91
	ds_read_b64_tr_b16 v[88:89], v166 offset:56320
	ds_read_b64_tr_b16 v[90:91], v166 offset:56832
	v_add_f32_e32 v100, v94, v100
	v_add_f32_e32 v100, v95, v100
	v_add_f32_e32 v100, 0, v100
	v_cvt_pk_bf16_f32 v138, v92, v93
	v_cvt_pk_bf16_f32 v139, v94, v95
	s_mov_b64 s[50:51], 0x1fe000
	s_add_i32 s13, s13, s29
	v_lshl_add_u64 v[92:93], v[154:155], 0, s[50:51]
	s_mov_b32 s23, m0
	s_mov_b32 m0, s13
	s_nop 0
	global_load_lds_dwordx4 v[92:93], off
	s_mov_b32 m0, s23
	v_lshl_add_u64 v[92:93], v[152:153], 0, s[42:43]
	s_add_i32 s11, s11, 0xa000
	s_mov_b32 s13, m0
	s_mov_b32 m0, s11
	s_nop 0
	global_load_lds_dwordx4 v[92:93], off
	s_mov_b32 m0, s13
	v_add_f32_e32 v160, v160, v100
	s_waitcnt lgkmcnt(14)
	v_mfma_f32_32x32x16_bf16 v[0:15], v[148:151], v[64:67], v[0:15]
	v_exp_f32_e32 v112, v112
	v_exp_f32_e32 v113, v113
	v_exp_f32_e32 v114, v114
	v_exp_f32_e32 v115, v115
	s_waitcnt lgkmcnt(12)
	v_mfma_f32_32x32x16_bf16 v[16:31], v[148:151], v[68:71], v[16:31]
	v_exp_f32_e32 v116, v116
	v_exp_f32_e32 v117, v117
	v_exp_f32_e32 v118, v118
	v_exp_f32_e32 v119, v119
	v_add_u32_e32 v92, s22, v165
	ds_read_b128 v[64:67], v92
	s_waitcnt lgkmcnt(11)
	v_mfma_f32_32x32x16_bf16 v[0:15], v[144:147], v[72:75], v[0:15]
	v_exp_f32_e32 v120, v120
	v_exp_f32_e32 v121, v121
	v_exp_f32_e32 v122, v122
	v_exp_f32_e32 v123, v123
	ds_read_b128 v[68:71], v92 offset:1024
	s_waitcnt lgkmcnt(10)
	v_mfma_f32_32x32x16_bf16 v[16:31], v[144:147], v[76:79], v[16:31]
	v_exp_f32_e32 v124, v124
	v_exp_f32_e32 v125, v125
	v_exp_f32_e32 v126, v126
	v_exp_f32_e32 v127, v127
	ds_read_b128 v[72:75], v92 offset:512
	s_waitcnt lgkmcnt(9)
	v_mfma_f32_32x32x16_bf16 v[0:15], v[140:143], v[96:99], v[0:15]
	v_exp_f32_e32 v48, v48
	v_exp_f32_e32 v49, v49
	v_exp_f32_e32 v50, v50
	v_exp_f32_e32 v51, v51
	ds_read_b128 v[76:79], v92 offset:1536
	s_waitcnt lgkmcnt(8)
	v_mfma_f32_32x32x16_bf16 v[16:31], v[140:143], v[80:83], v[16:31]
	v_exp_f32_e32 v52, v52
	v_exp_f32_e32 v53, v53
	v_exp_f32_e32 v54, v54
	v_exp_f32_e32 v55, v55
	s_waitcnt lgkmcnt(6)
	v_mfma_f32_32x32x16_bf16 v[0:15], v[136:139], v[84:87], v[0:15]
	v_exp_f32_e32 v56, v56
	v_exp_f32_e32 v57, v57
	v_exp_f32_e32 v58, v58
	v_exp_f32_e32 v59, v59
	s_waitcnt lgkmcnt(4)
	v_mfma_f32_32x32x16_bf16 v[16:31], v[136:139], v[88:91], v[16:31]
	v_exp_f32_e32 v60, v60
	v_exp_f32_e32 v61, v61
	v_exp_f32_e32 v62, v62
	v_exp_f32_e32 v63, v63
	s_waitcnt vmcnt(3) lgkmcnt(0)
	s_barrier
; #define WAIT_BAR(N) asm volatile("s_waitcnt vmcnt(" #N ") lgkmcnt(0)\n\ts_barrier":::"memory")
;   #define RESC() do{ if(resc){ asm volatile("s_waitcnt lgkmcnt(0)":::"memory"); \
;       _Pragma("unroll") for(int d_=0;d_<2;++d_) _Pragma("unroll") for(int r=0;r<16;++r)o[d_][r]*=wsf[crow(r,hi)]; } }while(0)
;   #define ROT() do{sl_prev=sl_cur;sl_cur=sl_next;sl_next=(sl_next==(NSLOT-1)*SLOTB)?0:sl_next+SLOTB;}while(0)
;   #define ENDW(tt) do{ if((tt)+3<NT){WAIT_BAR(3);} else if((tt)+2<NT){WAIT_BAR(2);} else {WAIT_BAR(0);} }while(0)
; #define WAIT_BAR(N) asm volatile("s_waitcnt vmcnt(" #N ") lgkmcnt(0)\n\ts_barrier":::"memory")
;   #define RESC() do{ if(resc){ asm volatile("s_waitcnt lgkmcnt(0)":::"memory"); \
;       _Pragma("unroll") for(int d_=0;d_<4;++d_) _Pragma("unroll") for(int r=0;r<16;++r)o[d_][r]*=wsf[crow(r,hi)]; } }while(0)
;   #define ROT() do{sl_prev=sl_cur;sl_cur=sl_next;sl_next=(sl_next==(NSLOT-1)*SLOTB)?0:sl_next+SLOTB;}while(0)
;   #define ENDW(tt) do{ if((tt)+3<NT){WAIT_BAR(5);} else if((tt)+2<NT){WAIT_BAR(4);} else {WAIT_BAR(0);} }while(0)
; #define WAIT_BAR(N) asm volatile("s_waitcnt vmcnt(" #N ") lgkmcnt(0)\n\ts_barrier":::"memory")
;   #define RESC() do{ if(resc){ asm volatile("s_waitcnt lgkmcnt(0)":::"memory"); \
;       _Pragma("unroll") for(int d_=0;d_<2;++d_) _Pragma("unroll") for(int r=0;r<16;++r)o[d_][r]*=wsf[crow(r,hi)]; } }while(0)
;   #define ROT() do{sl_prev=sl_cur;sl_cur=sl_next;sl_next=(sl_next==(NSLOT-1)*SLOTB)?0:sl_next+SLOTB;}while(0)
;   #define ENDW(tt) do{ if((tt)+3<NT){WAIT_BAR(3);} else if((tt)+2<NT){WAIT_BAR(2);} else {WAIT_BAR(0);} }while(0)
; template<int THRL,bool FIXED> __device__ __forceinline__ void attn_unit(int qb,const bf16*Qp,const unsigned char*__restrict__ K8h,const bf16*__restrict__ Vh,bf16*Op,int PO,char*shm){
;     ...
;   int t=1;
;     ...
;   for(;t+5<NT;t+=2){
;     STEP(pB0,pB1,pA0,pA1,t,true,true,true);     WAIT_BAR(3); RESC(); ROT();
;     STEP(pA0,pA1,pB0,pB1,t+1,true,true,true);   WAIT_BAR(3); RESC(); ROT();
;   }
;     ...
;   for(;t+1<NT;t+=2){
;     STEP(pB0,pB1,pA0,pA1,t,(t+3<NT),(t+2<NT),(t+1<NT));       ENDW(t);   RESC(); ROT();
;     STEP(pA0,pA1,pB0,pB1,t+1,(t+4<NT),(t+3<NT),(t+2<NT));     ENDW(t+1); RESC(); ROT();
	s_add_i32 s11, s22, 0x2000
	s_cmpk_lg_i32 s22, 0x4000
	s_cselect_b32 s11, s11, 0
	ds_read_b64_tr_b16 v[80:81], v166 offset:24576
	ds_read_b64_tr_b16 v[82:83], v166 offset:25088
	v_add_f32_e32 v84, v112, v113
	v_add_f32_e32 v84, v114, v84
	v_add_f32_e32 v84, v115, v84
	v_add_f32_e32 v84, v116, v84
	v_add_f32_e32 v88, v117, v84
	v_cvt_pk_bf16_f32 v148, v112, v113
	v_cvt_pk_bf16_f32 v149, v114, v115
	s_waitcnt lgkmcnt(4)
	v_mfma_scale_f32_32x32x64_f8f6f4 v[96:111], v[64:71], v[128:135], v[32:47], v242, v241 op_sel_hi:[0,0,0]
	ds_read_b64_tr_b16 v[84:85], v166 offset:28672
	ds_read_b64_tr_b16 v[86:87], v166 offset:29184
	v_add_f32_e32 v64, v118, v88
	v_add_f32_e32 v64, v119, v64
	v_add_f32_e32 v64, v120, v64
	v_add_f32_e32 v92, v121, v64
	v_cvt_pk_bf16_f32 v150, v116, v117
	v_cvt_pk_bf16_f32 v151, v118, v119
	s_waitcnt lgkmcnt(4)
	v_mfma_scale_f32_32x32x64_f8f6f4 v[64:79], v[72:79], v[128:135], v[32:47], v242, v241 op_sel_hi:[0,0,0]
	ds_read_b64_tr_b16 v[88:89], v166 offset:25600
	ds_read_b64_tr_b16 v[90:91], v166 offset:26112
	v_add_f32_e32 v92, v122, v92
	v_add_f32_e32 v92, v123, v92
	v_add_f32_e32 v92, v124, v92
	v_add_f32_e32 v112, v125, v92
	v_cvt_pk_bf16_f32 v144, v120, v121
	v_cvt_pk_bf16_f32 v145, v122, v123
	ds_read_b64_tr_b16 v[92:93], v166 offset:29696
	ds_read_b64_tr_b16 v[94:95], v166 offset:30208
	v_add_f32_e32 v112, v126, v112
	v_add_f32_e32 v112, v127, v112
	v_add_f32_e32 v112, v48, v112
	v_add_f32_e32 v116, v49, v112
	v_cvt_pk_bf16_f32 v146, v124, v125
	v_cvt_pk_bf16_f32 v147, v126, v127
	ds_read_b64_tr_b16 v[112:113], v166 offset:26624
	ds_read_b64_tr_b16 v[114:115], v166 offset:27136
	v_add_f32_e32 v116, v50, v116
	v_add_f32_e32 v116, v51, v116
	v_add_f32_e32 v116, v52, v116
	v_add_f32_e32 v120, v53, v116
	v_cvt_pk_bf16_f32 v140, v48, v49
	v_cvt_pk_bf16_f32 v141, v50, v51
	ds_read_b64_tr_b16 v[116:117], v166 offset:30720
	ds_read_b64_tr_b16 v[118:119], v166 offset:31232
	v_add_f32_e32 v48, v54, v120
	v_add_f32_e32 v48, v55, v48
	v_add_f32_e32 v48, v56, v48
	v_add_f32_e32 v48, v57, v48
	v_cvt_pk_bf16_f32 v142, v52, v53
	v_cvt_pk_bf16_f32 v143, v54, v55
	ds_read_b64_tr_b16 v[120:121], v166 offset:27648
	ds_read_b64_tr_b16 v[122:123], v166 offset:28160
	v_add_f32_e32 v48, v58, v48
	v_add_f32_e32 v48, v59, v48
	v_add_f32_e32 v48, v60, v48
	v_add_f32_e32 v48, v61, v48
	v_cvt_pk_bf16_f32 v136, v56, v57
	v_cvt_pk_bf16_f32 v137, v58, v59
	ds_read_b64_tr_b16 v[124:125], v166 offset:31744
	ds_read_b64_tr_b16 v[126:127], v166 offset:32256
	v_add_f32_e32 v48, v62, v48
	v_add_f32_e32 v48, v63, v48
	v_add_f32_e32 v48, 0, v48
	v_cvt_pk_bf16_f32 v138, v60, v61
	v_cvt_pk_bf16_f32 v139, v62, v63
	s_add_i32 s10, s10, 0xc000
	v_add_f32_e32 v160, v160, v48
	v_lshl_add_u64 v[48:49], v[152:153], 0, s[46:47]
	s_add_i32 s28, s28, s10
	s_mov_b32 s13, m0
	s_mov_b32 m0, s28
	s_nop 0
	global_load_lds_dwordx4 v[48:49], off
	s_mov_b32 m0, s13
	s_waitcnt lgkmcnt(14)
	v_mfma_f32_32x32x16_bf16 v[0:15], v[148:151], v[80:83], v[0:15]
	v_exp_f32_e32 v96, v96
	v_exp_f32_e32 v97, v97
	v_exp_f32_e32 v98, v98
	v_exp_f32_e32 v99, v99
	s_waitcnt lgkmcnt(12)
	v_mfma_f32_32x32x16_bf16 v[16:31], v[148:151], v[84:87], v[16:31]
	v_exp_f32_e32 v100, v100
	v_exp_f32_e32 v101, v101
	v_exp_f32_e32 v102, v102
	v_exp_f32_e32 v103, v103
	v_add_u32_e32 v60, s11, v165
	ds_read_b128 v[48:51], v60
	s_waitcnt lgkmcnt(11)
	v_mfma_f32_32x32x16_bf16 v[0:15], v[144:147], v[88:91], v[0:15]
	v_exp_f32_e32 v104, v104
	v_exp_f32_e32 v105, v105
	v_exp_f32_e32 v106, v106
	v_exp_f32_e32 v107, v107
	ds_read_b128 v[52:55], v60 offset:1024
	s_waitcnt lgkmcnt(10)
	v_mfma_f32_32x32x16_bf16 v[16:31], v[144:147], v[92:95], v[16:31]
	v_exp_f32_e32 v108, v108
	v_exp_f32_e32 v109, v109
	v_exp_f32_e32 v110, v110
	v_exp_f32_e32 v111, v111
	ds_read_b128 v[56:59], v60 offset:512
	s_waitcnt lgkmcnt(9)
	v_mfma_f32_32x32x16_bf16 v[0:15], v[140:143], v[112:115], v[0:15]
	v_exp_f32_e32 v64, v64
	v_exp_f32_e32 v65, v65
	v_exp_f32_e32 v66, v66
	v_exp_f32_e32 v67, v67
	ds_read_b128 v[60:63], v60 offset:1536
	s_waitcnt lgkmcnt(8)
	v_mfma_f32_32x32x16_bf16 v[16:31], v[140:143], v[116:119], v[16:31]
	v_exp_f32_e32 v68, v68
	v_exp_f32_e32 v69, v69
	v_exp_f32_e32 v70, v70
	v_exp_f32_e32 v71, v71
	s_waitcnt lgkmcnt(6)
	v_mfma_f32_32x32x16_bf16 v[0:15], v[136:139], v[120:123], v[0:15]
	v_exp_f32_e32 v72, v72
	v_exp_f32_e32 v73, v73
	v_exp_f32_e32 v74, v74
	v_exp_f32_e32 v75, v75
	s_waitcnt lgkmcnt(4)
	v_mfma_f32_32x32x16_bf16 v[16:31], v[136:139], v[124:127], v[16:31]
	v_exp_f32_e32 v76, v76
	v_exp_f32_e32 v77, v77
	v_exp_f32_e32 v78, v78
	v_exp_f32_e32 v79, v79
	s_waitcnt vmcnt(2) lgkmcnt(0)
	s_barrier
; #define WAIT_BAR(N) asm volatile("s_waitcnt vmcnt(" #N ") lgkmcnt(0)\n\ts_barrier":::"memory")
;   #define RESC() do{ if(resc){ asm volatile("s_waitcnt lgkmcnt(0)":::"memory"); \
;       _Pragma("unroll") for(int d_=0;d_<2;++d_) _Pragma("unroll") for(int r=0;r<16;++r)o[d_][r]*=wsf[crow(r,hi)]; } }while(0)
;   #define ROT() do{sl_prev=sl_cur;sl_cur=sl_next;sl_next=(sl_next==(NSLOT-1)*SLOTB)?0:sl_next+SLOTB;}while(0)
;   #define ENDW(tt) do{ if((tt)+3<NT){WAIT_BAR(3);} else if((tt)+2<NT){WAIT_BAR(2);} else {WAIT_BAR(0);} }while(0)
; #define WAIT_BAR(N) asm volatile("s_waitcnt vmcnt(" #N ") lgkmcnt(0)\n\ts_barrier":::"memory")
;   #define RESC() do{ if(resc){ asm volatile("s_waitcnt lgkmcnt(0)":::"memory"); \
;       _Pragma("unroll") for(int d_=0;d_<4;++d_) _Pragma("unroll") for(int r=0;r<16;++r)o[d_][r]*=wsf[crow(r,hi)]; } }while(0)
;   #define ROT() do{sl_prev=sl_cur;sl_cur=sl_next;sl_next=(sl_next==(NSLOT-1)*SLOTB)?0:sl_next+SLOTB;}while(0)
;   #define ENDW(tt) do{ if((tt)+3<NT){WAIT_BAR(5);} else if((tt)+2<NT){WAIT_BAR(4);} else {WAIT_BAR(0);} }while(0)
; #define WAIT_BAR(N) asm volatile("s_waitcnt vmcnt(" #N ") lgkmcnt(0)\n\ts_barrier":::"memory")
;   #define RESC() do{ if(resc){ asm volatile("s_waitcnt lgkmcnt(0)":::"memory"); \
;       _Pragma("unroll") for(int d_=0;d_<2;++d_) _Pragma("unroll") for(int r=0;r<16;++r)o[d_][r]*=wsf[crow(r,hi)]; } }while(0)
;   #define ROT() do{sl_prev=sl_cur;sl_cur=sl_next;sl_next=(sl_next==(NSLOT-1)*SLOTB)?0:sl_next+SLOTB;}while(0)
;   #define ENDW(tt) do{ if((tt)+3<NT){WAIT_BAR(3);} else if((tt)+2<NT){WAIT_BAR(2);} else {WAIT_BAR(0);} }while(0)
; template<int THRL,bool FIXED> __device__ __forceinline__ void attn_unit(int qb,const bf16*Qp,const unsigned char*__restrict__ K8h,const bf16*__restrict__ Vh,bf16*Op,int PO,char*shm){
;     ...
;   int t=1;
;     ...
;   for(;t+5<NT;t+=2){
;     STEP(pB0,pB1,pA0,pA1,t,true,true,true);     WAIT_BAR(3); RESC(); ROT();
;     STEP(pA0,pA1,pB0,pB1,t+1,true,true,true);   WAIT_BAR(3); RESC(); ROT();
;   }
;     ...
;   for(;t+1<NT;t+=2){
;     STEP(pB0,pB1,pA0,pA1,t,(t+3<NT),(t+2<NT),(t+1<NT));       ENDW(t);   RESC(); ROT();
;     STEP(pA0,pA1,pB0,pB1,t+1,(t+4<NT),(t+3<NT),(t+2<NT));     ENDW(t+1); RESC(); ROT();
	s_add_i32 s13, s11, 0x2000
	s_cmpk_lg_i32 s11, 0x4000
	s_cselect_b32 s11, s13, 0
	ds_read_b64_tr_b16 v[112:113], v166 offset:32768
	ds_read_b64_tr_b16 v[114:115], v166 offset:33280
	v_add_f32_e32 v80, v96, v97
	v_add_f32_e32 v80, v98, v80
	v_add_f32_e32 v80, v99, v80
	v_add_f32_e32 v80, v100, v80
	v_add_f32_e32 v116, v101, v80
	v_cvt_pk_bf16_f32 v148, v96, v97
	v_cvt_pk_bf16_f32 v149, v98, v99
	s_waitcnt lgkmcnt(4)
	v_mfma_scale_f32_32x32x64_f8f6f4 v[80:95], v[48:55], v[128:135], v[32:47], v242, v241 op_sel_hi:[0,0,0]
	ds_read_b64_tr_b16 v[96:97], v166 offset:36864
	ds_read_b64_tr_b16 v[98:99], v166 offset:37376
	v_add_f32_e32 v48, v102, v116
	v_add_f32_e32 v48, v103, v48
	v_add_f32_e32 v48, v104, v48
	v_add_f32_e32 v116, v105, v48
	s_waitcnt lgkmcnt(4)
	v_mfma_scale_f32_32x32x64_f8f6f4 v[48:63], v[56:63], v[128:135], v[32:47], v242, v241 op_sel_hi:[0,0,0]
	v_cvt_pk_bf16_f32 v150, v100, v101
	v_cvt_pk_bf16_f32 v151, v102, v103
	ds_read_b64_tr_b16 v[100:101], v166 offset:33792
	ds_read_b64_tr_b16 v[102:103], v166 offset:34304
	v_add_f32_e32 v116, v106, v116
	v_add_f32_e32 v116, v107, v116
	v_add_f32_e32 v116, v108, v116
	v_add_f32_e32 v120, v109, v116
	v_cvt_pk_bf16_f32 v144, v104, v105
	v_cvt_pk_bf16_f32 v145, v106, v107
	ds_read_b64_tr_b16 v[116:117], v166 offset:37888
	ds_read_b64_tr_b16 v[118:119], v166 offset:38400
	v_add_f32_e32 v104, v110, v120
	v_add_f32_e32 v104, v111, v104
	v_add_f32_e32 v104, v64, v104
	v_add_f32_e32 v104, v65, v104
	v_cvt_pk_bf16_f32 v146, v108, v109
	v_cvt_pk_bf16_f32 v147, v110, v111
	ds_read_b64_tr_b16 v[120:121], v166 offset:34816
	ds_read_b64_tr_b16 v[122:123], v166 offset:35328
	v_add_f32_e32 v104, v66, v104
	v_add_f32_e32 v104, v67, v104
	v_add_f32_e32 v104, v68, v104
	v_add_f32_e32 v104, v69, v104
	v_cvt_pk_bf16_f32 v140, v64, v65
	v_cvt_pk_bf16_f32 v141, v66, v67
	ds_read_b64_tr_b16 v[124:125], v166 offset:38912
	ds_read_b64_tr_b16 v[126:127], v166 offset:39424
	v_add_f32_e32 v64, v70, v104
	v_add_f32_e32 v64, v71, v64
	v_add_f32_e32 v64, v72, v64
	v_add_f32_e32 v64, v73, v64
	v_cvt_pk_bf16_f32 v142, v68, v69
	v_cvt_pk_bf16_f32 v143, v70, v71
	ds_read_b64_tr_b16 v[152:153], v166 offset:35840
	ds_read_b64_tr_b16 v[154:155], v166 offset:36352
	v_add_f32_e32 v64, v74, v64
	v_add_f32_e32 v64, v75, v64
	v_add_f32_e32 v64, v76, v64
	v_add_f32_e32 v64, v77, v64
	v_cvt_pk_bf16_f32 v136, v72, v73
	v_cvt_pk_bf16_f32 v137, v74, v75
	ds_read_b64_tr_b16 v[72:73], v166 offset:39936
	ds_read_b64_tr_b16 v[74:75], v166 offset:40448
	v_add_f32_e32 v64, v78, v64
	v_add_f32_e32 v64, v79, v64
	v_add_f32_e32 v64, 0, v64
	v_cvt_pk_bf16_f32 v138, v76, v77
	v_cvt_pk_bf16_f32 v139, v78, v79
	s_nop 0
	v_add_f32_e32 v104, v160, v64
	s_waitcnt lgkmcnt(14)
	v_mfma_f32_32x32x16_bf16 v[0:15], v[148:151], v[112:115], v[0:15]
	v_exp_f32_e32 v80, v80
	v_exp_f32_e32 v81, v81
	v_exp_f32_e32 v82, v82
	v_exp_f32_e32 v83, v83
	s_waitcnt lgkmcnt(12)
	v_mfma_f32_32x32x16_bf16 v[16:31], v[148:151], v[96:99], v[16:31]
	v_exp_f32_e32 v84, v84
	v_exp_f32_e32 v85, v85
	v_exp_f32_e32 v86, v86
	v_exp_f32_e32 v87, v87
	v_add_u32_e32 v76, s11, v165
	ds_read_b128 v[64:67], v76
	s_waitcnt lgkmcnt(11)
	v_mfma_f32_32x32x16_bf16 v[0:15], v[144:147], v[100:103], v[0:15]
	v_exp_f32_e32 v88, v88
	v_exp_f32_e32 v89, v89
	v_exp_f32_e32 v90, v90
	v_exp_f32_e32 v91, v91
	ds_read_b128 v[68:71], v76 offset:1024
	s_waitcnt lgkmcnt(10)
	v_mfma_f32_32x32x16_bf16 v[16:31], v[144:147], v[116:119], v[16:31]
	v_exp_f32_e32 v92, v92
	v_exp_f32_e32 v93, v93
	v_exp_f32_e32 v94, v94
	v_exp_f32_e32 v95, v95
	ds_read_b128 v[106:109], v76 offset:512
	s_waitcnt lgkmcnt(9)
	v_mfma_f32_32x32x16_bf16 v[0:15], v[140:143], v[120:123], v[0:15]
	v_exp_f32_e32 v48, v48
	v_exp_f32_e32 v49, v49
	v_exp_f32_e32 v50, v50
	v_exp_f32_e32 v51, v51
	ds_read_b128 v[110:113], v76 offset:1536
	s_waitcnt lgkmcnt(8)
	v_mfma_f32_32x32x16_bf16 v[16:31], v[140:143], v[124:127], v[16:31]
	v_exp_f32_e32 v52, v52
	v_exp_f32_e32 v53, v53
	v_exp_f32_e32 v54, v54
	v_exp_f32_e32 v55, v55
	s_waitcnt lgkmcnt(6)
	v_mfma_f32_32x32x16_bf16 v[0:15], v[136:139], v[152:155], v[0:15]
	v_exp_f32_e32 v56, v56
	v_exp_f32_e32 v57, v57
	v_exp_f32_e32 v58, v58
	v_exp_f32_e32 v59, v59
	s_waitcnt lgkmcnt(4)
	v_mfma_f32_32x32x16_bf16 v[16:31], v[136:139], v[72:75], v[16:31]
	v_exp_f32_e32 v60, v60
	v_exp_f32_e32 v61, v61
	v_exp_f32_e32 v62, v62
	v_exp_f32_e32 v63, v63
	s_waitcnt vmcnt(0) lgkmcnt(0)
	s_barrier
; #define SBAR() __builtin_amdgcn_sched_barrier(0)
; #define WAIT_BAR(N) asm volatile("s_waitcnt vmcnt(" #N ") lgkmcnt(0)\n\ts_barrier":::"memory")
;   #define RESC() do{ if(resc){ asm volatile("s_waitcnt lgkmcnt(0)":::"memory"); \
;       _Pragma("unroll") for(int d_=0;d_<2;++d_) _Pragma("unroll") for(int r=0;r<16;++r)o[d_][r]*=wsf[crow(r,hi)]; } }while(0)
;   #define PKW(P,B) cvtpk_s(P[B],P[B+1])
; #define SBAR() __builtin_amdgcn_sched_barrier(0)
; __device__ __forceinline__ void pv(f32x16*o,int vb,bf16x8 pa0,bf16x8 pa1,bf16x8 pa2,bf16x8 pa3){
;   #pragma unroll
;   for(int d0=0;d0<2;++d0){s16x4 lo[4],hi[4];
;     #pragma unroll
;     for(int ks=0;ks<4;++ks){
;       asm volatile("ds_read_b64_tr_b16 %0,%1 offset:%c2":"=&v"(lo[ks]):"v"(vb),"i"(d0*4096+ks*1024):"memory");
;       asm volatile("ds_read_b64_tr_b16 %0,%1 offset:%c2":"=&v"(hi[ks]):"v"(vb),"i"(d0*4096+ks*1024+512):"memory");}
;     asm volatile("s_waitcnt lgkmcnt(0)":::"memory");SBAR();
;     ...
;     o[d0]=__builtin_amdgcn_mfma_f32_32x32x16_bf16(pa0,PK(0),o[d0],0,0,0);
;     o[d0]=__builtin_amdgcn_mfma_f32_32x32x16_bf16(pa1,PK(1),o[d0],0,0,0);
;     o[d0]=__builtin_amdgcn_mfma_f32_32x32x16_bf16(pa2,PK(2),o[d0],0,0,0);
;     o[d0]=__builtin_amdgcn_mfma_f32_32x32x16_bf16(pa3,PK(3),o[d0],0,0,0);
;     ...
;   }
; }
; template<int THRL,bool FIXED> __device__ __forceinline__ void attn_unit(int qb,const bf16*Qp,const unsigned char*__restrict__ K8h,const bf16*__restrict__ Vh,bf16*Op,int PO,char*shm){
;     ...
;   int t=1;
;     ...
;   for(;t+5<NT;t+=2){
;     STEP(pB0,pB1,pA0,pA1,t,true,true,true);     WAIT_BAR(3); RESC(); ROT();
;     STEP(pA0,pA1,pB0,pB1,t+1,true,true,true);   WAIT_BAR(3); RESC(); ROT();
;   }
;     ...
;   for(;t+1<NT;t+=2){
;     STEP(pB0,pB1,pA0,pA1,t,(t+3<NT),(t+2<NT),(t+1<NT));       ENDW(t);   RESC(); ROT();
;     STEP(pA0,pA1,pB0,pB1,t+1,(t+4<NT),(t+3<NT),(t+2<NT));     ENDW(t+1); RESC(); ROT();
;   }
;   STEP(pB0,pB1,pA0,pA1,NT-1,false,false,false); RESC();
;   { float sacc=pB0[0]+pB0[1]; _Pragma("unroll") for(int r=2;r<16;++r)sacc+=pB0[r]; _Pragma("unroll") for(int r=0;r<16;++r)sacc+=pB1[r]; l_reg+=sacc;
;     pw0=(u32x4){PKW(pB0,0),PKW(pB0,2),PKW(pB0,4),PKW(pB0,6)};pw1=(u32x4){PKW(pB0,8),PKW(pB0,10),PKW(pB0,12),PKW(pB0,14)};pw2=(u32x4){PKW(pB1,0),PKW(pB1,2),PKW(pB1,4),PKW(pB1,6)};pw3=(u32x4){PKW(pB1,8),PKW(pB1,10),PKW(pB1,12),PKW(pB1,14)};
;     SBAR(); pv(o,vb0+VSL(NT-1),PAF(0),PAF(1),PAF(2),PAF(3)); }
	ds_read_b64_tr_b16 v[96:97], v166 offset:40960
	ds_read_b64_tr_b16 v[98:99], v166 offset:41472
	v_add_f32_e32 v72, v80, v81
	v_add_f32_e32 v72, v82, v72
	v_add_f32_e32 v72, v83, v72
	v_add_f32_e32 v72, v84, v72
	v_add_f32_e32 v100, v85, v72
	v_cvt_pk_bf16_f32 v148, v80, v81
	v_cvt_pk_bf16_f32 v149, v82, v83
	s_waitcnt lgkmcnt(4)
	v_mfma_scale_f32_32x32x64_f8f6f4 v[64:79], v[64:71], v[128:135], v[32:47], v242, v241 op_sel_hi:[0,0,0]
	ds_read_b64_tr_b16 v[80:81], v166 offset:45056
	ds_read_b64_tr_b16 v[82:83], v166 offset:45568
	s_waitcnt lgkmcnt(4)
	v_mfma_scale_f32_32x32x64_f8f6f4 v[32:47], v[106:113], v[128:135], v[32:47], v242, v241 op_sel_hi:[0,0,0]
	v_add_f32_e32 v100, v86, v100
	v_add_f32_e32 v100, v87, v100
	v_add_f32_e32 v100, v88, v100
	v_add_f32_e32 v105, v89, v100
	v_cvt_pk_bf16_f32 v150, v84, v85
	v_cvt_pk_bf16_f32 v151, v86, v87
	ds_read_b64_tr_b16 v[100:101], v166 offset:41984
	ds_read_b64_tr_b16 v[102:103], v166 offset:42496
	v_add_f32_e32 v84, v90, v105
	v_add_f32_e32 v84, v91, v84
	v_add_f32_e32 v84, v92, v84
	v_add_f32_e32 v105, v93, v84
	v_cvt_pk_bf16_f32 v144, v88, v89
	v_cvt_pk_bf16_f32 v145, v90, v91
	ds_read_b64_tr_b16 v[84:85], v166 offset:46080
	ds_read_b64_tr_b16 v[86:87], v166 offset:46592
	v_add_f32_e32 v88, v94, v105
	v_add_f32_e32 v88, v95, v88
	v_add_f32_e32 v88, v48, v88
	v_add_f32_e32 v105, v49, v88
	v_cvt_pk_bf16_f32 v146, v92, v93
	v_cvt_pk_bf16_f32 v147, v94, v95
	ds_read_b64_tr_b16 v[88:89], v166 offset:43008
	ds_read_b64_tr_b16 v[90:91], v166 offset:43520
	v_add_f32_e32 v92, v50, v105
	v_add_f32_e32 v92, v51, v92
	v_add_f32_e32 v92, v52, v92
	v_add_f32_e32 v92, v53, v92
	v_cvt_pk_bf16_f32 v140, v48, v49
	v_cvt_pk_bf16_f32 v141, v50, v51
	ds_read_b64_tr_b16 v[48:49], v166 offset:47104
	ds_read_b64_tr_b16 v[50:51], v166 offset:47616
	v_add_f32_e32 v92, v54, v92
	v_add_f32_e32 v92, v55, v92
	v_add_f32_e32 v92, v56, v92
	v_add_f32_e32 v105, v57, v92
	v_cvt_pk_bf16_f32 v142, v52, v53
	v_cvt_pk_bf16_f32 v143, v54, v55
	ds_read_b64_tr_b16 v[92:93], v166 offset:44032
	ds_read_b64_tr_b16 v[94:95], v166 offset:44544
	v_add_f32_e32 v52, v58, v105
	v_add_f32_e32 v52, v59, v52
	v_add_f32_e32 v52, v60, v52
	v_add_f32_e32 v105, v61, v52
	v_cvt_pk_bf16_f32 v136, v56, v57
	v_cvt_pk_bf16_f32 v137, v58, v59
	ds_read_b64_tr_b16 v[52:53], v166 offset:48128
	ds_read_b64_tr_b16 v[54:55], v166 offset:48640
	v_add_f32_e32 v56, v62, v105
	v_add_f32_e32 v56, v63, v56
	v_add_f32_e32 v56, 0, v56
	v_cvt_pk_bf16_f32 v138, v60, v61
	v_cvt_pk_bf16_f32 v139, v62, v63
	v_exp_f32_e32 v64, v64
	v_exp_f32_e32 v65, v65
	v_exp_f32_e32 v66, v66
	v_exp_f32_e32 v67, v67
	s_nop 0
	v_exp_f32_e32 v68, v68
	v_exp_f32_e32 v69, v69
	v_exp_f32_e32 v70, v70
	v_exp_f32_e32 v71, v71
	s_nop 0
	v_exp_f32_e32 v72, v72
	v_exp_f32_e32 v73, v73
	v_exp_f32_e32 v74, v74
	v_exp_f32_e32 v75, v75
	s_nop 0
	v_exp_f32_e32 v76, v76
	v_exp_f32_e32 v77, v77
	v_exp_f32_e32 v78, v78
	v_exp_f32_e32 v79, v79
	v_exp_f32_e32 v32, v32
	v_exp_f32_e32 v33, v33
	v_exp_f32_e32 v34, v34
	v_exp_f32_e32 v35, v35
	s_nop 0
	v_exp_f32_e32 v36, v36
	v_exp_f32_e32 v37, v37
	v_exp_f32_e32 v38, v38
	v_exp_f32_e32 v39, v39
	s_nop 0
	v_exp_f32_e32 v40, v40
	v_exp_f32_e32 v41, v41
	v_exp_f32_e32 v42, v42
	v_exp_f32_e32 v43, v43
	s_nop 0
	v_exp_f32_e32 v44, v44
	v_exp_f32_e32 v45, v45
	v_exp_f32_e32 v46, v46
	v_exp_f32_e32 v47, v47
	s_waitcnt lgkmcnt(14)
	v_mfma_f32_32x32x16_bf16 v[0:15], v[148:151], v[96:99], v[0:15]
	v_add_f32_e32 v57, v64, v65
	v_add_f32_e32 v57, v66, v57
	v_add_f32_e32 v57, v67, v57
	v_add_f32_e32 v57, v68, v57
	v_add_f32_e32 v57, v69, v57
	v_add_f32_e32 v57, v70, v57
	v_add_f32_e32 v57, v71, v57
	s_waitcnt lgkmcnt(12)
	v_mfma_f32_32x32x16_bf16 v[16:31], v[148:151], v[80:83], v[16:31]
	v_add_f32_e32 v57, v72, v57
	v_add_f32_e32 v57, v73, v57
	v_add_f32_e32 v57, v74, v57
	v_add_f32_e32 v57, v75, v57
	v_add_f32_e32 v57, v76, v57
	v_add_f32_e32 v57, v77, v57
	v_add_f32_e32 v57, v78, v57
	s_waitcnt lgkmcnt(10)
	v_mfma_f32_32x32x16_bf16 v[0:15], v[144:147], v[100:103], v[0:15]
	v_add_f32_e32 v57, v79, v57
	v_add_f32_e32 v57, v32, v57
	v_add_f32_e32 v57, v33, v57
	v_add_f32_e32 v57, v34, v57
	v_add_f32_e32 v57, v35, v57
	v_add_f32_e32 v57, v36, v57
	v_add_f32_e32 v57, v37, v57
	s_waitcnt lgkmcnt(8)
	v_mfma_f32_32x32x16_bf16 v[16:31], v[144:147], v[84:87], v[16:31]
	v_add_f32_e32 v57, v38, v57
	v_add_f32_e32 v57, v39, v57
	v_add_f32_e32 v57, v40, v57
	v_add_f32_e32 v57, v41, v57
	v_add_f32_e32 v57, v42, v57
	v_add_f32_e32 v57, v43, v57
	v_add_f32_e32 v57, v44, v57
	s_waitcnt lgkmcnt(6)
	v_mfma_f32_32x32x16_bf16 v[0:15], v[140:143], v[88:91], v[0:15]
	v_add_f32_e32 v57, v45, v57
	v_add_f32_e32 v57, v46, v57
	v_add_f32_e32 v57, v47, v57
	v_add_f32_e32 v56, v104, v56
	v_add_f32_e32 v56, v56, v57
	v_cvt_pk_bf16_f32 v32, v32, v33
	v_cvt_pk_bf16_f32 v58, v64, v65
	s_waitcnt lgkmcnt(4)
	v_mfma_f32_32x32x16_bf16 v[16:31], v[140:143], v[48:51], v[16:31]
	v_cvt_pk_bf16_f32 v59, v66, v67
	v_cvt_pk_bf16_f32 v60, v68, v69
	v_cvt_pk_bf16_f32 v61, v70, v71
	v_cvt_pk_bf16_f32 v62, v72, v73
	v_cvt_pk_bf16_f32 v63, v74, v75
	v_cvt_pk_bf16_f32 v64, v76, v77
	v_cvt_pk_bf16_f32 v65, v78, v79
	s_waitcnt lgkmcnt(2)
	v_mfma_f32_32x32x16_bf16 v[0:15], v[136:139], v[92:95], v[0:15]
	v_cvt_pk_bf16_f32 v33, v34, v35
	v_cvt_pk_bf16_f32 v34, v36, v37
	v_cvt_pk_bf16_f32 v35, v38, v39
	v_cvt_pk_bf16_f32 v36, v40, v41
	v_cvt_pk_bf16_f32 v37, v42, v43
	v_cvt_pk_bf16_f32 v38, v44, v45
	v_cvt_pk_bf16_f32 v39, v46, v47
	s_waitcnt lgkmcnt(0)
	v_mfma_f32_32x32x16_bf16 v[16:31], v[136:139], v[52:55], v[16:31]
	v_add_u32_e32 v40, s10, v163
	v_add3_u32 v57, v40, v162, v164
	ds_read_b64_tr_b16 v[40:41],v57 offset:0
	ds_read_b64_tr_b16 v[42:43],v57 offset:512
	ds_read_b64_tr_b16 v[44:45],v57 offset:1024
	ds_read_b64_tr_b16 v[46:47],v57 offset:1536
	ds_read_b64_tr_b16 v[48:49],v57 offset:2048
	ds_read_b64_tr_b16 v[50:51],v57 offset:2560
	ds_read_b64_tr_b16 v[52:53],v57 offset:3072
	ds_read_b64_tr_b16 v[54:55],v57 offset:3584
	s_waitcnt lgkmcnt(0)
	s_nop 0
	v_mfma_f32_32x32x16_bf16 v[0:15], v[58:61], v[40:43], v[0:15]
	ds_read_b64_tr_b16 v[40:41],v57 offset:4096
	ds_read_b64_tr_b16 v[42:43],v57 offset:4608
	v_mfma_f32_32x32x16_bf16 v[0:15], v[62:65], v[44:47], v[0:15]
	ds_read_b64_tr_b16 v[44:45],v57 offset:5120
	ds_read_b64_tr_b16 v[46:47],v57 offset:5632
	v_mfma_f32_32x32x16_bf16 v[0:15], v[32:35], v[48:51], v[0:15]
	ds_read_b64_tr_b16 v[48:49],v57 offset:6144
	ds_read_b64_tr_b16 v[50:51],v57 offset:6656
	v_mfma_f32_32x32x16_bf16 v[0:15], v[36:39], v[52:55], v[0:15]
	ds_read_b64_tr_b16 v[52:53],v57 offset:7168
	ds_read_b64_tr_b16 v[54:55],v57 offset:7680
	s_waitcnt lgkmcnt(0)
	v_mfma_f32_32x32x16_bf16 v[16:31], v[58:61], v[40:43], v[16:31]
	v_cmp_gt_u32_e32 vcc, 32, v156
	v_mfma_f32_32x32x16_bf16 v[16:31], v[62:65], v[44:47], v[16:31]
	v_mfma_f32_32x32x16_bf16 v[16:31], v[32:35], v[48:51], v[16:31]
	v_mov_b32_e32 v32, v56
	s_nop 1
	v_permlane32_swap_b32_e32 v56, v32
	v_mfma_f32_32x32x16_bf16 v[16:31], v[36:39], v[52:55], v[16:31]
	s_and_saveexec_b64 s[10:11], vcc
	s_cbranch_execz .LBB0_541
; template<int THRL,bool FIXED> __device__ __forceinline__ void attn_unit(int qb,const bf16*Qp,const unsigned char*__restrict__ K8h,const bf16*__restrict__ Vh,bf16*Op,int PO,char*shm){
;     ...
;   {auto rr=__builtin_amdgcn_permlane32_swap(__float_as_uint(l_reg),__float_as_uint(l_reg),false,false);l_reg=__uint_as_float(rr[0])+__uint_as_float(rr[1]);}
;   if(hi==0)wsf[32+r32]=l_reg;asm volatile("s_waitcnt lgkmcnt(0)":::"memory");
	v_lshl_add_u32 v33, v158, 2, s12
	v_add_f32_e32 v32, v56, v32
	ds_write_b32 v33, v32 offset:57472
	s_branch .LBB0_541

; #define WAIT_BAR(N) asm volatile("s_waitcnt vmcnt(" #N ") lgkmcnt(0)\n\ts_barrier":::"memory")
;   #define DMA_K(t,slot) glds16(ksrc+(long)(t)*KVBLK*PQ,(unsigned)__builtin_amdgcn_readfirstlane(kdst+(slot)))
;   #define DMA_V(t,slot) glds16(vsrc+(long)(t)*KVBLK*PQ,(unsigned)__builtin_amdgcn_readfirstlane(vdst+(slot)))
;   #define CMASK(P0,P1,t) do{}while(0)
;   #define CMASK(P0,P1,t) do{}while(0)
;   #define CMASK(P0,P1,t) do{}while(0)
; #define WAIT_BAR(N) asm volatile("s_waitcnt vmcnt(" #N ") lgkmcnt(0)\n\ts_barrier":::"memory")
;   #define CMASK(P0,P1,t) do{}while(0)
; template<int THRL,bool FIXED> __device__ __forceinline__ void attn_unit(int qb,const bf16*Qp,const bf16*__restrict__ Kh,const bf16*__restrict__ Vh,bf16*Op,int PO,char*shm,bool comb,float lam,const float*gsub,float gscale){
;   int tid_=threadIdx.x; asm volatile("":"+v"(tid_)); const int tid=tid_,lane=tid&63,r32=lane&31,hi=lane>>5; const int wid=__builtin_amdgcn_readfirstlane(tid>>6);
;   const int q0=qb*QB;
;   const bf16*Qw=Qp+(long)(q0+wid*QBLK)*PQ;
;   const unsigned lds0=(unsigned)(uintptr_t)shm;
;   float*wsf=(float*)(shm+LDS_WS)+wid*64;
;   const bf16*ksrc=Kh+(long)lane*PQ+wid*8;
;   const bf16*vsrc=Vh+(long)(16*(wid&3)+(lane>>2))*PQ+(wid>>2)*32+(lane&3)*8;
;   const unsigned kdst=lds0+LDS_K+wid*1024, vdst=lds0+LDS_V+wid*1024;
;     ...
;   const int vb0=(int)(lds0+LDS_V)+((lane>>4)&1)*32+(lane&3)*8+(4*hi+((lane&15)>>2))*64;
;   const char*Kbase=shm+LDS_K; bf16x8 kf[8];
;   const lds_cptr shm3=(lds_cptr)shm; const lds_cptr kp0=shm3+LDS_K+hi*1024+r32*16; const lds_cptr vp0=shm3+LDS_V+((lane>>4)&1)*32+(lane&3)*8+(4*hi+((lane&15)>>2))*64;
;   constexpr int NT=SEQ/KVBLK;
;   DMA_K(0,0);DMA_V(0,VSL(0));DMA_K(1,SLOTB);DMA_V(1,VSL(1));
;   bf16x8 qr[4];
;   #pragma unroll
;   for(int d0=0;d0<4;++d0)qr[d0]=*reinterpret_cast<const bf16x8*>(&Qw[(long)r32*PQ+d0*16+hi*8]);
;   float mhat=0.f,l_reg=0.f;f32x16 o[4];o[0]=f32x16{};o[1]=f32x16{};o[2]=f32x16{};o[3]=f32x16{};f32x16 negm=f32x16{};asm volatile("":"+v"(negm));
;     ...
;   bool resc=false;
;     ...
;   f32x16 pA0,pA1,pB0,pB1;
;   int sl_prev=0,sl_cur=0,sl_next=SLOTB;
;     ...
;   DMA_K(2,2*SLOTB);
;   WAIT_BAR(3);
;   qkt(pA0,pA1,Kbase,qr,negm,r32,hi);asm volatile("s_nop 15\n\ts_nop 7":"+v"(pA0),"+v"(pA1));CMASK(pA0,pA1,0);
;   START(pA0,pA1);
;   _Pragma("unroll") for(int r=0;r<16;++r)pA1[r]=__builtin_amdgcn_exp2f(pA1[r]);
;   WAIT_BAR(0);
.LBB0_549:
	s_xor_b64 s[10:11], s[12:13], -1
	s_xor_b64 s[12:13], s[66:67], -1
	s_lshl_b64 s[66:67], s[64:65], 1
	v_mov_b32_e32 v46, v238
	s_add_u32 s22, s4, s66
	s_addc_u32 s23, s5, s67
	v_readfirstlane_b32 s28, v46
	s_ashr_i32 s77, s28, 6
	s_lshl_b32 s3, s77, 5
	v_and_b32_e32 v234, 63, v46
	s_add_i32 s64, s3, s74
	s_ashr_i32 s65, s64, 31
	s_mul_i32 s29, s64, 0x1200
	v_mul_u32_u24_e32 v0, 0x900, v234
	s_mul_hi_i32 s3, s64, 0x1200
	s_add_u32 s50, s22, s29
	v_lshlrev_b32_e32 v160, 1, v0
	s_addc_u32 s51, s23, s3
	v_lshl_add_u64 v[0:1], s[22:23], 0, v[160:161]
	s_lshl_b32 s22, s77, 3
	s_ashr_i32 s23, s22, 31
	s_lshl_b64 s[68:69], s[22:23], 1
	v_lshl_add_u64 v[34:35], v[0:1], 0, s[68:69]
	s_lshl_b32 s3, s77, 4
	v_bfe_u32 v0, v46, 2, 4
	v_and_or_b32 v0, s3, 48, v0
	s_ashr_i32 s3, s28, 3
	s_and_b32 s22, s3, 0xffffffe0
	v_mul_u32_u24_e32 v0, 0x900, v0
	s_ashr_i32 s23, s22, 31
	v_lshlrev_b32_e32 v32, 1, v0
	v_mov_b32_e32 v33, v161
	s_lshl_b64 s[70:71], s[22:23], 1
	v_lshlrev_b32_e32 v2, 3, v46
	s_lshl_b32 s3, s77, 10
	v_lshl_add_u64 v[0:1], s[4:5], 0, v[32:33]
	v_and_b32_e32 v236, 24, v2
	s_cmp_lg_u32 0, -1
	v_lshl_add_u64 v[0:1], v[0:1], 0, s[70:71]
	v_lshlrev_b32_e32 v2, 1, v236
	v_mov_b32_e32 v3, v161
	s_cselect_b32 s22, 0, 0
	v_lshl_add_u64 v[208:209], v[34:35], 0, s[92:93]
	v_lshl_add_u64 v[36:37], v[0:1], 0, v[2:3]
	s_add_i32 s29, s3, s22
	s_mov_b32 s22, m0
	s_mov_b32 m0, s29
	s_nop 0
	global_load_lds_dwordx4 v[208:209], off
	s_mov_b32 m0, s22
	v_lshl_add_u64 v[206:207], v[36:37], 0, s[0:1]
	s_add_i32 s35, s29, 0x6000
	s_mov_b32 s22, m0
	s_mov_b32 m0, s35
	s_nop 0
	global_load_lds_dwordx4 v[206:207], off
	s_mov_b32 m0, s22
	v_lshl_add_u64 v[0:1], v[36:37], 0, s[52:53]
	s_add_i32 s22, s29, 0x8000
	s_mov_b32 s23, m0
	s_mov_b32 m0, s22
	s_nop 0
	global_load_lds_dwordx4 v[0:1], off
	s_mov_b32 m0, s23
	v_lshl_add_u64 v[0:1], v[34:35], 0, s[94:95]
	s_add_i32 s22, s29, 0x2000
	s_mov_b32 s23, m0
	s_mov_b32 m0, s22
	s_nop 0
	global_load_lds_dwordx4 v[0:1], off
	s_mov_b32 m0, s23
	v_lshl_add_u64 v[0:1], v[36:37], 0, s[16:17]
	v_and_b32_e32 v232, 31, v46
	s_add_i32 s22, s29, 0xa000
	s_mov_b32 s23, m0
	s_mov_b32 m0, s22
	s_nop 0
	global_load_lds_dwordx4 v[0:1], off
	s_mov_b32 m0, s23
	v_lshl_add_u64 v[0:1], v[36:37], 0, s[90:91]
	s_add_i32 s22, s29, 0xc000
	s_mov_b32 s23, m0
	s_mov_b32 m0, s22
	s_nop 0
	global_load_lds_dwordx4 v[0:1], off
	s_mov_b32 m0, s23
	v_mul_u32_u24_e32 v0, 0x900, v232
	v_bfe_u32 v233, v46, 5, 1
	v_lshlrev_b32_e32 v0, 1, v0
	v_lshl_or_b32 v0, v233, 4, v0
	global_load_dwordx4 v[190:193], v0, s[50:51] offset:1536
	global_load_dwordx4 v[186:189], v0, s[50:51] offset:1568
	global_load_dwordx4 v[174:177], v0, s[50:51] offset:1600
	global_load_dwordx4 v[162:165], v0, s[50:51] offset:1632
	v_lshlrev_b32_e32 v235, 10, v233
	v_lshlrev_b32_e32 v1, 4, v232
	v_add3_u32 v215, 0, v235, v1
	v_mov_b32_e32 v0, v161
	v_mov_b32_e32 v1, v161
	v_mov_b32_e32 v2, v161
	v_mov_b32_e32 v4, v161
	v_mov_b32_e32 v5, v161
	v_mov_b32_e32 v6, v161
	v_mov_b32_e32 v7, v161
	v_mov_b32_e32 v8, v161
	v_mov_b32_e32 v9, v161
	v_mov_b32_e32 v10, v161
	v_mov_b32_e32 v11, v161
	v_mov_b32_e32 v12, v161
	v_mov_b32_e32 v13, v161
	v_mov_b32_e32 v14, v161
	v_mov_b32_e32 v15, v161
	v_lshl_add_u64 v[16:17], v[34:35], 0, s[88:89]
	s_add_i32 s22, s29, 0x4000
	s_mov_b32 s23, m0
	s_mov_b32 m0, s22
	s_nop 0
	global_load_lds_dwordx4 v[16:17], off
	s_mov_b32 m0, s23
	s_waitcnt vmcnt(3) lgkmcnt(0)
	s_barrier
	ds_read_b128 v[38:41], v215
	ds_read_b128 v[42:45], v215 offset:512
	v_mov_b32_e32 v216, 0
	s_mov_b32 s44, -1
	s_movk_i32 s50, 0x2000
	s_movk_i32 s34, 0x4000
	v_bfe_u32 v230, v46, 4, 2
	v_and_b32_e32 v231, 15, v46
	s_mov_b32 s51, 0x10000
	v_mov_b32_e32 v47, v216
	v_mov_b32_e32 v48, 0
	v_mov_b32_e32 v49, v216
	s_waitcnt vmcnt(3) lgkmcnt(1)
	v_mfma_f32_32x32x16_bf16 v[16:31], v[38:41], v[190:193], v[0:15]
	v_mov_b32_e32 v50, v216
	v_mov_b32_e32 v51, v216
	v_mov_b32_e32 v52, v216
	v_mov_b32_e32 v53, v216
	v_mov_b32_e32 v54, v216
	v_mov_b32_e32 v55, v216
	v_mov_b32_e32 v56, v216
	s_waitcnt lgkmcnt(0)
	v_mfma_f32_32x32x16_bf16 v[0:15], v[42:45], v[190:193], v[0:15]
	ds_read_b128 v[38:41], v215 offset:2048
	ds_read_b128 v[42:45], v215 offset:2560
	v_mov_b32_e32 v57, v216
	v_mov_b32_e32 v58, v216
	v_mov_b32_e32 v59, v216
	v_mov_b32_e32 v60, v216
	v_mov_b32_e32 v61, v216
	v_mov_b32_e32 v62, v216
	s_waitcnt vmcnt(2) lgkmcnt(1)
	v_mfma_f32_32x32x16_bf16 v[16:31], v[38:41], v[186:189], v[16:31]
	v_mov_b32_e32 v63, v216
	s_waitcnt lgkmcnt(0)
	v_mfma_f32_32x32x16_bf16 v[0:15], v[42:45], v[186:189], v[0:15]
	ds_read_b128 v[38:41], v215 offset:4096
	ds_read_b128 v[42:45], v215 offset:4608
	s_waitcnt vmcnt(1) lgkmcnt(1)
	v_mfma_f32_32x32x16_bf16 v[16:31], v[38:41], v[174:177], v[16:31]
	ds_read_b128 v[38:41], v215 offset:6144
	s_waitcnt lgkmcnt(1)
	v_mfma_f32_32x32x16_bf16 v[0:15], v[42:45], v[174:177], v[0:15]
	ds_read_b128 v[42:45], v215 offset:6656
	s_waitcnt vmcnt(0) lgkmcnt(1)
	v_mfma_f32_32x32x16_bf16 v[16:31], v[38:41], v[162:165], v[16:31]
	v_lshlrev_b32_e32 v38, 1, v46
	v_lshlrev_b32_e32 v39, 4, v46
	v_and_b32_e32 v237, 32, v38
	v_and_b32_e32 v38, 0xc0, v39
	v_add_u32_e32 v39, 0, v237
	v_lshl_or_b32 v240, v233, 8, v38
	v_add3_u32 v214, v39, v236, v240
	s_waitcnt lgkmcnt(0)
	v_mfma_f32_32x32x16_bf16 v[0:15], v[42:45], v[162:165], v[0:15]
	s_nop 15
	s_nop 7
	v_mov_b32_e32 v38, v216
	v_max3_f32 v40, v16, v17, v0
	v_max3_f32 v41, v18, v19, v1
	v_mov_b32_e32 v39, v216
	v_max3_f32 v40, v40, v2, v3
	v_max3_f32 v41, v41, v22, v23
	v_mov_b32_e32 v42, v216
	v_max3_f32 v40, v40, v20, v21
	v_max3_f32 v41, v41, v6, v7
	v_mov_b32_e32 v43, v216
	v_max3_f32 v40, v40, v4, v5
	v_max3_f32 v41, v41, v26, v27
	v_mov_b32_e32 v44, v216
	v_max3_f32 v40, v40, v24, v25
	v_max3_f32 v41, v41, v10, v11
	v_mov_b32_e32 v45, v216
	v_max3_f32 v40, v40, v8, v9
	v_max3_f32 v41, v41, v30, v31
	s_nop 0
	v_max3_f32 v40, v40, v28, v29
	v_max3_f32 v41, v41, v14, v15
	s_nop 0
	v_max3_f32 v40, v40, v12, v13
	s_nop 0
	v_max_f32_e32 v40, v40, v41
	s_nop 0
	v_mov_b32_e32 v41, v40
	s_nop 1
	v_permlane32_swap_b32_e32 v40, v41
	v_max_f32_e32 v40, v40, v41
	s_nop 0
	v_add_f32_e32 v41, v161, v40
	v_sub_f32_e32 v0, v0, v40
	v_sub_f32_e32 v1, v1, v40
	v_sub_f32_e32 v16, v16, v40
	v_sub_f32_e32 v17, v17, v40
	v_sub_f32_e32 v18, v18, v40
	s_nop 0
	v_xor_b32_e32 v64, 0x80000000, v41
	v_mov_b32_e32 v65, v64
	v_mov_b32_e32 v66, v64
	v_mov_b32_e32 v67, v64
	v_mov_b32_e32 v68, v64
	v_mov_b32_e32 v69, v64
	v_mov_b32_e32 v70, v64
	v_mov_b32_e32 v71, v64
	v_mov_b32_e32 v72, v64
	v_mov_b32_e32 v73, v64
	v_mov_b32_e32 v74, v64
	v_mov_b32_e32 v75, v64
	v_mov_b32_e32 v76, v64
	v_mov_b32_e32 v77, v64
	v_mov_b32_e32 v78, v64
	v_mov_b32_e32 v79, v64
	s_waitcnt vmcnt(0) lgkmcnt(0)
	s_barrier
; #define WAIT_BAR(N) asm volatile("s_waitcnt vmcnt(" #N ") lgkmcnt(0)\n\ts_barrier":::"memory")
;   #define DMA_K(t,slot) glds16(ksrc+(long)(t)*KVBLK*PQ,(unsigned)__builtin_amdgcn_readfirstlane(kdst+(slot)))
;   #define DMA_V(t,slot) glds16(vsrc+(long)(t)*KVBLK*PQ,(unsigned)__builtin_amdgcn_readfirstlane(vdst+(slot)))
;   #define START(P0,P1) do{ const float rm=rowmax(P0,P1); resc=false; \
;     { const float dl=rm; mhat=fadd_s(mhat,dl); \
;       _Pragma("unroll") for(int r=0;r<16;++r){P0[r]=fsub_s(P0[r],dl);P1[r]=fsub_s(P1[r],dl);} \
;       _Pragma("unroll") for(int r=0;r<16;++r)negm[r]=-mhat; asm volatile("":"+v"(negm)); } \
;     _Pragma("unroll") for(int r=0;r<16;++r)P0[r]=__builtin_amdgcn_exp2f(P0[r]); }while(0)
;   #define ROT() do{sl_prev=sl_cur;sl_cur=sl_next;sl_next=(sl_next==(NSLOT-1)*SLOTB)?0:sl_next+SLOTB;}while(0)
; #define WAIT_BAR(N) asm volatile("s_waitcnt vmcnt(" #N ") lgkmcnt(0)\n\ts_barrier":::"memory")
;   #define DMA_K(t,slot) glds16(ksrc+(long)(t)*KVBLK*PQ,(unsigned)__builtin_amdgcn_readfirstlane(kdst+(slot)))
;   #define DMA_V(t,slot) do{ glds16(vsrc+(long)(t)*KVBLK*PQ,(unsigned)__builtin_amdgcn_readfirstlane(vdst+(slot))); glds16(vsrc+(long)(t)*KVBLK*PQ+64,(unsigned)__builtin_amdgcn_readfirstlane(vdst+(slot)+8192)); }while(0)
;   #define START(P0,P1) do{ const float rm=rowmax(P0,P1); resc=false; \
;     { const float dl=rm; mhat=fadd_s(mhat,dl); \
;       _Pragma("unroll") for(int r=0;r<16;++r){P0[r]=fsub_s(P0[r],dl);P1[r]=fsub_s(P1[r],dl);} \
;       _Pragma("unroll") for(int r=0;r<16;++r)negm[r]=-mhat; asm volatile("":"+v"(negm)); } \
;     _Pragma("unroll") for(int r=0;r<16;++r)P0[r]=__builtin_amdgcn_exp2f(P0[r]); }while(0)
;   #define ROT() do{sl_prev=sl_cur;sl_cur=sl_next;sl_next=(sl_next==(NSLOT-1)*SLOTB)?0:sl_next+SLOTB;}while(0)
; #define WAIT_BAR(N) asm volatile("s_waitcnt vmcnt(" #N ") lgkmcnt(0)\n\ts_barrier":::"memory")
; template<int THRL,bool FIXED> __device__ __forceinline__ void attn_unit(int qb,const bf16*Qp,const bf16*__restrict__ Kh,const bf16*__restrict__ Vh,bf16*Op,int PO,char*shm,bool comb,float lam,const float*gsub,float gscale){
;     ...
;   START(pA0,pA1);
;   _Pragma("unroll") for(int r=0;r<16;++r)pA1[r]=__builtin_amdgcn_exp2f(pA1[r]);
;   WAIT_BAR(0);
;   DMA_K(3,0);DMA_V(2,VSL(2));
;   ROT();
;   kload8(kf,kp0+sl_cur);
;   WAIT_BAR(3);
;   s16x4 vlo[8],vhi[8]; u32x4 pw0,pw1,pw2,pw3;
	v_exp_f32_e32 v80, v0
	v_exp_f32_e32 v81, v1
	v_lshl_add_u64 v[0:1], v[34:35], 0, s[14:15]
	s_mov_b32 s22, m0
	s_mov_b32 m0, s29
	s_nop 0
	global_load_lds_dwordx4 v[0:1], off
	s_mov_b32 m0, s22
	v_lshl_add_u64 v[0:1], v[36:37], 0, s[54:55]
	s_add_i32 s22, s29, 0xe000
	s_mov_b32 s23, m0
	s_mov_b32 m0, s22
	s_nop 0
	global_load_lds_dwordx4 v[0:1], off
	s_mov_b32 m0, s23
	v_lshl_add_u64 v[0:1], v[36:37], 0, s[18:19]
	s_add_i32 s22, s29, 0x10000
	s_mov_b32 s23, m0
	s_mov_b32 m0, s22
	s_nop 0
	global_load_lds_dwordx4 v[0:1], off
	s_mov_b32 m0, s23
	ds_read_b128 v[112:115], v215 offset:8192
	ds_read_b128 v[202:205], v215 offset:8704
	ds_read_b128 v[198:201], v215 offset:10240
	ds_read_b128 v[194:197], v215 offset:10752
	ds_read_b128 v[156:159], v215 offset:12288
	ds_read_b128 v[152:155], v215 offset:12800
	ds_read_b128 v[148:151], v215 offset:14336
	ds_read_b128 v[144:147], v215 offset:14848
	s_add_u32 s22, s66, s68
	v_sub_f32_e32 v2, v2, v40
	v_sub_f32_e32 v19, v19, v40
	v_sub_f32_e32 v3, v3, v40
	v_sub_f32_e32 v20, v20, v40
	v_sub_f32_e32 v4, v4, v40
	v_sub_f32_e32 v21, v21, v40
	v_sub_f32_e32 v5, v5, v40
	v_sub_f32_e32 v22, v22, v40
	v_sub_f32_e32 v6, v6, v40
	v_sub_f32_e32 v23, v23, v40
	v_sub_f32_e32 v7, v7, v40
	v_sub_f32_e32 v24, v24, v40
	v_sub_f32_e32 v8, v8, v40
	v_sub_f32_e32 v25, v25, v40
	v_sub_f32_e32 v9, v9, v40
	v_sub_f32_e32 v26, v26, v40
	v_sub_f32_e32 v10, v10, v40
	v_sub_f32_e32 v27, v27, v40
	v_sub_f32_e32 v11, v11, v40
	v_sub_f32_e32 v28, v28, v40
	v_sub_f32_e32 v12, v12, v40
	v_sub_f32_e32 v29, v29, v40
	v_sub_f32_e32 v13, v13, v40
	v_sub_f32_e32 v30, v30, v40
	v_sub_f32_e32 v14, v14, v40
	v_sub_f32_e32 v31, v31, v40
	v_sub_f32_e32 v15, v15, v40
	v_exp_f32_e32 v96, v16
	v_exp_f32_e32 v97, v17
	v_exp_f32_e32 v98, v18
	v_exp_f32_e32 v99, v19
	v_exp_f32_e32 v100, v20
	v_exp_f32_e32 v101, v21
	v_exp_f32_e32 v102, v22
	v_exp_f32_e32 v103, v23
	v_exp_f32_e32 v104, v24
	v_exp_f32_e32 v105, v25
	v_exp_f32_e32 v106, v26
	v_exp_f32_e32 v107, v27
	v_exp_f32_e32 v108, v28
	v_exp_f32_e32 v109, v29
	v_exp_f32_e32 v110, v30
	v_exp_f32_e32 v111, v31
	v_exp_f32_e32 v82, v2
	v_exp_f32_e32 v83, v3
	v_exp_f32_e32 v84, v4
	v_exp_f32_e32 v85, v5
	v_exp_f32_e32 v86, v6
	v_exp_f32_e32 v87, v7
	v_exp_f32_e32 v88, v8
	v_exp_f32_e32 v89, v9
	v_exp_f32_e32 v90, v10
	v_exp_f32_e32 v91, v11
	v_exp_f32_e32 v92, v12
	v_exp_f32_e32 v93, v13
	v_exp_f32_e32 v94, v14
	v_exp_f32_e32 v95, v15
	v_and_b32_e32 v0, 3, v46
	s_addc_u32 s23, s67, s69
	s_waitcnt vmcnt(3) lgkmcnt(0)
	s_barrier
	v_lshl_or_b32 v0, v0, 4, s70
	v_mov_b32_e32 v1, s71
	s_add_u32 s22, s75, s22
	v_lshl_add_u64 v[0:1], v[0:1], 0, v[32:33]
	s_addc_u32 s23, s76, s23
	v_lshl_add_u64 v[210:211], s[8:9], 0, v[0:1]
	v_lshl_add_u64 v[212:213], s[22:23], 0, v[160:161]
	v_mov_b32_e32 v0, 0
	v_mov_b32_e32 v1, v216
	v_mov_b32_e32 v2, v216
	v_mov_b32_e32 v3, v216
	v_mov_b32_e32 v4, v216
	v_mov_b32_e32 v5, v216
	v_mov_b32_e32 v6, v216
	v_mov_b32_e32 v7, v216
	v_mov_b32_e32 v8, v216
	v_mov_b32_e32 v9, v216
	v_mov_b32_e32 v10, v216
	v_mov_b32_e32 v11, v216
	v_mov_b32_e32 v12, v216
	v_mov_b32_e32 v13, v216
	v_mov_b32_e32 v14, v216
	v_mov_b32_e32 v15, v216
	v_mov_b32_e32 v16, 0
	v_mov_b32_e32 v17, v216
	v_mov_b32_e32 v18, v216
	v_mov_b32_e32 v19, v216
	v_mov_b32_e32 v20, v216
	v_mov_b32_e32 v21, v216
	v_mov_b32_e32 v22, v216
	v_mov_b32_e32 v23, v216
	v_mov_b32_e32 v24, v216
	v_mov_b32_e32 v25, v216
	v_mov_b32_e32 v26, v216
	v_mov_b32_e32 v27, v216
	v_mov_b32_e32 v28, v216
	v_mov_b32_e32 v29, v216
	v_mov_b32_e32 v30, v216
	v_mov_b32_e32 v31, v216
	v_mov_b32_e32 v32, 0
	v_mov_b32_e32 v33, v216
	v_mov_b32_e32 v34, v216
	v_mov_b32_e32 v35, v216
	v_mov_b32_e32 v36, v216
	v_mov_b32_e32 v37, v216
	v_mov_b32_e32 v40, v216
	v_mov_b32_e32 v41, v216
	v_mov_b32_e32 v46, v216
	s_mov_b32 s101, m0
.LBB0_550:
	s_and_b32 s22, s51, 0xc000
	v_add_u32_e32 v160, s22, v214
	v_add_u32_e32 v217, 0x8000, v160
	ds_read_b64_tr_b16 v[222:223], v160 offset:24576
	ds_read_b64_tr_b16 v[224:225], v160 offset:25088
	s_add_i32 s23, s51, 0xffff4000
	v_add_f32_e32 v116, v96, v97
	v_add_f32_e32 v116, v98, v116
	v_add_f32_e32 v116, v99, v116
	v_add_f32_e32 v116, v100, v116
	v_add_f32_e32 v116, v101, v116
	v_cvt_pk_bf16_f32 v182, v96, v97
	v_cvt_pk_bf16_f32 v183, v98, v99
	v_mfma_f32_32x32x16_bf16 v[128:143], v[112:115], v[190:193], v[64:79]
	ds_read_b64_tr_b16 v[96:97], v160 offset:28672
	ds_read_b64_tr_b16 v[98:99], v160 offset:29184
	v_add_f32_e32 v112, v102, v116
	v_add_f32_e32 v112, v103, v112
	v_add_f32_e32 v112, v104, v112
	v_add_f32_e32 v166, v105, v112
	v_mfma_f32_32x32x16_bf16 v[112:127], v[202:205], v[190:193], v[64:79]
	v_cvt_pk_bf16_f32 v184, v100, v101
	v_cvt_pk_bf16_f32 v185, v102, v103
	ds_read_b64_tr_b16 v[100:101], v160 offset:25600
	ds_read_b64_tr_b16 v[102:103], v160 offset:26112
	v_add_f32_e32 v166, v106, v166
	v_add_f32_e32 v166, v107, v166
	v_add_f32_e32 v166, v108, v166
	v_add_f32_e32 v166, v109, v166
	v_cvt_pk_bf16_f32 v178, v104, v105
	v_cvt_pk_bf16_f32 v179, v106, v107
	v_mfma_f32_32x32x16_bf16 v[128:143], v[198:201], v[186:189], v[128:143]
	ds_read_b64_tr_b16 v[104:105], v160 offset:29696
	ds_read_b64_tr_b16 v[106:107], v160 offset:30208
	v_mfma_f32_32x32x16_bf16 v[112:127], v[194:197], v[186:189], v[112:127]
	v_add_f32_e32 v166, v110, v166
	v_add_f32_e32 v166, v111, v166
	v_add_f32_e32 v166, v80, v166
	v_add_f32_e32 v166, v81, v166
	v_cvt_pk_bf16_f32 v180, v108, v109
	v_cvt_pk_bf16_f32 v181, v110, v111
	ds_read_b64_tr_b16 v[108:109], v160 offset:26624
	ds_read_b64_tr_b16 v[110:111], v160 offset:27136
	v_mfma_f32_32x32x16_bf16 v[128:143], v[156:159], v[174:177], v[128:143]
	v_add_f32_e32 v156, v82, v166
	v_add_f32_e32 v156, v83, v156
	v_add_f32_e32 v156, v84, v156
	v_add_f32_e32 v156, v85, v156
	v_cvt_pk_bf16_f32 v170, v80, v81
	v_cvt_pk_bf16_f32 v171, v82, v83
	ds_read_b64_tr_b16 v[80:81], v160 offset:30720
	ds_read_b64_tr_b16 v[82:83], v160 offset:31232
	v_mfma_f32_32x32x16_bf16 v[112:127], v[152:155], v[174:177], v[112:127]
	v_add_f32_e32 v152, v86, v156
	v_add_f32_e32 v152, v87, v152
	v_add_f32_e32 v152, v88, v152
	v_add_f32_e32 v152, v89, v152
	v_cvt_pk_bf16_f32 v172, v84, v85
	v_cvt_pk_bf16_f32 v173, v86, v87
	ds_read_b64_tr_b16 v[84:85], v160 offset:27648
	ds_read_b64_tr_b16 v[86:87], v160 offset:28160
	v_mfma_f32_32x32x16_bf16 v[128:143], v[148:151], v[162:165], v[128:143]
	v_add_f32_e32 v148, v90, v152
	v_add_f32_e32 v148, v91, v148
	v_add_f32_e32 v148, v92, v148
	v_add_f32_e32 v148, v93, v148
	v_cvt_pk_bf16_f32 v166, v88, v89
	v_cvt_pk_bf16_f32 v167, v90, v91
	ds_read_b64_tr_b16 v[88:89], v160 offset:31744
	ds_read_b64_tr_b16 v[90:91], v160 offset:32256
	v_mfma_f32_32x32x16_bf16 v[112:127], v[144:147], v[162:165], v[112:127]
	v_add_f32_e32 v144, v94, v148
	v_add_f32_e32 v144, v95, v144
	v_add_f32_e32 v160, 0, v144
	v_cvt_pk_bf16_f32 v168, v92, v93
	v_cvt_pk_bf16_f32 v169, v94, v95
	s_add_i32 s50, s50, s29
	s_mov_b32 m0, s50
	v_lshl_add_u64 v[92:93], v[212:213], 0, s[20:21]
	global_load_lds_dwordx4 v[92:93], off
	s_add_i32 s50, s51, 0xffffc000
	s_and_b32 s50, s50, 0xc000
	s_add_i32 s50, s50, s35
	s_mov_b32 m0, s50
	v_lshl_add_u64 v[92:93], v[210:211], 0, s[36:37]
	global_load_lds_dwordx4 v[92:93], off
	s_addk_i32 s50, 0x2000
	s_mov_b32 m0, s50
	v_lshl_add_u64 v[92:93], v[210:211], 0, s[26:27]
	global_load_lds_dwordx4 v[92:93], off
	s_waitcnt lgkmcnt(8)
	v_mfma_f32_32x32x16_bf16 v[0:15], v[182:185], v[222:225], v[0:15]
	v_exp_f32_e32 v128, v128
	v_exp_f32_e32 v129, v129
	ds_read_b64_tr_b16 v[92:93], v217
	ds_read_b64_tr_b16 v[94:95], v217 offset:512
	v_mfma_f32_32x32x16_bf16 v[16:31], v[182:185], v[96:99], v[16:31]
	v_exp_f32_e32 v130, v130
	v_exp_f32_e32 v131, v131
	ds_read_b64_tr_b16 v[96:97], v217 offset:4096
	ds_read_b64_tr_b16 v[98:99], v217 offset:4608
	v_mfma_f32_32x32x16_bf16 v[0:15], v[178:181], v[100:103], v[0:15]
	v_exp_f32_e32 v132, v132
	v_exp_f32_e32 v133, v133
	ds_read_b64_tr_b16 v[100:101], v217 offset:1024
	ds_read_b64_tr_b16 v[102:103], v217 offset:1536
	v_mfma_f32_32x32x16_bf16 v[16:31], v[178:181], v[104:107], v[16:31]
	v_exp_f32_e32 v134, v134
	v_exp_f32_e32 v135, v135
	ds_read_b64_tr_b16 v[104:105], v217 offset:5120
	ds_read_b64_tr_b16 v[106:107], v217 offset:5632
	s_waitcnt lgkmcnt(8)
	v_mfma_f32_32x32x16_bf16 v[0:15], v[170:173], v[108:111], v[0:15]
	v_exp_f32_e32 v136, v136
	v_exp_f32_e32 v137, v137
	ds_read_b64_tr_b16 v[108:109], v217 offset:2048
	ds_read_b64_tr_b16 v[110:111], v217 offset:2560
	v_mfma_f32_32x32x16_bf16 v[16:31], v[170:173], v[80:83], v[16:31]
	v_exp_f32_e32 v138, v138
	v_exp_f32_e32 v139, v139
	ds_read_b64_tr_b16 v[80:81], v217 offset:6144
	ds_read_b64_tr_b16 v[82:83], v217 offset:6656
	v_mfma_f32_32x32x16_bf16 v[0:15], v[166:169], v[84:87], v[0:15]
	v_exp_f32_e32 v140, v140
	v_exp_f32_e32 v141, v141
	ds_read_b64_tr_b16 v[84:85], v217 offset:3072
	ds_read_b64_tr_b16 v[86:87], v217 offset:3584
	v_mfma_f32_32x32x16_bf16 v[16:31], v[166:169], v[88:91], v[16:31]
	v_exp_f32_e32 v142, v142
	v_exp_f32_e32 v143, v143
	ds_read_b64_tr_b16 v[88:89], v217 offset:7168
	ds_read_b64_tr_b16 v[90:91], v217 offset:7680
	s_waitcnt lgkmcnt(8)
	v_mfma_f32_32x32x16_bf16 v[32:47], v[182:185], v[92:95], v[32:47]
	v_exp_f32_e32 v112, v112
	v_exp_f32_e32 v113, v113
	v_mfma_f32_32x32x16_bf16 v[48:63], v[182:185], v[96:99], v[48:63]
	v_exp_f32_e32 v114, v114
	v_exp_f32_e32 v115, v115
	v_add_u32_e32 v96, s34, v215
	ds_read_b128 v[92:95], v96
	ds_read_b128 v[144:147], v96 offset:512
	v_mfma_f32_32x32x16_bf16 v[32:47], v[178:181], v[100:103], v[32:47]
	v_exp_f32_e32 v116, v116
	v_exp_f32_e32 v117, v117
	ds_read_b128 v[148:151], v96 offset:2048
	ds_read_b128 v[152:155], v96 offset:2560
	v_mfma_f32_32x32x16_bf16 v[48:63], v[178:181], v[104:107], v[48:63]
	v_exp_f32_e32 v118, v118
	v_exp_f32_e32 v119, v119
	ds_read_b128 v[156:159], v96 offset:4096
	ds_read_b128 v[194:197], v96 offset:4608
	s_waitcnt lgkmcnt(6)
	v_mfma_f32_32x32x16_bf16 v[32:47], v[170:173], v[108:111], v[32:47]
	v_exp_f32_e32 v120, v120
	v_exp_f32_e32 v121, v121
	ds_read_b128 v[198:201], v96 offset:6144
	ds_read_b128 v[202:205], v96 offset:6656
	v_mfma_f32_32x32x16_bf16 v[48:63], v[170:173], v[80:83], v[48:63]
	v_exp_f32_e32 v122, v122
	v_exp_f32_e32 v123, v123
	v_mfma_f32_32x32x16_bf16 v[32:47], v[166:169], v[84:87], v[32:47]
	v_exp_f32_e32 v124, v124
	v_exp_f32_e32 v125, v125
	v_mfma_f32_32x32x16_bf16 v[48:63], v[166:169], v[88:91], v[48:63]
	v_exp_f32_e32 v126, v126
	v_exp_f32_e32 v127, v127
	s_waitcnt vmcnt(5) lgkmcnt(0)
	s_barrier
; #define WAIT_BAR(N) asm volatile("s_waitcnt vmcnt(" #N ") lgkmcnt(0)\n\ts_barrier":::"memory")
;   #define RESC() do{ if(resc){ asm volatile("s_waitcnt lgkmcnt(0)":::"memory"); \
;       _Pragma("unroll") for(int d_=0;d_<2;++d_) _Pragma("unroll") for(int r=0;r<16;++r)o[d_][r]*=wsf[crow(r,hi)]; } }while(0)
;   #define ROT() do{sl_prev=sl_cur;sl_cur=sl_next;sl_next=(sl_next==(NSLOT-1)*SLOTB)?0:sl_next+SLOTB;}while(0)
; #define WAIT_BAR(N) asm volatile("s_waitcnt vmcnt(" #N ") lgkmcnt(0)\n\ts_barrier":::"memory")
;   #define RESC() do{ if(resc){ asm volatile("s_waitcnt lgkmcnt(0)":::"memory"); \
;       _Pragma("unroll") for(int d_=0;d_<4;++d_) _Pragma("unroll") for(int r=0;r<16;++r)o[d_][r]*=wsf[crow(r,hi)]; } }while(0)
;   #define ROT() do{sl_prev=sl_cur;sl_cur=sl_next;sl_next=(sl_next==(NSLOT-1)*SLOTB)?0:sl_next+SLOTB;}while(0)
; #define WAIT_BAR(N) asm volatile("s_waitcnt vmcnt(" #N ") lgkmcnt(0)\n\ts_barrier":::"memory")
;   #define RESC() do{ if(resc){ asm volatile("s_waitcnt lgkmcnt(0)":::"memory"); \
;       _Pragma("unroll") for(int d_=0;d_<2;++d_) _Pragma("unroll") for(int r=0;r<16;++r)o[d_][r]*=wsf[crow(r,hi)]; } }while(0)
;   #define ROT() do{sl_prev=sl_cur;sl_cur=sl_next;sl_next=(sl_next==(NSLOT-1)*SLOTB)?0:sl_next+SLOTB;}while(0)
; template<int THRL,bool FIXED> __device__ __forceinline__ void attn_unit(int qb,const bf16*Qp,const bf16*__restrict__ Kh,const bf16*__restrict__ Vh,bf16*Op,int PO,char*shm,bool comb,float lam,const float*gsub,float gscale){
;     ...
;   int t=1;
;     ...
;   for(;t+5<NT;t+=2){
;     STEP(pB0,pB1,pA0,pA1,t,true,true,true);     WAIT_BAR(5); RESC(); ROT();
;     STEP(pA0,pA1,pB0,pB1,t+1,true,true,true);   WAIT_BAR(5); RESC(); ROT();
	s_add_i32 s50, s34, 0x2000
	s_cmpk_lg_i32 s34, 0x4000
	s_cselect_b32 s50, s50, 0
	s_and_b32 s23, s23, 0xc000
	v_add_u32_e32 v217, s23, v214
	v_add_u32_e32 v243, 0x8000, v217
	ds_read_b64_tr_b16 v[222:223], v217 offset:24576
	ds_read_b64_tr_b16 v[224:225], v217 offset:25088
	v_mfma_f32_32x32x16_bf16 v[96:111], v[92:95], v[190:193], v[64:79]
	v_add_f32_e32 v80, v128, v129
	v_add_f32_e32 v80, v130, v80
	v_add_f32_e32 v80, v131, v80
	v_add_f32_e32 v80, v132, v80
	v_add_f32_e32 v80, v133, v80
	v_cvt_pk_bf16_f32 v182, v128, v129
	v_cvt_pk_bf16_f32 v183, v130, v131
	ds_read_b64_tr_b16 v[128:129], v217 offset:28672
	ds_read_b64_tr_b16 v[130:131], v217 offset:29184
	v_add_f32_e32 v80, v134, v80
	v_add_f32_e32 v80, v135, v80
	v_add_f32_e32 v80, v136, v80
	v_add_f32_e32 v166, v137, v80
	v_mfma_f32_32x32x16_bf16 v[80:95], v[144:147], v[190:193], v[64:79]
	v_cvt_pk_bf16_f32 v184, v132, v133
	v_cvt_pk_bf16_f32 v185, v134, v135
	ds_read_b64_tr_b16 v[132:133], v217 offset:25600
	ds_read_b64_tr_b16 v[134:135], v217 offset:26112
	v_mfma_f32_32x32x16_bf16 v[96:111], v[148:151], v[186:189], v[96:111]
	v_add_f32_e32 v144, v138, v166
	v_add_f32_e32 v144, v139, v144
	v_add_f32_e32 v144, v140, v144
	v_add_f32_e32 v144, v141, v144
	v_cvt_pk_bf16_f32 v178, v136, v137
	v_cvt_pk_bf16_f32 v179, v138, v139
	ds_read_b64_tr_b16 v[136:137], v217 offset:29696
	ds_read_b64_tr_b16 v[138:139], v217 offset:30208
	v_mfma_f32_32x32x16_bf16 v[80:95], v[152:155], v[186:189], v[80:95]
	v_add_f32_e32 v144, v142, v144
	v_add_f32_e32 v144, v143, v144
	v_add_f32_e32 v144, v112, v144
	v_add_f32_e32 v144, v113, v144
	v_cvt_pk_bf16_f32 v180, v140, v141
	v_cvt_pk_bf16_f32 v181, v142, v143
	ds_read_b64_tr_b16 v[140:141], v217 offset:26624
	ds_read_b64_tr_b16 v[142:143], v217 offset:27136
	v_mfma_f32_32x32x16_bf16 v[96:111], v[156:159], v[174:177], v[96:111]
	v_add_f32_e32 v144, v114, v144
	v_add_f32_e32 v144, v115, v144
	v_add_f32_e32 v144, v116, v144
	v_add_f32_e32 v144, v117, v144
	v_cvt_pk_bf16_f32 v170, v112, v113
	v_cvt_pk_bf16_f32 v171, v114, v115
	ds_read_b64_tr_b16 v[112:113], v217 offset:30720
	ds_read_b64_tr_b16 v[114:115], v217 offset:31232
	v_mfma_f32_32x32x16_bf16 v[80:95], v[194:197], v[174:177], v[80:95]
	v_add_f32_e32 v144, v118, v144
	v_add_f32_e32 v144, v119, v144
	v_add_f32_e32 v144, v120, v144
	v_add_f32_e32 v144, v121, v144
	v_cvt_pk_bf16_f32 v172, v116, v117
	v_cvt_pk_bf16_f32 v173, v118, v119
	ds_read_b64_tr_b16 v[116:117], v217 offset:27648
	ds_read_b64_tr_b16 v[118:119], v217 offset:28160
	v_mfma_f32_32x32x16_bf16 v[96:111], v[198:201], v[162:165], v[96:111]
	v_add_f32_e32 v144, v122, v144
	v_add_f32_e32 v144, v123, v144
	v_add_f32_e32 v144, v124, v144
	v_add_f32_e32 v144, v125, v144
	v_cvt_pk_bf16_f32 v166, v120, v121
	v_cvt_pk_bf16_f32 v167, v122, v123
	ds_read_b64_tr_b16 v[120:121], v217 offset:31744
	ds_read_b64_tr_b16 v[122:123], v217 offset:32256
	v_mfma_f32_32x32x16_bf16 v[80:95], v[202:205], v[162:165], v[80:95]
	v_add_f32_e32 v144, v126, v144
	v_add_f32_e32 v144, v127, v144
	v_add_f32_e32 v217, 0, v144
	v_cvt_pk_bf16_f32 v168, v124, v125
	v_cvt_pk_bf16_f32 v169, v126, v127
	s_add_i32 s23, s34, s29
	s_mov_b32 m0, s23
	v_lshl_add_u64 v[124:125], v[212:213], 0, s[38:39]
	global_load_lds_dwordx4 v[124:125], off
	s_add_i32 s22, s22, s35
	s_mov_b32 m0, s22
	s_nop 0
	global_load_lds_dwordx4 v[210:211], off
	s_addk_i32 s22, 0x2000
	s_mov_b32 m0, s22
	v_lshl_add_u64 v[124:125], v[210:211], 0, s[24:25]
	global_load_lds_dwordx4 v[124:125], off
	s_waitcnt lgkmcnt(8)
	v_mfma_f32_32x32x16_bf16 v[0:15], v[182:185], v[222:225], v[0:15]
	v_exp_f32_e32 v96, v96
	v_exp_f32_e32 v97, v97
	ds_read_b64_tr_b16 v[124:125], v243
	ds_read_b64_tr_b16 v[126:127], v243 offset:512
	v_mfma_f32_32x32x16_bf16 v[16:31], v[182:185], v[128:131], v[16:31]
	v_exp_f32_e32 v98, v98
	v_exp_f32_e32 v99, v99
	ds_read_b64_tr_b16 v[128:129], v243 offset:4096
	ds_read_b64_tr_b16 v[130:131], v243 offset:4608
	v_mfma_f32_32x32x16_bf16 v[0:15], v[178:181], v[132:135], v[0:15]
	v_exp_f32_e32 v100, v100
	v_exp_f32_e32 v101, v101
	ds_read_b64_tr_b16 v[132:133], v243 offset:1024
	ds_read_b64_tr_b16 v[134:135], v243 offset:1536
	v_mfma_f32_32x32x16_bf16 v[16:31], v[178:181], v[136:139], v[16:31]
	v_exp_f32_e32 v102, v102
	v_exp_f32_e32 v103, v103
	ds_read_b64_tr_b16 v[136:137], v243 offset:5120
	ds_read_b64_tr_b16 v[138:139], v243 offset:5632
	s_waitcnt lgkmcnt(8)
	v_mfma_f32_32x32x16_bf16 v[0:15], v[170:173], v[140:143], v[0:15]
	v_exp_f32_e32 v104, v104
	v_exp_f32_e32 v105, v105
	ds_read_b64_tr_b16 v[140:141], v243 offset:2048
	ds_read_b64_tr_b16 v[142:143], v243 offset:2560
	v_mfma_f32_32x32x16_bf16 v[16:31], v[170:173], v[112:115], v[16:31]
	v_exp_f32_e32 v106, v106
	v_exp_f32_e32 v107, v107
	ds_read_b64_tr_b16 v[222:223], v243 offset:6144
	ds_read_b64_tr_b16 v[224:225], v243 offset:6656
	v_mfma_f32_32x32x16_bf16 v[0:15], v[166:169], v[116:119], v[0:15]
	v_exp_f32_e32 v108, v108
	v_exp_f32_e32 v109, v109
	ds_read_b64_tr_b16 v[116:117], v243 offset:3072
	ds_read_b64_tr_b16 v[118:119], v243 offset:3584
	v_mfma_f32_32x32x16_bf16 v[16:31], v[166:169], v[120:123], v[16:31]
	v_exp_f32_e32 v110, v110
	v_exp_f32_e32 v111, v111
	ds_read_b64_tr_b16 v[120:121], v243 offset:7168
	ds_read_b64_tr_b16 v[122:123], v243 offset:7680
	s_waitcnt lgkmcnt(8)
	v_mfma_f32_32x32x16_bf16 v[32:47], v[182:185], v[124:127], v[32:47]
	v_exp_f32_e32 v80, v80
	v_exp_f32_e32 v81, v81
	v_mfma_f32_32x32x16_bf16 v[48:63], v[182:185], v[128:131], v[48:63]
	v_exp_f32_e32 v82, v82
	v_exp_f32_e32 v83, v83
	v_add_u32_e32 v124, s50, v215
	ds_read_b128 v[112:115], v124
	ds_read_b128 v[202:205], v124 offset:512
	v_mfma_f32_32x32x16_bf16 v[32:47], v[178:181], v[132:135], v[32:47]
	v_exp_f32_e32 v84, v84
	v_exp_f32_e32 v85, v85
	ds_read_b128 v[198:201], v124 offset:2048
	ds_read_b128 v[194:197], v124 offset:2560
	v_mfma_f32_32x32x16_bf16 v[48:63], v[178:181], v[136:139], v[48:63]
	v_exp_f32_e32 v86, v86
	v_exp_f32_e32 v87, v87
	ds_read_b128 v[156:159], v124 offset:4096
	ds_read_b128 v[152:155], v124 offset:4608
	s_waitcnt lgkmcnt(6)
	v_mfma_f32_32x32x16_bf16 v[32:47], v[170:173], v[140:143], v[32:47]
	v_exp_f32_e32 v88, v88
	v_exp_f32_e32 v89, v89
	ds_read_b128 v[148:151], v124 offset:6144
	ds_read_b128 v[144:147], v124 offset:6656
	v_mfma_f32_32x32x16_bf16 v[48:63], v[170:173], v[222:225], v[48:63]
	v_exp_f32_e32 v90, v90
	v_exp_f32_e32 v91, v91
	v_mfma_f32_32x32x16_bf16 v[32:47], v[166:169], v[116:119], v[32:47]
	v_exp_f32_e32 v92, v92
	v_exp_f32_e32 v93, v93
	v_mfma_f32_32x32x16_bf16 v[48:63], v[166:169], v[120:123], v[48:63]
	v_exp_f32_e32 v94, v94
	v_exp_f32_e32 v95, v95
	s_add_i32 s22, s50, 0x2000
	s_waitcnt vmcnt(5) lgkmcnt(0)
	s_barrier
; #define WAIT_BAR(N) asm volatile("s_waitcnt vmcnt(" #N ") lgkmcnt(0)\n\ts_barrier":::"memory")
;   #define RESC() do{ if(resc){ asm volatile("s_waitcnt lgkmcnt(0)":::"memory"); \
;       _Pragma("unroll") for(int d_=0;d_<2;++d_) _Pragma("unroll") for(int r=0;r<16;++r)o[d_][r]*=wsf[crow(r,hi)]; } }while(0)
;   #define ROT() do{sl_prev=sl_cur;sl_cur=sl_next;sl_next=(sl_next==(NSLOT-1)*SLOTB)?0:sl_next+SLOTB;}while(0)
;   #define ENDW(tt) do{ if((tt)+3<NT){WAIT_BAR(3);} else if((tt)+2<NT){WAIT_BAR(2);} else {WAIT_BAR(0);} }while(0)
; #define WAIT_BAR(N) asm volatile("s_waitcnt vmcnt(" #N ") lgkmcnt(0)\n\ts_barrier":::"memory")
;   #define RESC() do{ if(resc){ asm volatile("s_waitcnt lgkmcnt(0)":::"memory"); \
;       _Pragma("unroll") for(int d_=0;d_<4;++d_) _Pragma("unroll") for(int r=0;r<16;++r)o[d_][r]*=wsf[crow(r,hi)]; } }while(0)
;   #define ROT() do{sl_prev=sl_cur;sl_cur=sl_next;sl_next=(sl_next==(NSLOT-1)*SLOTB)?0:sl_next+SLOTB;}while(0)
;   #define ENDW(tt) do{ if((tt)+3<NT){WAIT_BAR(5);} else if((tt)+2<NT){WAIT_BAR(4);} else {WAIT_BAR(0);} }while(0)
; #define WAIT_BAR(N) asm volatile("s_waitcnt vmcnt(" #N ") lgkmcnt(0)\n\ts_barrier":::"memory")
;   #define RESC() do{ if(resc){ asm volatile("s_waitcnt lgkmcnt(0)":::"memory"); \
;       _Pragma("unroll") for(int d_=0;d_<2;++d_) _Pragma("unroll") for(int r=0;r<16;++r)o[d_][r]*=wsf[crow(r,hi)]; } }while(0)
;   #define ROT() do{sl_prev=sl_cur;sl_cur=sl_next;sl_next=(sl_next==(NSLOT-1)*SLOTB)?0:sl_next+SLOTB;}while(0)
;   #define ENDW(tt) do{ if((tt)+3<NT){WAIT_BAR(3);} else if((tt)+2<NT){WAIT_BAR(2);} else {WAIT_BAR(0);} }while(0)
; template<int THRL,bool FIXED> __device__ __forceinline__ void attn_unit(int qb,const bf16*Qp,const bf16*__restrict__ Kh,const bf16*__restrict__ Vh,bf16*Op,int PO,char*shm,bool comb,float lam,const float*gsub,float gscale){
;     ...
;   int t=1;
;     ...
;   for(;t+5<NT;t+=2){
;     STEP(pB0,pB1,pA0,pA1,t,true,true,true);     WAIT_BAR(5); RESC(); ROT();
;     STEP(pA0,pA1,pB0,pB1,t+1,true,true,true);   WAIT_BAR(5); RESC(); ROT();
;   }
;     ...
;   for(;t+1<NT;t+=2){
;     STEP(pB0,pB1,pA0,pA1,t,(t+3<NT),(t+2<NT),(t+1<NT));       ENDW(t);   RESC(); ROT();
	s_cmpk_lg_i32 s50, 0x4000
	v_add_f32_e32 v116, v216, v160
	s_cselect_b32 s34, s22, 0
	s_add_i32 s44, s44, 2
	s_add_i32 s51, s51, 0x8000
	v_lshl_add_u64 v[210:211], v[210:211], 0, s[40:41]
	v_lshl_add_u64 v[212:213], v[212:213], 0, s[40:41]
	s_cmpk_gt_u32 s44, 0xf8
	v_add_f32_e32 v216, v116, v217
	s_cbranch_scc0 .LBB0_550
	s_mov_b32 m0, s101
	s_and_b32 s22, s28, 0x3fffffc0
	s_lshl_b32 s22, s22, 2
	s_add_i32 s28, s22, 0
	s_add_i32 s28, s28, 0x16000
	v_add_u32_e32 v210, 0x6000, v214
	v_add_u32_e32 v160, 0x10000, v214
	v_mov_b32_e32 v211, v160
	ds_read_b64_tr_b16 v[244:245], v214 offset:57344
	ds_read_b64_tr_b16 v[246:247], v214 offset:57856
	v_add_f32_e32 v116, v96, v97
	v_add_f32_e32 v116, v98, v116
	v_add_f32_e32 v116, v99, v116
	v_add_f32_e32 v116, v100, v116
	v_add_f32_e32 v116, v101, v116
	v_cvt_pk_bf16_f32 v182, v96, v97
	v_cvt_pk_bf16_f32 v183, v98, v99
	s_waitcnt lgkmcnt(9)
	v_mfma_f32_32x32x16_bf16 v[128:143], v[112:115], v[190:193], v[64:79]
	ds_read_b64_tr_b16 v[248:249], v214 offset:61440
	ds_read_b64_tr_b16 v[250:251], v214 offset:61952
	v_add_f32_e32 v96, v102, v116
	v_add_f32_e32 v96, v103, v96
	v_add_f32_e32 v96, v104, v96
	v_add_f32_e32 v96, v105, v96
	v_cvt_pk_bf16_f32 v184, v100, v101
	v_cvt_pk_bf16_f32 v185, v102, v103
	s_waitcnt lgkmcnt(10)
	v_mfma_f32_32x32x16_bf16 v[112:127], v[202:205], v[190:193], v[64:79]
	ds_read_b64_tr_b16 v[98:99], v214 offset:58368
	ds_read_b64_tr_b16 v[100:101], v214 offset:58880
	v_add_f32_e32 v96, v106, v96
	v_add_f32_e32 v96, v107, v96
	v_add_f32_e32 v96, v108, v96
	v_add_f32_e32 v96, v109, v96
	v_cvt_pk_bf16_f32 v178, v104, v105
	v_cvt_pk_bf16_f32 v179, v106, v107
	s_waitcnt lgkmcnt(11)
	v_mfma_f32_32x32x16_bf16 v[128:143], v[198:201], v[186:189], v[128:143]
	ds_read_b64_tr_b16 v[102:103], v214 offset:62464
	ds_read_b64_tr_b16 v[104:105], v214 offset:62976
	v_add_f32_e32 v96, v110, v96
	v_add_f32_e32 v96, v111, v96
	v_add_f32_e32 v96, v80, v96
	v_add_f32_e32 v96, v81, v96
	v_cvt_pk_bf16_f32 v180, v108, v109
	v_cvt_pk_bf16_f32 v181, v110, v111
	s_waitcnt lgkmcnt(12)
	v_mfma_f32_32x32x16_bf16 v[112:127], v[194:197], v[186:189], v[112:127]
	ds_read_b64_tr_b16 v[106:107], v214 offset:59392
	ds_read_b64_tr_b16 v[108:109], v214 offset:59904
	v_add_f32_e32 v96, v82, v96
	v_add_f32_e32 v96, v83, v96
	v_add_f32_e32 v96, v84, v96
	v_add_f32_e32 v96, v85, v96
	v_cvt_pk_bf16_f32 v170, v80, v81
	v_cvt_pk_bf16_f32 v171, v82, v83
	s_waitcnt lgkmcnt(13)
	v_mfma_f32_32x32x16_bf16 v[128:143], v[156:159], v[174:177], v[128:143]
	ds_read_b64_tr_b16 v[80:81], v214 offset:63488
	ds_read_b64_tr_b16 v[82:83], v214 offset:64000
	v_add_f32_e32 v96, v86, v96
	v_add_f32_e32 v96, v87, v96
	v_add_f32_e32 v96, v88, v96
	v_add_f32_e32 v96, v89, v96
	v_cvt_pk_bf16_f32 v172, v84, v85
	v_cvt_pk_bf16_f32 v173, v86, v87
	s_waitcnt lgkmcnt(14)
	v_mfma_f32_32x32x16_bf16 v[112:127], v[152:155], v[174:177], v[112:127]
	ds_read_b64_tr_b16 v[84:85], v214 offset:60416
	ds_read_b64_tr_b16 v[86:87], v214 offset:60928
	v_add_f32_e32 v96, v90, v96
	v_add_f32_e32 v96, v91, v96
	v_add_f32_e32 v96, v92, v96
	v_add_f32_e32 v96, v93, v96
	v_cvt_pk_bf16_f32 v166, v88, v89
	v_cvt_pk_bf16_f32 v167, v90, v91
	s_waitcnt lgkmcnt(14)
	v_mfma_f32_32x32x16_bf16 v[128:143], v[148:151], v[162:165], v[128:143]
	ds_read_b64_tr_b16 v[88:89], v214 offset:64512
	ds_read_b64_tr_b16 v[90:91], v214 offset:65024
	v_add_f32_e32 v96, v94, v96
	v_add_f32_e32 v96, v95, v96
	v_add_f32_e32 v96, 0, v96
	v_cvt_pk_bf16_f32 v168, v92, v93
	v_cvt_pk_bf16_f32 v169, v94, v95
	v_mfma_f32_32x32x16_bf16 v[112:127], v[144:147], v[162:165], v[112:127]
	s_add_i32 s22, s50, s29
	s_cmp_lg_u32 0, -1
	v_lshl_add_u64 v[92:93], v[208:209], 0, s[42:43]
	s_mov_b32 s23, m0
	s_mov_b32 m0, s22
	s_nop 0
	global_load_lds_dwordx4 v[92:93], off
	s_mov_b32 m0, s23
	s_cselect_b32 s44, 0, 0
	s_mov_b64 s[22:23], 0x4728000
	s_add_i32 s35, s44, s3
	v_lshl_add_u64 v[92:93], v[206:207], 0, s[22:23]
	s_add_i32 s22, s35, 0xa000
	s_mov_b32 s23, m0
	s_mov_b32 m0, s22
	s_nop 0
	global_load_lds_dwordx4 v[92:93], off
	s_mov_b32 m0, s23
	s_mov_b64 s[22:23], 0x4728080
	v_lshl_add_u64 v[92:93], v[206:207], 0, s[22:23]
	s_add_i32 s22, s35, 0xc000
	s_mov_b32 s23, m0
	s_mov_b32 m0, s22
	s_nop 0
	global_load_lds_dwordx4 v[92:93], off
	s_mov_b32 m0, s23
	v_add_f32_e32 v96, v216, v96
	s_waitcnt lgkmcnt(14)
	v_mfma_f32_32x32x16_bf16 v[0:15], v[182:185], v[244:247], v[0:15]
	v_exp_f32_e32 v128, v128
	v_exp_f32_e32 v129, v129
	ds_read_b64_tr_b16 v[92:93], v211
	ds_read_b64_tr_b16 v[94:95], v211 offset:512
	s_waitcnt lgkmcnt(14)
	v_mfma_f32_32x32x16_bf16 v[16:31], v[182:185], v[248:251], v[16:31]
	v_exp_f32_e32 v130, v130
	v_exp_f32_e32 v131, v131
	ds_read_b64_tr_b16 v[144:145], v211 offset:4096
	ds_read_b64_tr_b16 v[146:147], v211 offset:4608
	s_waitcnt lgkmcnt(14)
	v_mfma_f32_32x32x16_bf16 v[0:15], v[178:181], v[98:101], v[0:15]
	v_exp_f32_e32 v132, v132
	v_exp_f32_e32 v133, v133
	ds_read_b64_tr_b16 v[98:99], v211 offset:1024
	ds_read_b64_tr_b16 v[100:101], v211 offset:1536
	s_waitcnt lgkmcnt(14)
	v_mfma_f32_32x32x16_bf16 v[16:31], v[178:181], v[102:105], v[16:31]
	v_exp_f32_e32 v134, v134
	v_exp_f32_e32 v135, v135
	ds_read_b64_tr_b16 v[102:103], v211 offset:5120
	ds_read_b64_tr_b16 v[104:105], v211 offset:5632
	s_waitcnt lgkmcnt(14)
	v_mfma_f32_32x32x16_bf16 v[0:15], v[170:173], v[106:109], v[0:15]
	v_exp_f32_e32 v136, v136
	v_exp_f32_e32 v137, v137
	ds_read_b64_tr_b16 v[106:107], v211 offset:2048
	ds_read_b64_tr_b16 v[108:109], v211 offset:2560
	s_waitcnt lgkmcnt(14)
	v_mfma_f32_32x32x16_bf16 v[16:31], v[170:173], v[80:83], v[16:31]
	v_exp_f32_e32 v138, v138
	v_exp_f32_e32 v139, v139
	ds_read_b64_tr_b16 v[80:81], v211 offset:6144
	ds_read_b64_tr_b16 v[82:83], v211 offset:6656
	s_waitcnt lgkmcnt(14)
; #define WAIT_BAR(N) asm volatile("s_waitcnt vmcnt(" #N ") lgkmcnt(0)\n\ts_barrier":::"memory")
;   #define RESC() do{ if(resc){ asm volatile("s_waitcnt lgkmcnt(0)":::"memory"); \
;       _Pragma("unroll") for(int d_=0;d_<2;++d_) _Pragma("unroll") for(int r=0;r<16;++r)o[d_][r]*=wsf[crow(r,hi)]; } }while(0)
;   #define ROT() do{sl_prev=sl_cur;sl_cur=sl_next;sl_next=(sl_next==(NSLOT-1)*SLOTB)?0:sl_next+SLOTB;}while(0)
;   #define ENDW(tt) do{ if((tt)+3<NT){WAIT_BAR(3);} else if((tt)+2<NT){WAIT_BAR(2);} else {WAIT_BAR(0);} }while(0)
; #define WAIT_BAR(N) asm volatile("s_waitcnt vmcnt(" #N ") lgkmcnt(0)\n\ts_barrier":::"memory")
;   #define RESC() do{ if(resc){ asm volatile("s_waitcnt lgkmcnt(0)":::"memory"); \
;       _Pragma("unroll") for(int d_=0;d_<4;++d_) _Pragma("unroll") for(int r=0;r<16;++r)o[d_][r]*=wsf[crow(r,hi)]; } }while(0)
;   #define ROT() do{sl_prev=sl_cur;sl_cur=sl_next;sl_next=(sl_next==(NSLOT-1)*SLOTB)?0:sl_next+SLOTB;}while(0)
;   #define ENDW(tt) do{ if((tt)+3<NT){WAIT_BAR(5);} else if((tt)+2<NT){WAIT_BAR(4);} else {WAIT_BAR(0);} }while(0)
; #define WAIT_BAR(N) asm volatile("s_waitcnt vmcnt(" #N ") lgkmcnt(0)\n\ts_barrier":::"memory")
;   #define RESC() do{ if(resc){ asm volatile("s_waitcnt lgkmcnt(0)":::"memory"); \
;       _Pragma("unroll") for(int d_=0;d_<2;++d_) _Pragma("unroll") for(int r=0;r<16;++r)o[d_][r]*=wsf[crow(r,hi)]; } }while(0)
;   #define ROT() do{sl_prev=sl_cur;sl_cur=sl_next;sl_next=(sl_next==(NSLOT-1)*SLOTB)?0:sl_next+SLOTB;}while(0)
;   #define ENDW(tt) do{ if((tt)+3<NT){WAIT_BAR(3);} else if((tt)+2<NT){WAIT_BAR(2);} else {WAIT_BAR(0);} }while(0)
; template<int THRL,bool FIXED> __device__ __forceinline__ void attn_unit(int qb,const bf16*Qp,const bf16*__restrict__ Kh,const bf16*__restrict__ Vh,bf16*Op,int PO,char*shm,bool comb,float lam,const float*gsub,float gscale){
;     ...
;   int t=1;
;     ...
;   for(;t+5<NT;t+=2){
;     STEP(pB0,pB1,pA0,pA1,t,true,true,true);     WAIT_BAR(5); RESC(); ROT();
;     STEP(pA0,pA1,pB0,pB1,t+1,true,true,true);   WAIT_BAR(5); RESC(); ROT();
;   }
;     ...
;   for(;t+1<NT;t+=2){
;     STEP(pB0,pB1,pA0,pA1,t,(t+3<NT),(t+2<NT),(t+1<NT));       ENDW(t);   RESC(); ROT();
;     STEP(pA0,pA1,pB0,pB1,t+1,(t+4<NT),(t+3<NT),(t+2<NT));     ENDW(t+1); RESC(); ROT();
	v_mfma_f32_32x32x16_bf16 v[0:15], v[166:169], v[84:87], v[0:15]
	v_exp_f32_e32 v140, v140
	v_exp_f32_e32 v141, v141
	ds_read_b64_tr_b16 v[84:85], v211 offset:3072
	ds_read_b64_tr_b16 v[86:87], v211 offset:3584
	s_waitcnt lgkmcnt(14)
	v_mfma_f32_32x32x16_bf16 v[16:31], v[166:169], v[88:91], v[16:31]
	v_exp_f32_e32 v142, v142
	v_exp_f32_e32 v143, v143
	ds_read_b64_tr_b16 v[88:89], v211 offset:7168
	ds_read_b64_tr_b16 v[90:91], v211 offset:7680
	s_waitcnt lgkmcnt(14)
	v_mfma_f32_32x32x16_bf16 v[32:47], v[182:185], v[92:95], v[32:47]
	v_exp_f32_e32 v112, v112
	v_exp_f32_e32 v113, v113
	s_waitcnt lgkmcnt(12)
	v_mfma_f32_32x32x16_bf16 v[48:63], v[182:185], v[144:147], v[48:63]
	v_exp_f32_e32 v114, v114
	v_exp_f32_e32 v115, v115
	v_add_u32_e32 v97, s34, v215
	ds_read_b128 v[92:95], v97
	ds_read_b128 v[194:197], v97 offset:512
	s_waitcnt lgkmcnt(12)
	v_mfma_f32_32x32x16_bf16 v[32:47], v[178:181], v[98:101], v[32:47]
	v_exp_f32_e32 v116, v116
	v_exp_f32_e32 v117, v117
	ds_read_b128 v[98:101], v97 offset:2048
	ds_read_b128 v[198:201], v97 offset:2560
	s_waitcnt lgkmcnt(12)
	v_mfma_f32_32x32x16_bf16 v[48:63], v[178:181], v[102:105], v[48:63]
	v_exp_f32_e32 v118, v118
	v_exp_f32_e32 v119, v119
	ds_read_b128 v[102:105], v97 offset:4096
	ds_read_b128 v[202:205], v97 offset:4608
	s_waitcnt lgkmcnt(12)
	v_mfma_f32_32x32x16_bf16 v[32:47], v[170:173], v[106:109], v[32:47]
	v_exp_f32_e32 v120, v120
	v_exp_f32_e32 v121, v121
	ds_read_b128 v[106:109], v97 offset:6144
	ds_read_b128 v[244:247], v97 offset:6656
	s_waitcnt lgkmcnt(12)
	v_mfma_f32_32x32x16_bf16 v[48:63], v[170:173], v[80:83], v[48:63]
	v_exp_f32_e32 v122, v122
	v_exp_f32_e32 v123, v123
	s_waitcnt lgkmcnt(10)
	v_mfma_f32_32x32x16_bf16 v[32:47], v[166:169], v[84:87], v[32:47]
	v_exp_f32_e32 v124, v124
	v_exp_f32_e32 v125, v125
	s_waitcnt lgkmcnt(8)
	v_mfma_f32_32x32x16_bf16 v[48:63], v[166:169], v[88:91], v[48:63]
	v_exp_f32_e32 v126, v126
	v_exp_f32_e32 v127, v127
	s_waitcnt vmcnt(5) lgkmcnt(0)
	s_barrier
	s_add_i32 s22, s34, 0x2000
	s_cmpk_lg_i32 s34, 0x4000
	s_cselect_b32 s22, s22, 0
	v_add_u32_e32 v211, 0x14000, v214
	ds_read_b64_tr_b16 v[248:249], v210 offset:49152
	ds_read_b64_tr_b16 v[250:251], v210 offset:49664
	v_add_f32_e32 v80, v128, v129
	v_add_f32_e32 v80, v130, v80
	v_add_f32_e32 v80, v131, v80
	v_add_f32_e32 v80, v132, v80
	v_add_f32_e32 v80, v133, v80
	v_cvt_pk_bf16_f32 v182, v128, v129
	v_cvt_pk_bf16_f32 v183, v130, v131
	s_waitcnt lgkmcnt(9)
	v_mfma_f32_32x32x16_bf16 v[144:159], v[92:95], v[190:193], v[64:79]
	ds_read_b64_tr_b16 v[222:223], v210 offset:53248
	ds_read_b64_tr_b16 v[224:225], v210 offset:53760
	v_add_f32_e32 v80, v134, v80
	v_add_f32_e32 v80, v135, v80
	v_add_f32_e32 v80, v136, v80
	v_add_f32_e32 v97, v137, v80
	s_waitcnt lgkmcnt(10)
	v_mfma_f32_32x32x16_bf16 v[80:95], v[194:197], v[190:193], v[64:79]
	v_cvt_pk_bf16_f32 v184, v132, v133
	v_cvt_pk_bf16_f32 v185, v134, v135
	ds_read_b64_tr_b16 v[130:131], v210 offset:50176
	ds_read_b64_tr_b16 v[132:133], v210 offset:50688
	v_add_f32_e32 v97, v138, v97
	v_add_f32_e32 v97, v139, v97
	v_add_f32_e32 v97, v140, v97
	v_add_f32_e32 v97, v141, v97
	v_cvt_pk_bf16_f32 v178, v136, v137
	v_cvt_pk_bf16_f32 v179, v138, v139
	s_waitcnt lgkmcnt(11)
	v_mfma_f32_32x32x16_bf16 v[144:159], v[98:101], v[186:189], v[144:159]
	ds_read_b64_tr_b16 v[98:99], v210 offset:54272
	ds_read_b64_tr_b16 v[100:101], v210 offset:54784
	s_waitcnt lgkmcnt(12)
	v_mfma_f32_32x32x16_bf16 v[80:95], v[198:201], v[186:189], v[80:95]
	v_add_f32_e32 v97, v142, v97
	v_add_f32_e32 v97, v143, v97
	v_add_f32_e32 v97, v112, v97
	v_add_f32_e32 v97, v113, v97
	v_cvt_pk_bf16_f32 v180, v140, v141
	v_cvt_pk_bf16_f32 v181, v142, v143
	ds_read_b64_tr_b16 v[134:135], v210 offset:51200
	ds_read_b64_tr_b16 v[136:137], v210 offset:51712
	v_add_f32_e32 v97, v114, v97
	v_add_f32_e32 v97, v115, v97
	v_add_f32_e32 v97, v116, v97
	v_add_f32_e32 v97, v117, v97
	v_cvt_pk_bf16_f32 v170, v112, v113
	v_cvt_pk_bf16_f32 v171, v114, v115
	s_waitcnt lgkmcnt(13)
	v_mfma_f32_32x32x16_bf16 v[144:159], v[102:105], v[174:177], v[144:159]
	ds_read_b64_tr_b16 v[102:103], v210 offset:55296
	ds_read_b64_tr_b16 v[104:105], v210 offset:55808
	s_waitcnt lgkmcnt(14)
	v_mfma_f32_32x32x16_bf16 v[80:95], v[202:205], v[174:177], v[80:95]
	v_add_f32_e32 v97, v118, v97
	v_add_f32_e32 v97, v119, v97
	v_add_f32_e32 v97, v120, v97
	v_add_f32_e32 v97, v121, v97
	v_cvt_pk_bf16_f32 v172, v116, v117
	v_cvt_pk_bf16_f32 v173, v118, v119
	ds_read_b64_tr_b16 v[110:111], v210 offset:52224
	ds_read_b64_tr_b16 v[112:113], v210 offset:52736
	v_add_f32_e32 v97, v122, v97
	v_add_f32_e32 v97, v123, v97
	v_add_f32_e32 v97, v124, v97
	v_add_f32_e32 v97, v125, v97
	v_cvt_pk_bf16_f32 v166, v120, v121
	v_cvt_pk_bf16_f32 v167, v122, v123
	s_waitcnt lgkmcnt(14)
	v_mfma_f32_32x32x16_bf16 v[144:159], v[106:109], v[162:165], v[144:159]
	ds_read_b64_tr_b16 v[106:107], v210 offset:56320
	ds_read_b64_tr_b16 v[108:109], v210 offset:56832
	v_mfma_f32_32x32x16_bf16 v[80:95], v[244:247], v[162:165], v[80:95]
	v_add_f32_e32 v97, v126, v97
	v_add_f32_e32 v97, v127, v97
	v_add_f32_e32 v97, 0, v97
	v_cvt_pk_bf16_f32 v168, v124, v125
	v_cvt_pk_bf16_f32 v169, v126, v127
	s_nop 0
	v_add_f32_e32 v128, v96, v97
	s_add_i32 s23, s34, s29
	v_lshl_add_u64 v[96:97], v[208:209], 0, s[46:47]
	s_mov_b32 s29, m0
	s_mov_b32 m0, s23
	s_nop 0
	global_load_lds_dwordx4 v[96:97], off
	s_mov_b32 m0, s29
	v_lshl_add_u64 v[96:97], v[206:207], 0, s[42:43]
	s_add_i32 s23, s35, 0xe000
	s_mov_b32 s29, m0
	s_mov_b32 m0, s23
	s_nop 0
	global_load_lds_dwordx4 v[96:97], off
	s_mov_b32 m0, s29
	s_mov_b64 s[50:51], 0x4770080
	v_lshl_add_u64 v[96:97], v[206:207], 0, s[50:51]
	s_add_i32 s23, s35, 0x10000
	s_mov_b32 s29, m0
	s_mov_b32 m0, s23
	s_nop 0
	global_load_lds_dwordx4 v[96:97], off
	s_mov_b32 m0, s29
	s_waitcnt lgkmcnt(14)
; #define WAIT_BAR(N) asm volatile("s_waitcnt vmcnt(" #N ") lgkmcnt(0)\n\ts_barrier":::"memory")
;   #define RESC() do{ if(resc){ asm volatile("s_waitcnt lgkmcnt(0)":::"memory"); \
;       _Pragma("unroll") for(int d_=0;d_<2;++d_) _Pragma("unroll") for(int r=0;r<16;++r)o[d_][r]*=wsf[crow(r,hi)]; } }while(0)
;   #define ROT() do{sl_prev=sl_cur;sl_cur=sl_next;sl_next=(sl_next==(NSLOT-1)*SLOTB)?0:sl_next+SLOTB;}while(0)
;   #define ENDW(tt) do{ if((tt)+3<NT){WAIT_BAR(3);} else if((tt)+2<NT){WAIT_BAR(2);} else {WAIT_BAR(0);} }while(0)
; #define WAIT_BAR(N) asm volatile("s_waitcnt vmcnt(" #N ") lgkmcnt(0)\n\ts_barrier":::"memory")
;   #define RESC() do{ if(resc){ asm volatile("s_waitcnt lgkmcnt(0)":::"memory"); \
;       _Pragma("unroll") for(int d_=0;d_<4;++d_) _Pragma("unroll") for(int r=0;r<16;++r)o[d_][r]*=wsf[crow(r,hi)]; } }while(0)
;   #define ROT() do{sl_prev=sl_cur;sl_cur=sl_next;sl_next=(sl_next==(NSLOT-1)*SLOTB)?0:sl_next+SLOTB;}while(0)
;   #define ENDW(tt) do{ if((tt)+3<NT){WAIT_BAR(5);} else if((tt)+2<NT){WAIT_BAR(4);} else {WAIT_BAR(0);} }while(0)
; #define WAIT_BAR(N) asm volatile("s_waitcnt vmcnt(" #N ") lgkmcnt(0)\n\ts_barrier":::"memory")
;   #define RESC() do{ if(resc){ asm volatile("s_waitcnt lgkmcnt(0)":::"memory"); \
;       _Pragma("unroll") for(int d_=0;d_<2;++d_) _Pragma("unroll") for(int r=0;r<16;++r)o[d_][r]*=wsf[crow(r,hi)]; } }while(0)
;   #define ROT() do{sl_prev=sl_cur;sl_cur=sl_next;sl_next=(sl_next==(NSLOT-1)*SLOTB)?0:sl_next+SLOTB;}while(0)
;   #define ENDW(tt) do{ if((tt)+3<NT){WAIT_BAR(3);} else if((tt)+2<NT){WAIT_BAR(2);} else {WAIT_BAR(0);} }while(0)
; template<int THRL,bool FIXED> __device__ __forceinline__ void attn_unit(int qb,const bf16*Qp,const bf16*__restrict__ Kh,const bf16*__restrict__ Vh,bf16*Op,int PO,char*shm,bool comb,float lam,const float*gsub,float gscale){
;     ...
;   int t=1;
;     ...
;   for(;t+5<NT;t+=2){
;     STEP(pB0,pB1,pA0,pA1,t,true,true,true);     WAIT_BAR(5); RESC(); ROT();
;     STEP(pA0,pA1,pB0,pB1,t+1,true,true,true);   WAIT_BAR(5); RESC(); ROT();
;   }
;     ...
;   for(;t+1<NT;t+=2){
;     STEP(pB0,pB1,pA0,pA1,t,(t+3<NT),(t+2<NT),(t+1<NT));       ENDW(t);   RESC(); ROT();
;     STEP(pA0,pA1,pB0,pB1,t+1,(t+4<NT),(t+3<NT),(t+2<NT));     ENDW(t+1); RESC(); ROT();
	v_mfma_f32_32x32x16_bf16 v[0:15], v[182:185], v[248:251], v[0:15]
	v_exp_f32_e32 v144, v144
	v_exp_f32_e32 v145, v145
	ds_read_b64_tr_b16 v[114:115], v211
	ds_read_b64_tr_b16 v[116:117], v211 offset:512
	s_waitcnt lgkmcnt(14)
	v_mfma_f32_32x32x16_bf16 v[16:31], v[182:185], v[222:225], v[16:31]
	v_exp_f32_e32 v146, v146
	v_exp_f32_e32 v147, v147
	ds_read_b64_tr_b16 v[118:119], v211 offset:4096
	ds_read_b64_tr_b16 v[120:121], v211 offset:4608
	s_waitcnt lgkmcnt(14)
	v_mfma_f32_32x32x16_bf16 v[0:15], v[178:181], v[130:133], v[0:15]
	v_exp_f32_e32 v148, v148
	v_exp_f32_e32 v149, v149
	ds_read_b64_tr_b16 v[122:123], v211 offset:1024
	ds_read_b64_tr_b16 v[124:125], v211 offset:1536
	s_waitcnt lgkmcnt(14)
	v_mfma_f32_32x32x16_bf16 v[16:31], v[178:181], v[98:101], v[16:31]
	v_exp_f32_e32 v150, v150
	v_exp_f32_e32 v151, v151
	ds_read_b64_tr_b16 v[96:97], v211 offset:5120
	ds_read_b64_tr_b16 v[98:99], v211 offset:5632
	s_waitcnt lgkmcnt(14)
	v_mfma_f32_32x32x16_bf16 v[0:15], v[170:173], v[134:137], v[0:15]
	v_exp_f32_e32 v152, v152
	v_exp_f32_e32 v153, v153
	ds_read_b64_tr_b16 v[130:131], v211 offset:2048
	ds_read_b64_tr_b16 v[132:133], v211 offset:2560
	s_waitcnt lgkmcnt(14)
	v_mfma_f32_32x32x16_bf16 v[16:31], v[170:173], v[102:105], v[16:31]
	v_exp_f32_e32 v154, v154
	v_exp_f32_e32 v155, v155
	ds_read_b64_tr_b16 v[100:101], v211 offset:6144
	ds_read_b64_tr_b16 v[102:103], v211 offset:6656
	s_waitcnt lgkmcnt(14)
	v_mfma_f32_32x32x16_bf16 v[0:15], v[166:169], v[110:113], v[0:15]
	v_exp_f32_e32 v156, v156
	v_exp_f32_e32 v157, v157
	ds_read_b64_tr_b16 v[110:111], v211 offset:3072
	ds_read_b64_tr_b16 v[112:113], v211 offset:3584
	s_waitcnt lgkmcnt(14)
	v_mfma_f32_32x32x16_bf16 v[16:31], v[166:169], v[106:109], v[16:31]
	v_exp_f32_e32 v158, v158
	v_exp_f32_e32 v159, v159
	ds_read_b64_tr_b16 v[104:105], v211 offset:7168
	ds_read_b64_tr_b16 v[106:107], v211 offset:7680
	s_waitcnt lgkmcnt(14)
	v_mfma_f32_32x32x16_bf16 v[32:47], v[182:185], v[114:117], v[32:47]
	v_exp_f32_e32 v80, v80
	v_exp_f32_e32 v81, v81
	s_waitcnt lgkmcnt(12)
	v_mfma_f32_32x32x16_bf16 v[48:63], v[182:185], v[118:121], v[48:63]
	v_exp_f32_e32 v82, v82
	v_exp_f32_e32 v83, v83
	v_add_u32_e32 v108, s22, v215
	ds_read_b128 v[134:137], v108
	ds_read_b128 v[138:141], v108 offset:512
	s_waitcnt lgkmcnt(12)
	v_mfma_f32_32x32x16_bf16 v[32:47], v[178:181], v[122:125], v[32:47]
	v_exp_f32_e32 v84, v84
	v_exp_f32_e32 v85, v85
	ds_read_b128 v[194:197], v108 offset:2048
	ds_read_b128 v[198:201], v108 offset:2560
	s_waitcnt lgkmcnt(12)
	v_mfma_f32_32x32x16_bf16 v[48:63], v[178:181], v[96:99], v[48:63]
	v_exp_f32_e32 v86, v86
	v_exp_f32_e32 v87, v87
	ds_read_b128 v[202:205], v108 offset:4096
	ds_read_b128 v[208:211], v108 offset:4608
	s_waitcnt lgkmcnt(12)
	v_mfma_f32_32x32x16_bf16 v[32:47], v[170:173], v[130:133], v[32:47]
	v_exp_f32_e32 v88, v88
	v_exp_f32_e32 v89, v89
	ds_read_b128 v[130:133], v108 offset:6144
	ds_read_b128 v[222:225], v108 offset:6656
	s_waitcnt lgkmcnt(12)
	v_mfma_f32_32x32x16_bf16 v[48:63], v[170:173], v[100:103], v[48:63]
	v_exp_f32_e32 v90, v90
	v_exp_f32_e32 v91, v91
	s_waitcnt lgkmcnt(10)
	v_mfma_f32_32x32x16_bf16 v[32:47], v[166:169], v[110:113], v[32:47]
	v_exp_f32_e32 v92, v92
	v_exp_f32_e32 v93, v93
	s_waitcnt lgkmcnt(8)
	v_mfma_f32_32x32x16_bf16 v[48:63], v[166:169], v[104:107], v[48:63]
	v_exp_f32_e32 v94, v94
	v_exp_f32_e32 v95, v95
	s_waitcnt vmcnt(5) lgkmcnt(0)
	s_barrier
	s_add_i32 s23, s22, 0x2000
	s_cmpk_lg_i32 s22, 0x4000
	s_cselect_b32 s22, s23, 0
	v_add_u32_e32 v212, 0x8000, v214
	ds_read_b64_tr_b16 v[244:245], v214 offset:24576
	ds_read_b64_tr_b16 v[246:247], v214 offset:25088
	v_add_f32_e32 v96, v144, v145
	v_add_f32_e32 v96, v146, v96
	v_add_f32_e32 v96, v147, v96
	v_add_f32_e32 v96, v148, v96
	v_add_f32_e32 v96, v149, v96
	v_cvt_pk_bf16_f32 v182, v144, v145
	v_cvt_pk_bf16_f32 v183, v146, v147
	s_waitcnt lgkmcnt(9)
	v_mfma_f32_32x32x16_bf16 v[112:127], v[134:137], v[190:193], v[64:79]
	ds_read_b64_tr_b16 v[134:135], v214 offset:28672
	ds_read_b64_tr_b16 v[136:137], v214 offset:29184
	v_add_f32_e32 v96, v150, v96
	v_add_f32_e32 v96, v151, v96
	v_add_f32_e32 v96, v152, v96
	v_add_f32_e32 v129, v153, v96
	v_cvt_pk_bf16_f32 v184, v148, v149
	v_cvt_pk_bf16_f32 v185, v150, v151
	s_waitcnt lgkmcnt(10)
	v_mfma_f32_32x32x16_bf16 v[96:111], v[138:141], v[190:193], v[64:79]
	ds_read_b64_tr_b16 v[138:139], v214 offset:25600
	ds_read_b64_tr_b16 v[140:141], v214 offset:26112
	v_add_f32_e32 v129, v154, v129
	v_add_f32_e32 v129, v155, v129
	v_add_f32_e32 v129, v156, v129
	v_add_f32_e32 v129, v157, v129
	v_cvt_pk_bf16_f32 v178, v152, v153
	v_cvt_pk_bf16_f32 v179, v154, v155
	s_waitcnt lgkmcnt(11)
	v_mfma_f32_32x32x16_bf16 v[112:127], v[194:197], v[186:189], v[112:127]
	ds_read_b64_tr_b16 v[146:147], v214 offset:29696
	ds_read_b64_tr_b16 v[148:149], v214 offset:30208
	v_add_f32_e32 v129, v158, v129
	v_add_f32_e32 v129, v159, v129
	v_add_f32_e32 v129, v80, v129
	v_add_f32_e32 v129, v81, v129
	v_cvt_pk_bf16_f32 v180, v156, v157
	v_cvt_pk_bf16_f32 v181, v158, v159
	s_waitcnt lgkmcnt(12)
	v_mfma_f32_32x32x16_bf16 v[96:111], v[198:201], v[186:189], v[96:111]
	ds_read_b64_tr_b16 v[150:151], v214 offset:26624
	ds_read_b64_tr_b16 v[152:153], v214 offset:27136
	v_add_f32_e32 v129, v82, v129
	v_add_f32_e32 v129, v83, v129
	v_add_f32_e32 v129, v84, v129
	v_add_f32_e32 v129, v85, v129
	v_cvt_pk_bf16_f32 v170, v80, v81
	v_cvt_pk_bf16_f32 v171, v82, v83
	s_waitcnt lgkmcnt(13)
	v_mfma_f32_32x32x16_bf16 v[112:127], v[202:205], v[174:177], v[112:127]
	ds_read_b64_tr_b16 v[80:81], v214 offset:30720
	ds_read_b64_tr_b16 v[82:83], v214 offset:31232
	v_add_f32_e32 v129, v86, v129
	v_add_f32_e32 v129, v87, v129
	v_add_f32_e32 v129, v88, v129
	v_add_f32_e32 v129, v89, v129
	v_cvt_pk_bf16_f32 v172, v84, v85
	v_cvt_pk_bf16_f32 v173, v86, v87
	s_waitcnt lgkmcnt(14)
; #define WAIT_BAR(N) asm volatile("s_waitcnt vmcnt(" #N ") lgkmcnt(0)\n\ts_barrier":::"memory")
;   #define RESC() do{ if(resc){ asm volatile("s_waitcnt lgkmcnt(0)":::"memory"); \
;       _Pragma("unroll") for(int d_=0;d_<2;++d_) _Pragma("unroll") for(int r=0;r<16;++r)o[d_][r]*=wsf[crow(r,hi)]; } }while(0)
;   #define ROT() do{sl_prev=sl_cur;sl_cur=sl_next;sl_next=(sl_next==(NSLOT-1)*SLOTB)?0:sl_next+SLOTB;}while(0)
;   #define ENDW(tt) do{ if((tt)+3<NT){WAIT_BAR(3);} else if((tt)+2<NT){WAIT_BAR(2);} else {WAIT_BAR(0);} }while(0)
; #define WAIT_BAR(N) asm volatile("s_waitcnt vmcnt(" #N ") lgkmcnt(0)\n\ts_barrier":::"memory")
;   #define RESC() do{ if(resc){ asm volatile("s_waitcnt lgkmcnt(0)":::"memory"); \
;       _Pragma("unroll") for(int d_=0;d_<4;++d_) _Pragma("unroll") for(int r=0;r<16;++r)o[d_][r]*=wsf[crow(r,hi)]; } }while(0)
;   #define ROT() do{sl_prev=sl_cur;sl_cur=sl_next;sl_next=(sl_next==(NSLOT-1)*SLOTB)?0:sl_next+SLOTB;}while(0)
;   #define ENDW(tt) do{ if((tt)+3<NT){WAIT_BAR(5);} else if((tt)+2<NT){WAIT_BAR(4);} else {WAIT_BAR(0);} }while(0)
; #define WAIT_BAR(N) asm volatile("s_waitcnt vmcnt(" #N ") lgkmcnt(0)\n\ts_barrier":::"memory")
;   #define RESC() do{ if(resc){ asm volatile("s_waitcnt lgkmcnt(0)":::"memory"); \
;       _Pragma("unroll") for(int d_=0;d_<2;++d_) _Pragma("unroll") for(int r=0;r<16;++r)o[d_][r]*=wsf[crow(r,hi)]; } }while(0)
;   #define ROT() do{sl_prev=sl_cur;sl_cur=sl_next;sl_next=(sl_next==(NSLOT-1)*SLOTB)?0:sl_next+SLOTB;}while(0)
;   #define ENDW(tt) do{ if((tt)+3<NT){WAIT_BAR(3);} else if((tt)+2<NT){WAIT_BAR(2);} else {WAIT_BAR(0);} }while(0)
; template<int THRL,bool FIXED> __device__ __forceinline__ void attn_unit(int qb,const bf16*Qp,const bf16*__restrict__ Kh,const bf16*__restrict__ Vh,bf16*Op,int PO,char*shm,bool comb,float lam,const float*gsub,float gscale){
;     ...
;   int t=1;
;     ...
;   for(;t+5<NT;t+=2){
;     STEP(pB0,pB1,pA0,pA1,t,true,true,true);     WAIT_BAR(5); RESC(); ROT();
;     STEP(pA0,pA1,pB0,pB1,t+1,true,true,true);   WAIT_BAR(5); RESC(); ROT();
;   }
;     ...
;   for(;t+1<NT;t+=2){
;     STEP(pB0,pB1,pA0,pA1,t,(t+3<NT),(t+2<NT),(t+1<NT));       ENDW(t);   RESC(); ROT();
;     STEP(pA0,pA1,pB0,pB1,t+1,(t+4<NT),(t+3<NT),(t+2<NT));     ENDW(t+1); RESC(); ROT();
	v_mfma_f32_32x32x16_bf16 v[96:111], v[208:211], v[174:177], v[96:111]
	ds_read_b64_tr_b16 v[84:85], v214 offset:27648
	ds_read_b64_tr_b16 v[86:87], v214 offset:28160
	v_add_f32_e32 v129, v90, v129
	v_add_f32_e32 v129, v91, v129
	v_add_f32_e32 v129, v92, v129
	v_add_f32_e32 v129, v93, v129
	v_cvt_pk_bf16_f32 v166, v88, v89
	v_cvt_pk_bf16_f32 v167, v90, v91
	s_waitcnt lgkmcnt(14)
	v_mfma_f32_32x32x16_bf16 v[112:127], v[130:133], v[162:165], v[112:127]
	ds_read_b64_tr_b16 v[88:89], v214 offset:31744
	ds_read_b64_tr_b16 v[90:91], v214 offset:32256
	v_add_f32_e32 v129, v94, v129
	v_add_f32_e32 v129, v95, v129
	v_add_f32_e32 v129, 0, v129
	v_cvt_pk_bf16_f32 v168, v92, v93
	v_cvt_pk_bf16_f32 v169, v94, v95
	v_mfma_f32_32x32x16_bf16 v[96:111], v[222:225], v[162:165], v[96:111]
	s_add_i32 s29, s44, 0x12000
	v_lshl_add_u64 v[92:93], v[206:207], 0, s[46:47]
	s_add_i32 s3, s3, s29
	s_mov_b32 s23, m0
	s_mov_b32 m0, s3
	s_nop 0
	global_load_lds_dwordx4 v[92:93], off
	s_mov_b32 m0, s23
	s_mov_b64 s[50:51], 0x47b8080
	v_lshl_add_u64 v[92:93], v[206:207], 0, s[50:51]
	s_add_i32 s35, s35, 0x14000
	s_mov_b32 s3, m0
	s_mov_b32 m0, s35
	s_nop 0
	global_load_lds_dwordx4 v[92:93], off
	s_mov_b32 m0, s3
	v_add_f32_e32 v144, v128, v129
	s_waitcnt lgkmcnt(14)
	v_mfma_f32_32x32x16_bf16 v[0:15], v[182:185], v[244:247], v[0:15]
	v_exp_f32_e32 v112, v112
	v_exp_f32_e32 v113, v113
	ds_read_b64_tr_b16 v[92:93], v212
	ds_read_b64_tr_b16 v[94:95], v212 offset:512
	s_waitcnt lgkmcnt(14)
	v_mfma_f32_32x32x16_bf16 v[16:31], v[182:185], v[134:137], v[16:31]
	v_exp_f32_e32 v114, v114
	v_exp_f32_e32 v115, v115
	ds_read_b64_tr_b16 v[128:129], v212 offset:4096
	ds_read_b64_tr_b16 v[130:131], v212 offset:4608
	s_waitcnt lgkmcnt(14)
	v_mfma_f32_32x32x16_bf16 v[0:15], v[178:181], v[138:141], v[0:15]
	v_exp_f32_e32 v116, v116
	v_exp_f32_e32 v117, v117
	ds_read_b64_tr_b16 v[132:133], v212 offset:1024
	ds_read_b64_tr_b16 v[134:135], v212 offset:1536
	s_waitcnt lgkmcnt(14)
	v_mfma_f32_32x32x16_bf16 v[16:31], v[178:181], v[146:149], v[16:31]
	v_exp_f32_e32 v118, v118
	v_exp_f32_e32 v119, v119
	ds_read_b64_tr_b16 v[136:137], v212 offset:5120
	ds_read_b64_tr_b16 v[138:139], v212 offset:5632
	s_waitcnt lgkmcnt(14)
	v_mfma_f32_32x32x16_bf16 v[0:15], v[170:173], v[150:153], v[0:15]
	v_exp_f32_e32 v120, v120
	v_exp_f32_e32 v121, v121
	ds_read_b64_tr_b16 v[140:141], v212 offset:2048
	ds_read_b64_tr_b16 v[142:143], v212 offset:2560
	s_waitcnt lgkmcnt(14)
	v_mfma_f32_32x32x16_bf16 v[16:31], v[170:173], v[80:83], v[16:31]
	v_exp_f32_e32 v122, v122
	v_exp_f32_e32 v123, v123
	ds_read_b64_tr_b16 v[80:81], v212 offset:6144
	ds_read_b64_tr_b16 v[82:83], v212 offset:6656
	s_waitcnt lgkmcnt(14)
	v_mfma_f32_32x32x16_bf16 v[0:15], v[166:169], v[84:87], v[0:15]
	v_exp_f32_e32 v124, v124
	v_exp_f32_e32 v125, v125
	ds_read_b64_tr_b16 v[84:85], v212 offset:3072
	ds_read_b64_tr_b16 v[86:87], v212 offset:3584
	s_waitcnt lgkmcnt(14)
	v_mfma_f32_32x32x16_bf16 v[16:31], v[166:169], v[88:91], v[16:31]
	v_exp_f32_e32 v126, v126
	v_exp_f32_e32 v127, v127
	ds_read_b64_tr_b16 v[88:89], v212 offset:7168
	ds_read_b64_tr_b16 v[90:91], v212 offset:7680
	s_waitcnt lgkmcnt(14)
	v_mfma_f32_32x32x16_bf16 v[32:47], v[182:185], v[92:95], v[32:47]
	v_exp_f32_e32 v96, v96
	v_exp_f32_e32 v97, v97
	s_waitcnt lgkmcnt(12)
	v_mfma_f32_32x32x16_bf16 v[48:63], v[182:185], v[128:131], v[48:63]
	v_exp_f32_e32 v98, v98
	v_exp_f32_e32 v99, v99
	v_add_u32_e32 v128, s22, v215
	ds_read_b128 v[92:95], v128
	ds_read_b128 v[146:149], v128 offset:512
	s_waitcnt lgkmcnt(12)
	v_mfma_f32_32x32x16_bf16 v[32:47], v[178:181], v[132:135], v[32:47]
	v_exp_f32_e32 v100, v100
	v_exp_f32_e32 v101, v101
	ds_read_b128 v[150:153], v128 offset:2048
	ds_read_b128 v[154:157], v128 offset:2560
	s_waitcnt lgkmcnt(12)
	v_mfma_f32_32x32x16_bf16 v[48:63], v[178:181], v[136:139], v[48:63]
	v_exp_f32_e32 v102, v102
	v_exp_f32_e32 v103, v103
	ds_read_b128 v[194:197], v128 offset:4096
	ds_read_b128 v[198:201], v128 offset:4608
	s_waitcnt lgkmcnt(12)
	v_mfma_f32_32x32x16_bf16 v[32:47], v[170:173], v[140:143], v[32:47]
	v_exp_f32_e32 v104, v104
	v_exp_f32_e32 v105, v105
	ds_read_b128 v[202:205], v128 offset:6144
	ds_read_b128 v[206:209], v128 offset:6656
	s_waitcnt lgkmcnt(12)
	v_mfma_f32_32x32x16_bf16 v[48:63], v[170:173], v[80:83], v[48:63]
	v_exp_f32_e32 v106, v106
	v_exp_f32_e32 v107, v107
	s_waitcnt lgkmcnt(10)
	v_mfma_f32_32x32x16_bf16 v[32:47], v[166:169], v[84:87], v[32:47]
	v_exp_f32_e32 v108, v108
	v_exp_f32_e32 v109, v109
	s_waitcnt lgkmcnt(8)
	v_mfma_f32_32x32x16_bf16 v[48:63], v[166:169], v[88:91], v[48:63]
	v_exp_f32_e32 v110, v110
	v_exp_f32_e32 v111, v111
	s_waitcnt vmcnt(4) lgkmcnt(0)
	s_barrier
; #define WAIT_BAR(N) asm volatile("s_waitcnt vmcnt(" #N ") lgkmcnt(0)\n\ts_barrier":::"memory")
;   #define RESC() do{ if(resc){ asm volatile("s_waitcnt lgkmcnt(0)":::"memory"); \
;       _Pragma("unroll") for(int d_=0;d_<2;++d_) _Pragma("unroll") for(int r=0;r<16;++r)o[d_][r]*=wsf[crow(r,hi)]; } }while(0)
;   #define ROT() do{sl_prev=sl_cur;sl_cur=sl_next;sl_next=(sl_next==(NSLOT-1)*SLOTB)?0:sl_next+SLOTB;}while(0)
;   #define ENDW(tt) do{ if((tt)+3<NT){WAIT_BAR(3);} else if((tt)+2<NT){WAIT_BAR(2);} else {WAIT_BAR(0);} }while(0)
; #define WAIT_BAR(N) asm volatile("s_waitcnt vmcnt(" #N ") lgkmcnt(0)\n\ts_barrier":::"memory")
;   #define RESC() do{ if(resc){ asm volatile("s_waitcnt lgkmcnt(0)":::"memory"); \
;       _Pragma("unroll") for(int d_=0;d_<4;++d_) _Pragma("unroll") for(int r=0;r<16;++r)o[d_][r]*=wsf[crow(r,hi)]; } }while(0)
;   #define ROT() do{sl_prev=sl_cur;sl_cur=sl_next;sl_next=(sl_next==(NSLOT-1)*SLOTB)?0:sl_next+SLOTB;}while(0)
;   #define ENDW(tt) do{ if((tt)+3<NT){WAIT_BAR(5);} else if((tt)+2<NT){WAIT_BAR(4);} else {WAIT_BAR(0);} }while(0)
; #define WAIT_BAR(N) asm volatile("s_waitcnt vmcnt(" #N ") lgkmcnt(0)\n\ts_barrier":::"memory")
;   #define RESC() do{ if(resc){ asm volatile("s_waitcnt lgkmcnt(0)":::"memory"); \
;       _Pragma("unroll") for(int d_=0;d_<2;++d_) _Pragma("unroll") for(int r=0;r<16;++r)o[d_][r]*=wsf[crow(r,hi)]; } }while(0)
;   #define ROT() do{sl_prev=sl_cur;sl_cur=sl_next;sl_next=(sl_next==(NSLOT-1)*SLOTB)?0:sl_next+SLOTB;}while(0)
;   #define ENDW(tt) do{ if((tt)+3<NT){WAIT_BAR(3);} else if((tt)+2<NT){WAIT_BAR(2);} else {WAIT_BAR(0);} }while(0)
; template<int THRL,bool FIXED> __device__ __forceinline__ void attn_unit(int qb,const bf16*Qp,const bf16*__restrict__ Kh,const bf16*__restrict__ Vh,bf16*Op,int PO,char*shm,bool comb,float lam,const float*gsub,float gscale){
;     ...
;   int t=1;
;     ...
;   for(;t+5<NT;t+=2){
;     STEP(pB0,pB1,pA0,pA1,t,true,true,true);     WAIT_BAR(5); RESC(); ROT();
;     STEP(pA0,pA1,pB0,pB1,t+1,true,true,true);   WAIT_BAR(5); RESC(); ROT();
;   }
;     ...
;   for(;t+1<NT;t+=2){
;     STEP(pB0,pB1,pA0,pA1,t,(t+3<NT),(t+2<NT),(t+1<NT));       ENDW(t);   RESC(); ROT();
;     STEP(pA0,pA1,pB0,pB1,t+1,(t+4<NT),(t+3<NT),(t+2<NT));     ENDW(t+1); RESC(); ROT();
	s_add_i32 s3, s22, 0x2000
	s_cmpk_lg_i32 s22, 0x4000
	s_cselect_b32 s3, s3, 0
	v_add_u32_e32 v158, 0xc000, v214
	ds_read_b64_tr_b16 v[210:211], v214 offset:40960
	ds_read_b64_tr_b16 v[212:213], v214 offset:41472
	v_add_f32_e32 v80, v112, v113
	v_add_f32_e32 v80, v114, v80
	v_add_f32_e32 v80, v115, v80
	v_add_f32_e32 v80, v116, v80
	v_add_f32_e32 v80, v117, v80
	v_cvt_pk_bf16_f32 v182, v112, v113
	v_cvt_pk_bf16_f32 v183, v114, v115
	s_waitcnt lgkmcnt(9)
	v_mfma_f32_32x32x16_bf16 v[128:143], v[92:95], v[190:193], v[64:79]
	ds_read_b64_tr_b16 v[222:223], v214 offset:45056
	ds_read_b64_tr_b16 v[224:225], v214 offset:45568
	v_add_f32_e32 v80, v118, v80
	v_add_f32_e32 v80, v119, v80
	v_add_f32_e32 v80, v120, v80
	v_add_f32_e32 v112, v121, v80
	s_waitcnt lgkmcnt(10)
	v_mfma_f32_32x32x16_bf16 v[80:95], v[146:149], v[190:193], v[64:79]
	v_cvt_pk_bf16_f32 v184, v116, v117
	v_cvt_pk_bf16_f32 v185, v118, v119
	ds_read_b64_tr_b16 v[114:115], v214 offset:41984
	ds_read_b64_tr_b16 v[116:117], v214 offset:42496
	v_add_f32_e32 v112, v122, v112
	v_add_f32_e32 v112, v123, v112
	v_add_f32_e32 v112, v124, v112
	v_add_f32_e32 v112, v125, v112
	v_cvt_pk_bf16_f32 v178, v120, v121
	v_cvt_pk_bf16_f32 v179, v122, v123
	s_waitcnt lgkmcnt(11)
	v_mfma_f32_32x32x16_bf16 v[128:143], v[150:153], v[186:189], v[128:143]
	ds_read_b64_tr_b16 v[118:119], v214 offset:46080
	ds_read_b64_tr_b16 v[120:121], v214 offset:46592
	s_waitcnt lgkmcnt(12)
	v_mfma_f32_32x32x16_bf16 v[80:95], v[154:157], v[186:189], v[80:95]
	v_add_f32_e32 v112, v126, v112
	v_add_f32_e32 v112, v127, v112
	v_add_f32_e32 v112, v96, v112
	v_add_f32_e32 v112, v97, v112
	v_cvt_pk_bf16_f32 v180, v124, v125
	v_cvt_pk_bf16_f32 v181, v126, v127
	ds_read_b64_tr_b16 v[122:123], v214 offset:43008
	ds_read_b64_tr_b16 v[124:125], v214 offset:43520
	v_add_f32_e32 v112, v98, v112
	v_add_f32_e32 v112, v99, v112
	v_add_f32_e32 v112, v100, v112
	v_add_f32_e32 v112, v101, v112
	v_cvt_pk_bf16_f32 v170, v96, v97
	v_cvt_pk_bf16_f32 v171, v98, v99
	s_waitcnt lgkmcnt(13)
	v_mfma_f32_32x32x16_bf16 v[128:143], v[194:197], v[174:177], v[128:143]
	ds_read_b64_tr_b16 v[96:97], v214 offset:47104
	ds_read_b64_tr_b16 v[98:99], v214 offset:47616
	s_waitcnt lgkmcnt(14)
	v_mfma_f32_32x32x16_bf16 v[80:95], v[198:201], v[174:177], v[80:95]
	v_add_f32_e32 v112, v102, v112
	v_add_f32_e32 v112, v103, v112
	v_add_f32_e32 v112, v104, v112
	v_add_f32_e32 v112, v105, v112
	v_cvt_pk_bf16_f32 v172, v100, v101
	v_cvt_pk_bf16_f32 v173, v102, v103
	ds_read_b64_tr_b16 v[100:101], v214 offset:44032
	ds_read_b64_tr_b16 v[102:103], v214 offset:44544
	v_add_f32_e32 v112, v106, v112
	v_add_f32_e32 v112, v107, v112
	v_add_f32_e32 v112, v108, v112
	v_add_f32_e32 v112, v109, v112
	v_cvt_pk_bf16_f32 v166, v104, v105
	v_cvt_pk_bf16_f32 v167, v106, v107
	s_waitcnt lgkmcnt(14)
	v_mfma_f32_32x32x16_bf16 v[128:143], v[202:205], v[162:165], v[128:143]
	ds_read_b64_tr_b16 v[104:105], v214 offset:48128
	ds_read_b64_tr_b16 v[106:107], v214 offset:48640
	v_mfma_f32_32x32x16_bf16 v[80:95], v[206:209], v[162:165], v[80:95]
	v_add_f32_e32 v112, v110, v112
	v_add_f32_e32 v112, v111, v112
	v_add_f32_e32 v112, 0, v112
	v_cvt_pk_bf16_f32 v168, v108, v109
	v_cvt_pk_bf16_f32 v169, v110, v111
	s_nop 0
	v_add_f32_e32 v112, v144, v112
	s_waitcnt lgkmcnt(14)
	v_mfma_f32_32x32x16_bf16 v[0:15], v[182:185], v[210:213], v[0:15]
	v_exp_f32_e32 v128, v128
	v_exp_f32_e32 v129, v129
	ds_read_b64_tr_b16 v[108:109], v158
	ds_read_b64_tr_b16 v[110:111], v158 offset:512
	s_waitcnt lgkmcnt(14)
	v_mfma_f32_32x32x16_bf16 v[16:31], v[182:185], v[222:225], v[16:31]
	v_exp_f32_e32 v130, v130
	v_exp_f32_e32 v131, v131
	ds_read_b64_tr_b16 v[144:145], v158 offset:4096
	ds_read_b64_tr_b16 v[146:147], v158 offset:4608
	s_waitcnt lgkmcnt(14)
	v_mfma_f32_32x32x16_bf16 v[0:15], v[178:181], v[114:117], v[0:15]
	v_exp_f32_e32 v132, v132
	v_exp_f32_e32 v133, v133
	ds_read_b64_tr_b16 v[114:115], v158 offset:1024
	ds_read_b64_tr_b16 v[116:117], v158 offset:1536
	s_waitcnt lgkmcnt(14)
	v_mfma_f32_32x32x16_bf16 v[16:31], v[178:181], v[118:121], v[16:31]
	v_exp_f32_e32 v134, v134
	v_exp_f32_e32 v135, v135
	ds_read_b64_tr_b16 v[118:119], v158 offset:5120
	ds_read_b64_tr_b16 v[120:121], v158 offset:5632
	s_waitcnt lgkmcnt(14)
	v_mfma_f32_32x32x16_bf16 v[0:15], v[170:173], v[122:125], v[0:15]
	v_exp_f32_e32 v136, v136
	v_exp_f32_e32 v137, v137
	ds_read_b64_tr_b16 v[122:123], v158 offset:2048
	ds_read_b64_tr_b16 v[124:125], v158 offset:2560
	s_waitcnt lgkmcnt(14)
	v_mfma_f32_32x32x16_bf16 v[16:31], v[170:173], v[96:99], v[16:31]
	v_exp_f32_e32 v138, v138
	v_exp_f32_e32 v139, v139
	ds_read_b64_tr_b16 v[96:97], v158 offset:6144
	ds_read_b64_tr_b16 v[98:99], v158 offset:6656
	s_waitcnt lgkmcnt(14)
	v_mfma_f32_32x32x16_bf16 v[0:15], v[166:169], v[100:103], v[0:15]
	v_exp_f32_e32 v140, v140
	v_exp_f32_e32 v141, v141
	ds_read_b64_tr_b16 v[100:101], v158 offset:3072
	ds_read_b64_tr_b16 v[102:103], v158 offset:3584
	s_waitcnt lgkmcnt(14)
	v_mfma_f32_32x32x16_bf16 v[16:31], v[166:169], v[104:107], v[16:31]
	v_exp_f32_e32 v142, v142
	v_exp_f32_e32 v143, v143
	ds_read_b64_tr_b16 v[104:105], v158 offset:7168
	ds_read_b64_tr_b16 v[106:107], v158 offset:7680
	s_waitcnt lgkmcnt(14)
	v_mfma_f32_32x32x16_bf16 v[32:47], v[182:185], v[108:111], v[32:47]
	v_exp_f32_e32 v80, v80
	v_exp_f32_e32 v81, v81
	s_waitcnt lgkmcnt(12)
	v_mfma_f32_32x32x16_bf16 v[48:63], v[182:185], v[144:147], v[48:63]
	v_exp_f32_e32 v82, v82
	v_exp_f32_e32 v83, v83
	v_add_u32_e32 v108, s3, v215
	ds_read_b128 v[144:147], v108
	ds_read_b128 v[148:151], v108 offset:512
	s_waitcnt lgkmcnt(12)
	v_mfma_f32_32x32x16_bf16 v[32:47], v[178:181], v[114:117], v[32:47]
	v_exp_f32_e32 v84, v84
	v_exp_f32_e32 v85, v85
	ds_read_b128 v[114:117], v108 offset:2048
	ds_read_b128 v[152:155], v108 offset:2560
	s_waitcnt lgkmcnt(12)
	v_mfma_f32_32x32x16_bf16 v[48:63], v[178:181], v[118:121], v[48:63]
	v_exp_f32_e32 v86, v86
	v_exp_f32_e32 v87, v87
	ds_read_b128 v[118:121], v108 offset:4096
	ds_read_b128 v[156:159], v108 offset:4608
	s_waitcnt lgkmcnt(12)
	v_mfma_f32_32x32x16_bf16 v[32:47], v[170:173], v[122:125], v[32:47]
	v_exp_f32_e32 v88, v88
	v_exp_f32_e32 v89, v89
	ds_read_b128 v[122:125], v108 offset:6144
	ds_read_b128 v[194:197], v108 offset:6656
	s_waitcnt lgkmcnt(12)
	v_mfma_f32_32x32x16_bf16 v[48:63], v[170:173], v[96:99], v[48:63]
	v_exp_f32_e32 v90, v90
	v_exp_f32_e32 v91, v91
	s_waitcnt lgkmcnt(10)
	v_mfma_f32_32x32x16_bf16 v[32:47], v[166:169], v[100:103], v[32:47]
	v_exp_f32_e32 v92, v92
	v_exp_f32_e32 v93, v93
	s_waitcnt lgkmcnt(8)
	v_mfma_f32_32x32x16_bf16 v[48:63], v[166:169], v[104:107], v[48:63]
	v_exp_f32_e32 v94, v94
	v_exp_f32_e32 v95, v95
	s_waitcnt vmcnt(0) lgkmcnt(0)
	s_barrier
; #define WAIT_BAR(N) asm volatile("s_waitcnt vmcnt(" #N ") lgkmcnt(0)\n\ts_barrier":::"memory")
;   #define RESC() do{ if(resc){ asm volatile("s_waitcnt lgkmcnt(0)":::"memory"); \
;       _Pragma("unroll") for(int d_=0;d_<2;++d_) _Pragma("unroll") for(int r=0;r<16;++r)o[d_][r]*=wsf[crow(r,hi)]; } }while(0)
;   #define ROT() do{sl_prev=sl_cur;sl_cur=sl_next;sl_next=(sl_next==(NSLOT-1)*SLOTB)?0:sl_next+SLOTB;}while(0)
;   #define ENDW(tt) do{ if((tt)+3<NT){WAIT_BAR(3);} else if((tt)+2<NT){WAIT_BAR(2);} else {WAIT_BAR(0);} }while(0)
; #define WAIT_BAR(N) asm volatile("s_waitcnt vmcnt(" #N ") lgkmcnt(0)\n\ts_barrier":::"memory")
;   #define RESC() do{ if(resc){ asm volatile("s_waitcnt lgkmcnt(0)":::"memory"); \
;       _Pragma("unroll") for(int d_=0;d_<4;++d_) _Pragma("unroll") for(int r=0;r<16;++r)o[d_][r]*=wsf[crow(r,hi)]; } }while(0)
;   #define ROT() do{sl_prev=sl_cur;sl_cur=sl_next;sl_next=(sl_next==(NSLOT-1)*SLOTB)?0:sl_next+SLOTB;}while(0)
;   #define ENDW(tt) do{ if((tt)+3<NT){WAIT_BAR(5);} else if((tt)+2<NT){WAIT_BAR(4);} else {WAIT_BAR(0);} }while(0)
; #define WAIT_BAR(N) asm volatile("s_waitcnt vmcnt(" #N ") lgkmcnt(0)\n\ts_barrier":::"memory")
;   #define RESC() do{ if(resc){ asm volatile("s_waitcnt lgkmcnt(0)":::"memory"); \
;       _Pragma("unroll") for(int d_=0;d_<2;++d_) _Pragma("unroll") for(int r=0;r<16;++r)o[d_][r]*=wsf[crow(r,hi)]; } }while(0)
;   #define ROT() do{sl_prev=sl_cur;sl_cur=sl_next;sl_next=(sl_next==(NSLOT-1)*SLOTB)?0:sl_next+SLOTB;}while(0)
;   #define ENDW(tt) do{ if((tt)+3<NT){WAIT_BAR(3);} else if((tt)+2<NT){WAIT_BAR(2);} else {WAIT_BAR(0);} }while(0)
; template<int THRL,bool FIXED> __device__ __forceinline__ void attn_unit(int qb,const bf16*Qp,const bf16*__restrict__ Kh,const bf16*__restrict__ Vh,bf16*Op,int PO,char*shm,bool comb,float lam,const float*gsub,float gscale){
;     ...
;   int t=1;
;     ...
;   for(;t+5<NT;t+=2){
;     STEP(pB0,pB1,pA0,pA1,t,true,true,true);     WAIT_BAR(5); RESC(); ROT();
;     STEP(pA0,pA1,pB0,pB1,t+1,true,true,true);   WAIT_BAR(5); RESC(); ROT();
;   }
;     ...
;   for(;t+1<NT;t+=2){
;     STEP(pB0,pB1,pA0,pA1,t,(t+3<NT),(t+2<NT),(t+1<NT));       ENDW(t);   RESC(); ROT();
;     STEP(pA0,pA1,pB0,pB1,t+1,(t+4<NT),(t+3<NT),(t+2<NT));     ENDW(t+1); RESC(); ROT();
;   }
;   STEP(pB0,pB1,pA0,pA1,NT-1,false,false,false); RESC();
	ds_read_b64_tr_b16 v[198:199], v214 offset:57344
	ds_read_b64_tr_b16 v[200:201], v214 offset:57856
	v_add_f32_e32 v96, v128, v129
	v_add_f32_e32 v96, v130, v96
	v_add_f32_e32 v96, v131, v96
	v_add_f32_e32 v96, v132, v96
	v_add_f32_e32 v113, v133, v96
	v_cvt_pk_bf16_f32 v182, v128, v129
	v_cvt_pk_bf16_f32 v183, v130, v131
	s_waitcnt lgkmcnt(9)
	v_mfma_f32_32x32x16_bf16 v[96:111], v[144:147], v[190:193], v[64:79]
	ds_read_b64_tr_b16 v[126:127], v214 offset:61440
	ds_read_b64_tr_b16 v[128:129], v214 offset:61952
	s_waitcnt lgkmcnt(10)
	v_mfma_f32_32x32x16_bf16 v[64:79], v[148:151], v[190:193], v[64:79]
	v_add_f32_e32 v113, v134, v113
	v_add_f32_e32 v113, v135, v113
	v_add_f32_e32 v113, v136, v113
	v_add_f32_e32 v113, v137, v113
	v_cvt_pk_bf16_f32 v184, v132, v133
	v_cvt_pk_bf16_f32 v185, v134, v135
	ds_read_b64_tr_b16 v[130:131], v214 offset:58368
	ds_read_b64_tr_b16 v[132:133], v214 offset:58880
	v_add_f32_e32 v113, v138, v113
	v_add_f32_e32 v113, v139, v113
	v_add_f32_e32 v113, v140, v113
	v_add_f32_e32 v113, v141, v113
	v_cvt_pk_bf16_f32 v178, v136, v137
	v_cvt_pk_bf16_f32 v179, v138, v139
	s_waitcnt lgkmcnt(11)
	v_mfma_f32_32x32x16_bf16 v[96:111], v[114:117], v[186:189], v[96:111]
	ds_read_b64_tr_b16 v[114:115], v214 offset:62464
	ds_read_b64_tr_b16 v[116:117], v214 offset:62976
	s_waitcnt lgkmcnt(12)
	v_mfma_f32_32x32x16_bf16 v[64:79], v[152:155], v[186:189], v[64:79]
	v_add_f32_e32 v113, v142, v113
	v_add_f32_e32 v113, v143, v113
	v_add_f32_e32 v113, v80, v113
	v_add_f32_e32 v113, v81, v113
	v_cvt_pk_bf16_f32 v180, v140, v141
	v_cvt_pk_bf16_f32 v181, v142, v143
	ds_read_b64_tr_b16 v[134:135], v214 offset:59392
	ds_read_b64_tr_b16 v[136:137], v214 offset:59904
	v_add_f32_e32 v113, v82, v113
	v_add_f32_e32 v113, v83, v113
	v_add_f32_e32 v113, v84, v113
	v_add_f32_e32 v113, v85, v113
	v_cvt_pk_bf16_f32 v170, v80, v81
	v_cvt_pk_bf16_f32 v171, v82, v83
	s_waitcnt lgkmcnt(13)
	v_mfma_f32_32x32x16_bf16 v[96:111], v[118:121], v[174:177], v[96:111]
	ds_read_b64_tr_b16 v[80:81], v214 offset:63488
	ds_read_b64_tr_b16 v[82:83], v214 offset:64000
	s_waitcnt lgkmcnt(14)
	v_mfma_f32_32x32x16_bf16 v[64:79], v[156:159], v[174:177], v[64:79]
	v_add_f32_e32 v113, v86, v113
	v_add_f32_e32 v113, v87, v113
	v_add_f32_e32 v113, v88, v113
	v_add_f32_e32 v113, v89, v113
	v_cvt_pk_bf16_f32 v172, v84, v85
	v_cvt_pk_bf16_f32 v173, v86, v87
	ds_read_b64_tr_b16 v[84:85], v214 offset:60416
	ds_read_b64_tr_b16 v[86:87], v214 offset:60928
	v_add_f32_e32 v113, v90, v113
	v_add_f32_e32 v113, v91, v113
	v_add_f32_e32 v113, v92, v113
	v_add_f32_e32 v113, v93, v113
	v_cvt_pk_bf16_f32 v166, v88, v89
	v_cvt_pk_bf16_f32 v167, v90, v91
	s_waitcnt lgkmcnt(14)
	v_mfma_f32_32x32x16_bf16 v[96:111], v[122:125], v[162:165], v[96:111]
	ds_read_b64_tr_b16 v[88:89], v214 offset:64512
	ds_read_b64_tr_b16 v[90:91], v214 offset:65024
	v_mfma_f32_32x32x16_bf16 v[64:79], v[194:197], v[162:165], v[64:79]
	v_add_f32_e32 v113, v94, v113
	v_add_f32_e32 v113, v95, v113
	v_add_f32_e32 v113, 0, v113
	v_cvt_pk_bf16_f32 v168, v92, v93
	v_cvt_pk_bf16_f32 v169, v94, v95
	s_waitcnt lgkmcnt(14)
	v_mfma_f32_32x32x16_bf16 v[0:15], v[182:185], v[198:201], v[0:15]
	s_nop 1
	v_exp_f32_e32 v96, v96
	v_exp_f32_e32 v97, v97
	ds_read_b64_tr_b16 v[92:93], v160
	ds_read_b64_tr_b16 v[94:95], v160 offset:512
	s_waitcnt lgkmcnt(14)
	v_mfma_f32_32x32x16_bf16 v[16:31], v[182:185], v[126:129], v[16:31]
	v_exp_f32_e32 v98, v98
	v_exp_f32_e32 v99, v99
	ds_read_b64_tr_b16 v[118:119], v160 offset:4096
	ds_read_b64_tr_b16 v[120:121], v160 offset:4608
	s_waitcnt lgkmcnt(14)
	v_mfma_f32_32x32x16_bf16 v[0:15], v[178:181], v[130:133], v[0:15]
	v_exp_f32_e32 v100, v100
	v_exp_f32_e32 v101, v101
	ds_read_b64_tr_b16 v[122:123], v160 offset:1024
	ds_read_b64_tr_b16 v[124:125], v160 offset:1536
	s_waitcnt lgkmcnt(14)
	v_mfma_f32_32x32x16_bf16 v[16:31], v[178:181], v[114:117], v[16:31]
	v_exp_f32_e32 v102, v102
	v_exp_f32_e32 v103, v103
	ds_read_b64_tr_b16 v[114:115], v160 offset:5120
	ds_read_b64_tr_b16 v[116:117], v160 offset:5632
	s_waitcnt lgkmcnt(14)
	v_mfma_f32_32x32x16_bf16 v[0:15], v[170:173], v[134:137], v[0:15]
	v_exp_f32_e32 v104, v104
	v_exp_f32_e32 v105, v105
	ds_read_b64_tr_b16 v[126:127], v160 offset:2048
	ds_read_b64_tr_b16 v[128:129], v160 offset:2560
	s_waitcnt lgkmcnt(14)
	v_mfma_f32_32x32x16_bf16 v[16:31], v[170:173], v[80:83], v[16:31]
	v_exp_f32_e32 v106, v106
	v_exp_f32_e32 v107, v107
	ds_read_b64_tr_b16 v[80:81], v160 offset:6144
	ds_read_b64_tr_b16 v[82:83], v160 offset:6656
	s_waitcnt lgkmcnt(14)
	v_mfma_f32_32x32x16_bf16 v[0:15], v[166:169], v[84:87], v[0:15]
	v_exp_f32_e32 v108, v108
	v_exp_f32_e32 v109, v109
	ds_read_b64_tr_b16 v[84:85], v160 offset:3072
	ds_read_b64_tr_b16 v[86:87], v160 offset:3584
	s_waitcnt lgkmcnt(14)
	v_mfma_f32_32x32x16_bf16 v[16:31], v[166:169], v[88:91], v[16:31]
	v_exp_f32_e32 v110, v110
	v_exp_f32_e32 v111, v111
	ds_read_b64_tr_b16 v[88:89], v160 offset:7168
	ds_read_b64_tr_b16 v[90:91], v160 offset:7680
	s_waitcnt lgkmcnt(14)
	v_mfma_f32_32x32x16_bf16 v[32:47], v[182:185], v[92:95], v[32:47]
	v_exp_f32_e32 v64, v64
	v_exp_f32_e32 v65, v65
	s_waitcnt lgkmcnt(12)
	v_mfma_f32_32x32x16_bf16 v[48:63], v[182:185], v[118:121], v[48:63]
	v_exp_f32_e32 v66, v66
	v_exp_f32_e32 v67, v67
	s_waitcnt lgkmcnt(10)
	v_mfma_f32_32x32x16_bf16 v[32:47], v[178:181], v[122:125], v[32:47]
	v_exp_f32_e32 v68, v68
	v_exp_f32_e32 v69, v69
	s_waitcnt lgkmcnt(8)
	v_mfma_f32_32x32x16_bf16 v[48:63], v[178:181], v[114:117], v[48:63]
	v_exp_f32_e32 v70, v70
	v_exp_f32_e32 v71, v71
	s_waitcnt lgkmcnt(6)
	v_mfma_f32_32x32x16_bf16 v[32:47], v[170:173], v[126:129], v[32:47]
	v_exp_f32_e32 v72, v72
	v_exp_f32_e32 v73, v73
	s_waitcnt lgkmcnt(4)
; #define SBAR() __builtin_amdgcn_sched_barrier(0)
;   #define RESC() do{ if(resc){ asm volatile("s_waitcnt lgkmcnt(0)":::"memory"); \
;       _Pragma("unroll") for(int d_=0;d_<2;++d_) _Pragma("unroll") for(int r=0;r<16;++r)o[d_][r]*=wsf[crow(r,hi)]; } }while(0)
;   #define PKW(P,B) cvtpk_s(P[B],P[B+1])
; #define SBAR() __builtin_amdgcn_sched_barrier(0)
;   #define RESC() do{ if(resc){ asm volatile("s_waitcnt lgkmcnt(0)":::"memory"); \
;       _Pragma("unroll") for(int d_=0;d_<4;++d_) _Pragma("unroll") for(int r=0;r<16;++r)o[d_][r]*=wsf[crow(r,hi)]; } }while(0)
;   #define PKW(P,B) cvtpk_s(P[B],P[B+1])
; #define SBAR() __builtin_amdgcn_sched_barrier(0)
;   #define PKW(P,B) cvtpk_s(P[B],P[B+1])
; __device__ __forceinline__ void pv(f32x16*o,int vb,bf16x8 pa0,bf16x8 pa1,bf16x8 pa2,bf16x8 pa3){
;   #pragma unroll
;   for(int d0=0;d0<4;++d0){s16x4 lo[4],hi[4];
;     #pragma unroll
;     for(int ks=0;ks<4;++ks){
;       asm volatile("ds_read_b64_tr_b16 %0,%1 offset:%c2":"=&v"(lo[ks]):"v"(vb),"i"(d0*4096+ks*1024):"memory");
;       asm volatile("ds_read_b64_tr_b16 %0,%1 offset:%c2":"=&v"(hi[ks]):"v"(vb),"i"(d0*4096+ks*1024+512):"memory");}
;     asm volatile("s_waitcnt lgkmcnt(0)":::"memory");SBAR();
;     ...
;     o[d0]=__builtin_amdgcn_mfma_f32_32x32x16_bf16(pa0,PK(0),o[d0],0,0,0);
;     o[d0]=__builtin_amdgcn_mfma_f32_32x32x16_bf16(pa1,PK(1),o[d0],0,0,0);
;     o[d0]=__builtin_amdgcn_mfma_f32_32x32x16_bf16(pa2,PK(2),o[d0],0,0,0);
;     o[d0]=__builtin_amdgcn_mfma_f32_32x32x16_bf16(pa3,PK(3),o[d0],0,0,0);
;     ...
;   }
; }
; template<int THRL,bool FIXED> __device__ __forceinline__ void attn_unit(int qb,const bf16*Qp,const bf16*__restrict__ Kh,const bf16*__restrict__ Vh,bf16*Op,int PO,char*shm,bool comb,float lam,const float*gsub,float gscale){
;     ...
;   STEP(pB0,pB1,pA0,pA1,NT-1,false,false,false); RESC();
;   { float sacc=pB0[0]+pB0[1]; _Pragma("unroll") for(int r=2;r<16;++r)sacc+=pB0[r]; _Pragma("unroll") for(int r=0;r<16;++r)sacc+=pB1[r]; l_reg+=sacc;
;     pw0=(u32x4){PKW(pB0,0),PKW(pB0,2),PKW(pB0,4),PKW(pB0,6)};pw1=(u32x4){PKW(pB0,8),PKW(pB0,10),PKW(pB0,12),PKW(pB0,14)};pw2=(u32x4){PKW(pB1,0),PKW(pB1,2),PKW(pB1,4),PKW(pB1,6)};pw3=(u32x4){PKW(pB1,8),PKW(pB1,10),PKW(pB1,12),PKW(pB1,14)};
;     SBAR(); pv(o,vb0+VSL(NT-1),PAF(0),PAF(1),PAF(2),PAF(3)); }
;   asm volatile("s_waitcnt lgkmcnt(0)\n\ts_barrier":::"memory");
	v_mfma_f32_32x32x16_bf16 v[48:63], v[170:173], v[80:83], v[48:63]
	v_exp_f32_e32 v74, v74
	v_exp_f32_e32 v75, v75
	s_waitcnt lgkmcnt(2)
	v_mfma_f32_32x32x16_bf16 v[32:47], v[166:169], v[84:87], v[32:47]
	v_exp_f32_e32 v76, v76
	v_exp_f32_e32 v77, v77
	s_waitcnt lgkmcnt(0)
	v_mfma_f32_32x32x16_bf16 v[48:63], v[166:169], v[88:91], v[48:63]
	v_exp_f32_e32 v78, v78
	v_exp_f32_e32 v79, v79
	v_add_f32_e32 v80, v96, v97
	v_add_f32_e32 v80, v98, v80
	v_add_f32_e32 v80, v99, v80
	v_add_f32_e32 v80, v100, v80
	v_add_f32_e32 v80, v101, v80
	v_add_f32_e32 v80, v102, v80
	v_add_f32_e32 v80, v103, v80
	v_add_f32_e32 v80, v104, v80
	v_add_f32_e32 v80, v105, v80
	v_add_f32_e32 v80, v106, v80
	v_add_f32_e32 v80, v107, v80
	v_add_f32_e32 v80, v108, v80
	v_add_f32_e32 v80, v109, v80
	v_add_f32_e32 v80, v110, v80
	v_add_f32_e32 v80, v111, v80
	v_add_f32_e32 v80, v80, v64
	v_add_f32_e32 v80, v65, v80
	v_add_f32_e32 v80, v66, v80
	v_add_f32_e32 v80, v67, v80
	v_add_f32_e32 v80, v68, v80
	v_add_f32_e32 v80, v69, v80
	v_add_f32_e32 v80, v70, v80
	v_add_f32_e32 v80, v71, v80
	v_add_f32_e32 v80, v72, v80
	v_add_f32_e32 v80, v73, v80
	v_add_f32_e32 v80, v74, v80
	v_add_f32_e32 v80, v75, v80
	v_add_f32_e32 v80, v76, v80
	v_add_f32_e32 v80, v77, v80
	v_add_f32_e32 v80, v78, v80
	v_add_f32_e32 v80, v79, v80
	v_add_f32_e32 v81, v112, v113
	v_add_f32_e32 v80, v81, v80
	v_cvt_pk_bf16_f32 v64, v64, v65
	v_cvt_pk_bf16_f32 v82, v96, v97
	v_cvt_pk_bf16_f32 v83, v98, v99
	v_cvt_pk_bf16_f32 v84, v100, v101
	v_cvt_pk_bf16_f32 v85, v102, v103
	v_cvt_pk_bf16_f32 v86, v104, v105
	v_cvt_pk_bf16_f32 v87, v106, v107
	v_cvt_pk_bf16_f32 v88, v108, v109
	v_cvt_pk_bf16_f32 v89, v110, v111
	v_cvt_pk_bf16_f32 v65, v66, v67
	v_cvt_pk_bf16_f32 v66, v68, v69
	v_cvt_pk_bf16_f32 v67, v70, v71
	v_cvt_pk_bf16_f32 v68, v72, v73
	v_cvt_pk_bf16_f32 v69, v74, v75
	v_cvt_pk_bf16_f32 v70, v76, v77
	v_cvt_pk_bf16_f32 v71, v78, v79
	v_add_u32_e32 v72, s29, v236
	v_add3_u32 v81, v72, v237, v240
	ds_read_b64_tr_b16 v[72:73],v81 offset:0
	ds_read_b64_tr_b16 v[74:75],v81 offset:512
	ds_read_b64_tr_b16 v[76:77],v81 offset:1024
	ds_read_b64_tr_b16 v[78:79],v81 offset:1536
	ds_read_b64_tr_b16 v[90:91],v81 offset:2048
	ds_read_b64_tr_b16 v[92:93],v81 offset:2560
	ds_read_b64_tr_b16 v[94:95],v81 offset:3072
	ds_read_b64_tr_b16 v[96:97],v81 offset:3584
	s_waitcnt lgkmcnt(0)
	s_nop 0
	v_mfma_f32_32x32x16_bf16 v[0:15], v[82:85], v[72:75], v[0:15]
	ds_read_b64_tr_b16 v[72:73],v81 offset:4096
	ds_read_b64_tr_b16 v[74:75],v81 offset:4608
	v_mfma_f32_32x32x16_bf16 v[0:15], v[86:89], v[76:79], v[0:15]
	ds_read_b64_tr_b16 v[76:77],v81 offset:5120
	ds_read_b64_tr_b16 v[78:79],v81 offset:5632
	v_mfma_f32_32x32x16_bf16 v[0:15], v[64:67], v[90:93], v[0:15]
	ds_read_b64_tr_b16 v[90:91],v81 offset:6144
	ds_read_b64_tr_b16 v[92:93],v81 offset:6656
	v_mfma_f32_32x32x16_bf16 v[0:15], v[68:71], v[94:97], v[0:15]
	ds_read_b64_tr_b16 v[94:95],v81 offset:7168
	ds_read_b64_tr_b16 v[96:97],v81 offset:7680
	s_waitcnt lgkmcnt(0)
	v_mfma_f32_32x32x16_bf16 v[16:31], v[82:85], v[72:75], v[16:31]
	ds_read_b64_tr_b16 v[72:73],v81 offset:8192
	ds_read_b64_tr_b16 v[74:75],v81 offset:8704
	v_mfma_f32_32x32x16_bf16 v[16:31], v[86:89], v[76:79], v[16:31]
	ds_read_b64_tr_b16 v[76:77],v81 offset:9216
	ds_read_b64_tr_b16 v[78:79],v81 offset:9728
	v_mfma_f32_32x32x16_bf16 v[16:31], v[64:67], v[90:93], v[16:31]
	ds_read_b64_tr_b16 v[90:91],v81 offset:10240
	ds_read_b64_tr_b16 v[92:93],v81 offset:10752
	v_mfma_f32_32x32x16_bf16 v[16:31], v[68:71], v[94:97], v[16:31]
	ds_read_b64_tr_b16 v[94:95],v81 offset:11264
	ds_read_b64_tr_b16 v[96:97],v81 offset:11776
	s_waitcnt lgkmcnt(0)
	v_mfma_f32_32x32x16_bf16 v[32:47], v[82:85], v[72:75], v[32:47]
	ds_read_b64_tr_b16 v[72:73],v81 offset:12288
	ds_read_b64_tr_b16 v[74:75],v81 offset:12800
	v_mfma_f32_32x32x16_bf16 v[32:47], v[86:89], v[76:79], v[32:47]
	ds_read_b64_tr_b16 v[76:77],v81 offset:13312
	ds_read_b64_tr_b16 v[78:79],v81 offset:13824
	v_mfma_f32_32x32x16_bf16 v[32:47], v[64:67], v[90:93], v[32:47]
	ds_read_b64_tr_b16 v[90:91],v81 offset:14336
	ds_read_b64_tr_b16 v[92:93],v81 offset:14848
	v_mfma_f32_32x32x16_bf16 v[32:47], v[68:71], v[94:97], v[32:47]
	ds_read_b64_tr_b16 v[94:95],v81 offset:15360
	ds_read_b64_tr_b16 v[96:97],v81 offset:15872
	s_waitcnt lgkmcnt(0)
	v_mfma_f32_32x32x16_bf16 v[48:63], v[82:85], v[72:75], v[48:63]
	s_waitcnt lgkmcnt(0)
	s_barrier
; __device__ __forceinline__ int crow(int r,int hi){return (r&3)+8*(r>>2)+4*hi;}
; __device__ __forceinline__ int crow(int r,int hi){return (r&3)+8*(r>>2)+4*hi;}
; template<int THRL,bool FIXED> __device__ __forceinline__ void attn_unit(int qb,const bf16*Qp,const bf16*__restrict__ Kh,const bf16*__restrict__ Vh,bf16*Op,int PO,char*shm,bool comb,float lam,const float*gsub,float gscale){
;     ...
;   {auto rr=__builtin_amdgcn_permlane32_swap(__float_as_uint(l_reg),__float_as_uint(l_reg),false,false);l_reg=__uint_as_float(rr[0])+__uint_as_float(rr[1]);}
;   if(hi==0)wsf[32+r32]=l_reg;asm volatile("s_waitcnt lgkmcnt(0)":::"memory");
;   float rli[16];
;   #pragma unroll
;   for(int r=0;r<16;++r)rli[r]=__builtin_amdgcn_rcpf(wsf[32+crow(r,hi)]);
;   bf16*Ow=Op+(long)(q0+wid*QBLK)*PO;
;   { bf16*stg=(bf16*)(shm+LDS_OST)+wid*4096;
;     #pragma unroll
;     for(int r=0;r<16;++r){const int orow=crow(r,hi);
;       #pragma unroll
;       for(int d0=0;d0<4;++d0)stg[orow*128+d0*32+r32]=__float2bfloat16(o[d0][r]*rli[r]);}
	v_cmp_gt_u32_e32 vcc, 32, v234
	v_mfma_f32_32x32x16_bf16 v[48:63], v[86:89], v[76:79], v[48:63]
	v_mfma_f32_32x32x16_bf16 v[48:63], v[64:67], v[90:93], v[48:63]
	v_mov_b32_e32 v64, v80
	s_nop 1
	v_permlane32_swap_b32_e32 v80, v64
	v_mfma_f32_32x32x16_bf16 v[48:63], v[68:71], v[94:97], v[48:63]
	s_and_saveexec_b64 s[66:67], vcc
	v_lshl_add_u32 v65, v232, 2, s28
	v_add_f32_e32 v64, v80, v64
	ds_write_b32 v65, v64 offset:128
	s_or_b64 exec, exec, s[66:67]
	s_waitcnt lgkmcnt(0)
	v_lshl_add_u32 v72, v233, 4, s28
	ds_read_b128 v[64:67], v72 offset:128
	ds_read_b128 v[68:71], v72 offset:160
	s_lshl_b32 s3, s77, 13
	s_add_i32 s3, s3, 0
	s_lshl_b64 s[64:65], s[64:65], 11
	s_waitcnt lgkmcnt(1)
	v_rcp_f32_e32 v73, v64
	v_rcp_f32_e32 v74, v65
	v_rcp_f32_e32 v75, v66
	v_rcp_f32_e32 v76, v67
	s_waitcnt lgkmcnt(0)
	v_rcp_f32_e32 v77, v68
	ds_read_b128 v[64:67], v72 offset:192
	v_rcp_f32_e32 v78, v69
	v_rcp_f32_e32 v79, v70
	v_rcp_f32_e32 v80, v71
	ds_read_b128 v[68:71], v72 offset:224
	v_lshlrev_b32_e32 v72, 1, v232
	v_mul_f32_e32 v0, v0, v73
	v_add3_u32 v72, s3, v235, v72
	v_cvt_pk_bf16_f32 v0, v0, s0
	ds_write_b16 v72, v0
	v_mul_f32_e32 v0, v16, v73
	v_cvt_pk_bf16_f32 v0, v0, s0
	ds_write_b16 v72, v0 offset:64
	v_mul_f32_e32 v0, v32, v73
	v_cvt_pk_bf16_f32 v0, v0, s0
	ds_write_b16 v72, v0 offset:128
	v_mul_f32_e32 v0, v48, v73
	v_cvt_pk_bf16_f32 v0, v0, s0
	ds_write_b16 v72, v0 offset:192
	v_mul_f32_e32 v0, v1, v74
	v_cvt_pk_bf16_f32 v0, v0, s0
	ds_write_b16 v72, v0 offset:256
	v_mul_f32_e32 v0, v17, v74
	v_cvt_pk_bf16_f32 v0, v0, s0
	ds_write_b16 v72, v0 offset:320
	v_mul_f32_e32 v0, v33, v74
	v_cvt_pk_bf16_f32 v0, v0, s0
	ds_write_b16 v72, v0 offset:384
	v_mul_f32_e32 v0, v49, v74
	v_cvt_pk_bf16_f32 v0, v0, s0
	ds_write_b16 v72, v0 offset:448
	v_mul_f32_e32 v0, v2, v75
	v_cvt_pk_bf16_f32 v0, v0, s0
	ds_write_b16 v72, v0 offset:512
	v_mul_f32_e32 v0, v18, v75
	v_cvt_pk_bf16_f32 v0, v0, s0
	ds_write_b16 v72, v0 offset:576
	v_mul_f32_e32 v0, v34, v75
	v_cvt_pk_bf16_f32 v0, v0, s0
	ds_write_b16 v72, v0 offset:640
	v_mul_f32_e32 v0, v50, v75
	v_cvt_pk_bf16_f32 v0, v0, s0
	ds_write_b16 v72, v0 offset:704
	v_mul_f32_e32 v0, v3, v76
	v_cvt_pk_bf16_f32 v0, v0, s0
	ds_write_b16 v72, v0 offset:768
	v_mul_f32_e32 v0, v19, v76
	v_cvt_pk_bf16_f32 v0, v0, s0
	ds_write_b16 v72, v0 offset:832
	v_mul_f32_e32 v0, v35, v76
	v_cvt_pk_bf16_f32 v0, v0, s0
	ds_write_b16 v72, v0 offset:896
	v_mul_f32_e32 v0, v51, v76
	v_cvt_pk_bf16_f32 v0, v0, s0
	ds_write_b16 v72, v0 offset:960
	v_mul_f32_e32 v0, v4, v77
	v_cvt_pk_bf16_f32 v0, v0, s0
	ds_write_b16 v72, v0 offset:2048
	v_mul_f32_e32 v0, v20, v77
	v_cvt_pk_bf16_f32 v0, v0, s0
	ds_write_b16 v72, v0 offset:2112
	v_mul_f32_e32 v0, v36, v77
	v_cvt_pk_bf16_f32 v0, v0, s0
	ds_write_b16 v72, v0 offset:2176
	v_mul_f32_e32 v0, v52, v77
	v_cvt_pk_bf16_f32 v0, v0, s0
	ds_write_b16 v72, v0 offset:2240
	v_mul_f32_e32 v0, v5, v78
	v_cvt_pk_bf16_f32 v0, v0, s0
	ds_write_b16 v72, v0 offset:2304
	v_mul_f32_e32 v0, v21, v78
	v_cvt_pk_bf16_f32 v0, v0, s0
	ds_write_b16 v72, v0 offset:2368
	v_mul_f32_e32 v0, v37, v78
	v_cvt_pk_bf16_f32 v0, v0, s0
	ds_write_b16 v72, v0 offset:2432
	v_mul_f32_e32 v0, v53, v78
	v_cvt_pk_bf16_f32 v0, v0, s0
	ds_write_b16 v72, v0 offset:2496
	v_mul_f32_e32 v0, v6, v79
	v_cvt_pk_bf16_f32 v0, v0, s0
	ds_write_b16 v72, v0 offset:2560
	v_mul_f32_e32 v0, v22, v79
	v_cvt_pk_bf16_f32 v0, v0, s0
	ds_write_b16 v72, v0 offset:2624
	v_mul_f32_e32 v0, v38, v79
	v_cvt_pk_bf16_f32 v0, v0, s0
	ds_write_b16 v72, v0 offset:2688
	v_mul_f32_e32 v0, v54, v79
	v_cvt_pk_bf16_f32 v0, v0, s0
	ds_write_b16 v72, v0 offset:2752
	v_mul_f32_e32 v0, v7, v80
	v_cvt_pk_bf16_f32 v0, v0, s0
	ds_write_b16 v72, v0 offset:2816
	v_mul_f32_e32 v0, v23, v80
	v_cvt_pk_bf16_f32 v0, v0, s0
	s_waitcnt lgkmcnt(14)
; __device__ __forceinline__ int crow(int r,int hi){return (r&3)+8*(r>>2)+4*hi;}
; __device__ __forceinline__ int crow(int r,int hi){return (r&3)+8*(r>>2)+4*hi;}
; template<int THRL,bool FIXED> __device__ __forceinline__ void attn_unit(int qb,const bf16*Qp,const bf16*__restrict__ Kh,const bf16*__restrict__ Vh,bf16*Op,int PO,char*shm,bool comb,float lam,const float*gsub,float gscale){
;     ...
;     for(int r=0;r<16;++r){const int orow=crow(r,hi);
;       #pragma unroll
;       for(int d0=0;d0<4;++d0)stg[orow*128+d0*32+r32]=__float2bfloat16(o[d0][r]*rli[r]);}
;     asm volatile("s_waitcnt lgkmcnt(0)":::"memory");
;     if(!comb){
;       #pragma unroll
;       for(int i=0;i<8;++i){const int row=i*4+(lane>>4),ch=lane&15; const u32x4 v=*(const u32x4*)(stg+row*128+ch*8); ATTN_STORE16(Ow+(long)row*PO+ch*8,v);}
	v_rcp_f32_e32 v64, v64
	ds_write_b16 v72, v0 offset:2880
	v_mul_f32_e32 v0, v39, v80
	v_cvt_pk_bf16_f32 v0, v0, s0
	ds_write_b16 v72, v0 offset:2944
	v_mul_f32_e32 v0, v55, v80
	v_cvt_pk_bf16_f32 v0, v0, s0
	ds_write_b16 v72, v0 offset:3008
	v_mul_f32_e32 v0, v8, v64
	v_cvt_pk_bf16_f32 v0, v0, s0
	ds_write_b16 v72, v0 offset:4096
	v_mul_f32_e32 v0, v24, v64
	v_cvt_pk_bf16_f32 v0, v0, s0
	v_rcp_f32_e32 v65, v65
	ds_write_b16 v72, v0 offset:4160
	v_mul_f32_e32 v0, v40, v64
	v_cvt_pk_bf16_f32 v0, v0, s0
	ds_write_b16 v72, v0 offset:4224
	v_mul_f32_e32 v0, v56, v64
	v_cvt_pk_bf16_f32 v0, v0, s0
	ds_write_b16 v72, v0 offset:4288
	v_mul_f32_e32 v0, v9, v65
	v_cvt_pk_bf16_f32 v0, v0, s0
	ds_write_b16 v72, v0 offset:4352
	v_mul_f32_e32 v0, v25, v65
	v_cvt_pk_bf16_f32 v0, v0, s0
	v_rcp_f32_e32 v66, v66
	ds_write_b16 v72, v0 offset:4416
	v_mul_f32_e32 v0, v41, v65
	v_cvt_pk_bf16_f32 v0, v0, s0
	ds_write_b16 v72, v0 offset:4480
	v_mul_f32_e32 v0, v57, v65
	v_cvt_pk_bf16_f32 v0, v0, s0
	ds_write_b16 v72, v0 offset:4544
	v_mul_f32_e32 v0, v10, v66
	v_cvt_pk_bf16_f32 v0, v0, s0
	ds_write_b16 v72, v0 offset:4608
	v_mul_f32_e32 v0, v26, v66
	v_cvt_pk_bf16_f32 v0, v0, s0
	v_rcp_f32_e32 v67, v67
	ds_write_b16 v72, v0 offset:4672
	v_mul_f32_e32 v0, v42, v66
	v_cvt_pk_bf16_f32 v0, v0, s0
	ds_write_b16 v72, v0 offset:4736
	v_mul_f32_e32 v0, v58, v66
	v_cvt_pk_bf16_f32 v0, v0, s0
	ds_write_b16 v72, v0 offset:4800
	v_mul_f32_e32 v0, v11, v67
	v_cvt_pk_bf16_f32 v0, v0, s0
	ds_write_b16 v72, v0 offset:4864
	v_mul_f32_e32 v0, v27, v67
	v_cvt_pk_bf16_f32 v0, v0, s0
	v_rcp_f32_e32 v68, v68
	ds_write_b16 v72, v0 offset:4928
	v_mul_f32_e32 v0, v43, v67
	v_cvt_pk_bf16_f32 v0, v0, s0
	ds_write_b16 v72, v0 offset:4992
	v_mul_f32_e32 v0, v59, v67
	v_cvt_pk_bf16_f32 v0, v0, s0
	ds_write_b16 v72, v0 offset:5056
	v_mul_f32_e32 v0, v12, v68
	v_cvt_pk_bf16_f32 v0, v0, s0
	ds_write_b16 v72, v0 offset:6144
	v_mul_f32_e32 v0, v28, v68
	v_cvt_pk_bf16_f32 v0, v0, s0
	v_rcp_f32_e32 v69, v69
	ds_write_b16 v72, v0 offset:6208
	v_mul_f32_e32 v0, v44, v68
	v_cvt_pk_bf16_f32 v0, v0, s0
	ds_write_b16 v72, v0 offset:6272
	v_mul_f32_e32 v0, v60, v68
	v_cvt_pk_bf16_f32 v0, v0, s0
	ds_write_b16 v72, v0 offset:6336
	v_mul_f32_e32 v0, v13, v69
	v_cvt_pk_bf16_f32 v0, v0, s0
	ds_write_b16 v72, v0 offset:6400
	v_mul_f32_e32 v0, v29, v69
	v_cvt_pk_bf16_f32 v0, v0, s0
	v_rcp_f32_e32 v70, v70
	ds_write_b16 v72, v0 offset:6464
	v_mul_f32_e32 v0, v45, v69
	v_cvt_pk_bf16_f32 v0, v0, s0
	ds_write_b16 v72, v0 offset:6528
	v_mul_f32_e32 v0, v61, v69
	v_cvt_pk_bf16_f32 v0, v0, s0
	ds_write_b16 v72, v0 offset:6592
	v_mul_f32_e32 v0, v14, v70
	v_cvt_pk_bf16_f32 v0, v0, s0
	ds_write_b16 v72, v0 offset:6656
	v_mul_f32_e32 v0, v30, v70
	v_cvt_pk_bf16_f32 v0, v0, s0
	v_rcp_f32_e32 v71, v71
	ds_write_b16 v72, v0 offset:6720
	v_mul_f32_e32 v0, v46, v70
	v_cvt_pk_bf16_f32 v0, v0, s0
	ds_write_b16 v72, v0 offset:6784
	v_mul_f32_e32 v0, v62, v70
	v_cvt_pk_bf16_f32 v0, v0, s0
	ds_write_b16 v72, v0 offset:6848
	v_mul_f32_e32 v0, v15, v71
	v_cvt_pk_bf16_f32 v0, v0, s0
	ds_write_b16 v72, v0 offset:6912
	v_mul_f32_e32 v0, v31, v71
	v_cvt_pk_bf16_f32 v0, v0, s0
	ds_write_b16 v72, v0 offset:6976
	v_mul_f32_e32 v0, v47, v71
	v_cvt_pk_bf16_f32 v0, v0, s0
	ds_write_b16 v72, v0 offset:7040
	v_mul_f32_e32 v0, v63, v71
	v_cvt_pk_bf16_f32 v0, v0, s0
	ds_write_b16 v72, v0 offset:7104
	s_waitcnt lgkmcnt(0)
	s_add_u32 s64, s72, s64
	v_lshlrev_b32_e32 v6, 3, v231
	v_or_b32_e32 v28, 4, v230
	v_or_b32_e32 v60, 8, v230
	v_or_b32_e32 v59, 12, v230
	v_or_b32_e32 v58, 16, v230
	v_or_b32_e32 v57, 20, v230
	v_or_b32_e32 v56, 24, v230
	s_addc_u32 s65, s73, s65
	s_mov_b64 s[66:67], -1
	s_andn2_b64 vcc, exec, s[12:13]
	v_lshlrev_b32_e32 v4, 11, v230
	v_lshlrev_b32_e32 v160, 1, v6
	v_lshlrev_b32_e32 v52, 11, v28
	v_lshlrev_b32_e32 v50, 11, v60
	v_lshlrev_b32_e32 v48, 11, v59
	v_lshlrev_b32_e32 v46, 11, v58
	v_lshlrev_b32_e32 v42, 11, v57
	v_lshlrev_b32_e32 v40, 11, v56
	v_or_b32_e32 v54, 28, v230
	s_cbranch_vccnz .LBB0_555
	v_add_u32_e32 v7, s3, v160
	v_lshl_add_u32 v0, v230, 8, v7
	ds_read_b128 v[0:3], v0
	v_lshl_add_u64 v[8:9], s[64:65], 0, v[160:161]
	v_mov_b32_e32 v5, v161
	v_lshl_add_u64 v[10:11], v[8:9], 0, v[4:5]
	v_mov_b32_e32 v53, v161
	s_waitcnt lgkmcnt(0)
	global_store_dwordx4 v[10:11], v[0:3], off offset:1024
	v_lshl_add_u64 v[10:11], v[8:9], 0, v[52:53]
	v_mov_b32_e32 v51, v161
	v_lshl_add_u32 v0, v28, 8, v7
	ds_read_b128 v[0:3], v0
	v_mov_b32_e32 v49, v161
	v_mov_b32_e32 v47, v161
	v_mov_b32_e32 v43, v161
	v_mov_b32_e32 v41, v161
	s_waitcnt lgkmcnt(0)
	global_store_dwordx4 v[10:11], v[0:3], off offset:1024
	v_lshl_add_u64 v[10:11], v[8:9], 0, v[50:51]
	v_or_b32_e32 v5, 28, v230
	v_lshl_add_u32 v0, v60, 8, v7
	ds_read_b128 v[0:3], v0
	s_mov_b64 s[66:67], 0
	s_waitcnt lgkmcnt(0)
	global_store_dwordx4 v[10:11], v[0:3], off offset:1024
	s_nop 1
	v_lshl_add_u32 v0, v59, 8, v7
	ds_read_b128 v[0:3], v0
	v_lshl_add_u64 v[10:11], v[8:9], 0, v[48:49]
	s_waitcnt lgkmcnt(0)
	global_store_dwordx4 v[10:11], v[0:3], off offset:1024
	s_nop 1
	v_lshl_add_u32 v0, v58, 8, v7
	ds_read_b128 v[0:3], v0
	v_lshl_add_u64 v[10:11], v[8:9], 0, v[46:47]
	s_waitcnt lgkmcnt(0)
	global_store_dwordx4 v[10:11], v[0:3], off offset:1024
	s_nop 1
	v_lshl_add_u32 v0, v57, 8, v7
	ds_read_b128 v[0:3], v0
	v_lshl_add_u64 v[10:11], v[8:9], 0, v[42:43]
	v_lshl_add_u64 v[8:9], v[8:9], 0, v[40:41]
	s_waitcnt lgkmcnt(0)
	global_store_dwordx4 v[10:11], v[0:3], off offset:1024
	s_nop 1
	v_lshl_add_u32 v0, v56, 8, v7
	ds_read_b128 v[0:3], v0
	s_waitcnt lgkmcnt(0)
	global_store_dwordx4 v[8:9], v[0:3], off offset:1024
	s_nop 1
	v_lshl_add_u32 v0, v5, 8, v7
	ds_read_b128 v[0:3], v0

; #define LAS __attribute__((address_space(3)))
; __global__ void __launch_bounds__(512, 2) mk_fwd(Args args) {
;     extern __shared__ __attribute__((aligned(16))) unsigned char lds[];
;     cg::grid_group grid = cg::this_grid();
;     volatile LAS unsigned* bst = (volatile LAS unsigned*)((LAS unsigned char*)lds + (LDS_BYTES - 64));
;     if (threadIdx.x < 2) bst[threadIdx.x] = 0u;
;     __syncthreads();
;     const XcdBarrier xbar = xcd_barrier_post((unsigned*)(args.ws + WS_BAR), bst);
;     ...
;     Frame F;
;     F.lds = (LAS unsigned char*)lds; F.tid = threadIdx.x; F.lane = F.tid & 63; F.wave = __builtin_amdgcn_readfirstlane(F.tid >> 6);
;     F.G = gridDim.x; F.gw = blockIdx.x * 8 + F.wave; F.NGW = F.G * 8;
	.amdhsa_kernel _Z6mk_fwd4Args
		.amdhsa_group_segment_fixed_size 0
		.amdhsa_private_segment_fixed_size 0
		.amdhsa_kernarg_size 560
		.amdhsa_user_sgpr_count 2
		.amdhsa_user_sgpr_dispatch_ptr 0
		.amdhsa_user_sgpr_queue_ptr 0
		.amdhsa_user_sgpr_kernarg_segment_ptr 1
		.amdhsa_user_sgpr_dispatch_id 0
		.amdhsa_user_sgpr_kernarg_preload_length 0
		.amdhsa_user_sgpr_kernarg_preload_offset 0
		.amdhsa_user_sgpr_private_segment_size 0
		.amdhsa_uses_dynamic_stack 0
		.amdhsa_enable_private_segment 0
		.amdhsa_system_sgpr_workgroup_id_x 1
		.amdhsa_system_sgpr_workgroup_id_y 0
		.amdhsa_system_sgpr_workgroup_id_z 0
		.amdhsa_system_sgpr_workgroup_info 0
		.amdhsa_system_vgpr_workitem_id 2
		.amdhsa_next_free_vgpr 256
		.amdhsa_next_free_sgpr 102
		.amdhsa_accum_offset 256
		.amdhsa_reserve_vcc 1
		.amdhsa_float_round_mode_32 0
		.amdhsa_float_round_mode_16_64 0
		.amdhsa_float_denorm_mode_32 3
		.amdhsa_float_denorm_mode_16_64 3
		.amdhsa_dx10_clamp 1
		.amdhsa_ieee_mode 1
		.amdhsa_fp16_overflow 0
		.amdhsa_tg_split 0
		.amdhsa_exception_fp_ieee_invalid_op 0
		.amdhsa_exception_fp_denorm_src 0
		.amdhsa_exception_fp_ieee_div_zero 0
		.amdhsa_exception_fp_ieee_overflow 0
		.amdhsa_exception_fp_ieee_underflow 0
		.amdhsa_exception_fp_ieee_inexact 0
		.amdhsa_exception_int_div_zero 0
	.end_amdhsa_kernel

; __global__ void __launch_bounds__(512, 2) mk_fwd(Args args) {
;     extern __shared__ __attribute__((aligned(16))) unsigned char lds[];
amdhsa.kernels:
  - .agpr_count:     0
    .args:
      - .offset:         0
        .size:           304
        .value_kind:     by_value
      - .offset:         304
        .size:           4
        .value_kind:     hidden_block_count_x
      - .offset:         308
        .size:           4
        .value_kind:     hidden_block_count_y
      - .offset:         312
        .size:           4
        .value_kind:     hidden_block_count_z
      - .offset:         316
        .size:           2
        .value_kind:     hidden_group_size_x
      - .offset:         318
        .size:           2
        .value_kind:     hidden_group_size_y
      - .offset:         320
        .size:           2
        .value_kind:     hidden_group_size_z
      - .offset:         322
        .size:           2
        .value_kind:     hidden_remainder_x
      - .offset:         324
        .size:           2
        .value_kind:     hidden_remainder_y
      - .offset:         326
        .size:           2
        .value_kind:     hidden_remainder_z
      - .offset:         344
        .size:           8
        .value_kind:     hidden_global_offset_x
      - .offset:         352
        .size:           8
        .value_kind:     hidden_global_offset_y
      - .offset:         360
        .size:           8
        .value_kind:     hidden_global_offset_z
      - .offset:         368
        .size:           2
        .value_kind:     hidden_grid_dims
      - .offset:         392
        .size:           8
        .value_kind:     hidden_multigrid_sync_arg
      - .offset:         424
        .size:           4
        .value_kind:     hidden_dynamic_lds_size
    .group_segment_fixed_size: 0
    .kernarg_segment_align: 8
    .kernarg_segment_size: 560
    .language:       OpenCL C
    .language_version:
      - 2
      - 0
    .max_flat_workgroup_size: 512
    .name:           _Z6mk_fwd4Args
    .private_segment_fixed_size: 0
    .sgpr_count:     108
    .sgpr_spill_count: 196
    .symbol:         _Z6mk_fwd4Args.kd
    .uniform_work_group_size: 1
    .uses_dynamic_stack: false
    .vgpr_count:     256
    .vgpr_spill_count: 0
    .wavefront_size: 64
